# c18 + load-segment slimming on the uniform schedule: counted waits merged into one s_waitcnt, ds_reads as m0->LDS-DMA fillers instead of s_nop (trip-0 skip block untouched)
# baseline (speedup 1.0000x reference)
.Lrb2_skip_7701:
	s_mov_b32 m0, s78
	ds_read_b128 v[184:187], v148
	ds_read_b128 v[188:191], v148 offset:1024
	ds_read_b128 v[192:195], v148 offset:2048
	ds_read_b128 v[196:199], v148 offset:3072
	ds_read_b128 v[200:203], v148 offset:4096
	ds_read_b128 v[204:207], v148 offset:5120
	ds_read_b128 v[208:211], v148 offset:6144
	global_load_lds_dwordx4 v138, s[70:71]
	s_mov_b32 m0, s79
	ds_read_b128 v[212:215], v148 offset:7168
	global_load_lds_dwordx4 v140, s[70:71]
	s_waitcnt vmcnt(8) lgkmcnt(0)
	s_setprio 1
	s_barrier
	v_mfma_f32_16x16x32_bf16 v[122:125], v[152:155], v[184:187], v[122:125]
	v_mfma_f32_16x16x32_bf16 v[114:117], v[160:163], v[184:187], v[114:117]
	v_mfma_f32_16x16x32_bf16 v[106:109], v[152:155], v[192:195], v[106:109]
	v_mfma_f32_16x16x32_bf16 v[98:101], v[160:163], v[192:195], v[98:101]
	v_mfma_f32_16x16x32_bf16 v[90:93], v[152:155], v[200:203], v[90:93]
	v_mfma_f32_16x16x32_bf16 v[82:85], v[160:163], v[200:203], v[82:85]
	v_mfma_f32_16x16x32_bf16 v[74:77], v[152:155], v[208:211], v[74:77]
	v_mfma_f32_16x16x32_bf16 v[58:61], v[160:163], v[208:211], v[58:61]
	v_mfma_f32_16x16x32_bf16 v[122:125], v[156:159], v[188:191], v[122:125]
	v_mfma_f32_16x16x32_bf16 v[114:117], v[164:167], v[188:191], v[114:117]
	v_mfma_f32_16x16x32_bf16 v[106:109], v[156:159], v[196:199], v[106:109]
	v_mfma_f32_16x16x32_bf16 v[98:101], v[164:167], v[196:199], v[98:101]
	v_mfma_f32_16x16x32_bf16 v[90:93], v[156:159], v[204:207], v[90:93]
	v_mfma_f32_16x16x32_bf16 v[82:85], v[164:167], v[204:207], v[82:85]
	v_mfma_f32_16x16x32_bf16 v[74:77], v[156:159], v[212:215], v[74:77]
	v_mfma_f32_16x16x32_bf16 v[58:61], v[164:167], v[212:215], v[58:61]
	s_setprio 0
	s_setprio 1
	v_mfma_f32_16x16x32_bf16 v[126:129], v[168:171], v[184:187], v[126:129]
	v_mfma_f32_16x16x32_bf16 v[118:121], v[176:179], v[184:187], v[118:121]
	v_mfma_f32_16x16x32_bf16 v[110:113], v[168:171], v[192:195], v[110:113]
	v_mfma_f32_16x16x32_bf16 v[102:105], v[176:179], v[192:195], v[102:105]
	v_mfma_f32_16x16x32_bf16 v[94:97], v[168:171], v[200:203], v[94:97]
	v_mfma_f32_16x16x32_bf16 v[86:89], v[176:179], v[200:203], v[86:89]
	v_mfma_f32_16x16x32_bf16 v[78:81], v[168:171], v[208:211], v[78:81]
	v_mfma_f32_16x16x32_bf16 v[66:69], v[176:179], v[208:211], v[66:69]
	v_mfma_f32_16x16x32_bf16 v[126:129], v[172:175], v[188:191], v[126:129]
	v_mfma_f32_16x16x32_bf16 v[118:121], v[180:183], v[188:191], v[118:121]
	v_mfma_f32_16x16x32_bf16 v[110:113], v[172:175], v[196:199], v[110:113]
	v_mfma_f32_16x16x32_bf16 v[102:105], v[180:183], v[196:199], v[102:105]
	v_mfma_f32_16x16x32_bf16 v[94:97], v[172:175], v[204:207], v[94:97]
	v_mfma_f32_16x16x32_bf16 v[86:89], v[180:183], v[204:207], v[86:89]
	v_mfma_f32_16x16x32_bf16 v[78:81], v[172:175], v[212:215], v[78:81]
	v_mfma_f32_16x16x32_bf16 v[66:69], v[180:183], v[212:215], v[66:69]
	s_barrier
	s_setprio 0
	s_mov_b32 m0, s81
	s_mov_b64 s[98:99], s[66:67]
	s_add_u32 s16, s66, 0x100000
	ds_read_b128 v[184:187], v148 offset:16384
	ds_read_b128 v[188:191], v148 offset:17408
	ds_read_b128 v[192:195], v148 offset:18432
	ds_read_b128 v[196:199], v148 offset:19456
	ds_read_b128 v[200:203], v148 offset:20480
	ds_read_b128 v[204:207], v148 offset:21504
	ds_read_b128 v[208:211], v148 offset:22528
	global_load_lds_dwordx4 v134, s[66:67]
	s_mov_b32 m0, s82
	s_addc_u32 s17, s67, 0
	global_load_lds_dwordx4 v130, s[66:67]
	s_mov_b32 m0, s83
	s_mov_b64 s[100:101], s[74:75]
	global_load_lds_dwordx4 v134, s[16:17]
	s_mov_b32 m0, s86
	ds_read_b128 v[212:215], v148 offset:23552
	global_load_lds_dwordx4 v130, s[16:17]
	s_waitcnt vmcnt(6) lgkmcnt(0)
	s_setprio 1
	s_barrier
	v_mfma_f32_16x16x32_bf16 v[62:65], v[152:155], v[184:187], v[62:65]
	v_mfma_f32_16x16x32_bf16 v[50:53], v[160:163], v[184:187], v[50:53]
	v_mfma_f32_16x16x32_bf16 v[42:45], v[152:155], v[192:195], v[42:45]
	v_mfma_f32_16x16x32_bf16 v[34:37], v[160:163], v[192:195], v[34:37]
	v_mfma_f32_16x16x32_bf16 v[26:29], v[152:155], v[200:203], v[26:29]
	v_mfma_f32_16x16x32_bf16 v[18:21], v[160:163], v[200:203], v[18:21]
	v_mfma_f32_16x16x32_bf16 v[10:13], v[152:155], v[208:211], v[10:13]
	v_mfma_f32_16x16x32_bf16 v[2:5], v[160:163], v[208:211], v[2:5]
	v_mfma_f32_16x16x32_bf16 v[62:65], v[156:159], v[188:191], v[62:65]
	v_mfma_f32_16x16x32_bf16 v[50:53], v[164:167], v[188:191], v[50:53]
	v_mfma_f32_16x16x32_bf16 v[42:45], v[156:159], v[196:199], v[42:45]
	v_mfma_f32_16x16x32_bf16 v[34:37], v[164:167], v[196:199], v[34:37]
	v_mfma_f32_16x16x32_bf16 v[26:29], v[156:159], v[204:207], v[26:29]
	v_mfma_f32_16x16x32_bf16 v[18:21], v[164:167], v[204:207], v[18:21]
	v_mfma_f32_16x16x32_bf16 v[10:13], v[156:159], v[212:215], v[10:13]
	v_mfma_f32_16x16x32_bf16 v[2:5], v[164:167], v[212:215], v[2:5]
	s_setprio 0
	s_setprio 1
	v_mfma_f32_16x16x32_bf16 v[70:73], v[168:171], v[184:187], v[70:73]
	v_mfma_f32_16x16x32_bf16 v[54:57], v[176:179], v[184:187], v[54:57]
	v_mfma_f32_16x16x32_bf16 v[46:49], v[168:171], v[192:195], v[46:49]
	v_mfma_f32_16x16x32_bf16 v[38:41], v[176:179], v[192:195], v[38:41]
	v_mfma_f32_16x16x32_bf16 v[30:33], v[168:171], v[200:203], v[30:33]
	v_mfma_f32_16x16x32_bf16 v[22:25], v[176:179], v[200:203], v[22:25]
	v_mfma_f32_16x16x32_bf16 v[14:17], v[168:171], v[208:211], v[14:17]
	v_mfma_f32_16x16x32_bf16 v[6:9], v[176:179], v[208:211], v[6:9]
	v_mfma_f32_16x16x32_bf16 v[70:73], v[172:175], v[188:191], v[70:73]
	v_mfma_f32_16x16x32_bf16 v[54:57], v[180:183], v[188:191], v[54:57]
	v_mfma_f32_16x16x32_bf16 v[46:49], v[172:175], v[196:199], v[46:49]
	v_mfma_f32_16x16x32_bf16 v[38:41], v[180:183], v[196:199], v[38:41]
	v_mfma_f32_16x16x32_bf16 v[30:33], v[172:175], v[204:207], v[30:33]
	v_mfma_f32_16x16x32_bf16 v[22:25], v[180:183], v[204:207], v[22:25]
	v_mfma_f32_16x16x32_bf16 v[14:17], v[172:175], v[212:215], v[14:17]
	v_mfma_f32_16x16x32_bf16 v[6:9], v[180:183], v[212:215], v[6:9]
	s_barrier
;     ...
;         for (int t = 2; t < nt; t += 2) PG8_KITER(t);
	s_setprio 0
	ds_read_b128 v[152:155], v149
	ds_read_b128 v[156:159], v149 offset:1024
	ds_read_b128 v[160:163], v149 offset:2048
	ds_read_b128 v[164:167], v149 offset:3072
	ds_read_b128 v[168:171], v150
	ds_read_b128 v[172:175], v150 offset:1024
	s_add_u32 s16, s74, 0x100000
	s_addc_u32 s17, s75, 0
	s_mov_b32 m0, s29
	ds_read_b128 v[180:183], v150 offset:3072
	global_load_lds_dwordx4 v136, s[100:101]
	s_mov_b32 m0, s33
	ds_read_b128 v[176:179], v150 offset:2048
	global_load_lds_dwordx4 v132, s[100:101]
	s_mov_b32 m0, s58
	ds_read_b128 v[184:187], v148 offset:32768
	ds_read_b128 v[188:191], v148 offset:33792
	ds_read_b128 v[192:195], v148 offset:34816
	ds_read_b128 v[196:199], v148 offset:35840
	ds_read_b128 v[200:203], v148 offset:36864
	ds_read_b128 v[204:207], v148 offset:37888
	ds_read_b128 v[208:211], v148 offset:38912
	global_load_lds_dwordx4 v136, s[16:17]
	s_mov_b32 m0, s59
	ds_read_b128 v[212:215], v148 offset:39936
	global_load_lds_dwordx4 v132, s[16:17]
	s_waitcnt vmcnt(8) lgkmcnt(0)
	s_setprio 1
	s_barrier
	v_mfma_f32_16x16x32_bf16 v[122:125], v[152:155], v[184:187], v[122:125]
	v_mfma_f32_16x16x32_bf16 v[114:117], v[160:163], v[184:187], v[114:117]
	v_mfma_f32_16x16x32_bf16 v[106:109], v[152:155], v[192:195], v[106:109]
	v_mfma_f32_16x16x32_bf16 v[98:101], v[160:163], v[192:195], v[98:101]
	v_mfma_f32_16x16x32_bf16 v[90:93], v[152:155], v[200:203], v[90:93]
	v_mfma_f32_16x16x32_bf16 v[82:85], v[160:163], v[200:203], v[82:85]
	v_mfma_f32_16x16x32_bf16 v[74:77], v[152:155], v[208:211], v[74:77]
	v_mfma_f32_16x16x32_bf16 v[58:61], v[160:163], v[208:211], v[58:61]
	v_mfma_f32_16x16x32_bf16 v[122:125], v[156:159], v[188:191], v[122:125]
	v_mfma_f32_16x16x32_bf16 v[114:117], v[164:167], v[188:191], v[114:117]
	v_mfma_f32_16x16x32_bf16 v[106:109], v[156:159], v[196:199], v[106:109]
	v_mfma_f32_16x16x32_bf16 v[98:101], v[164:167], v[196:199], v[98:101]
	v_mfma_f32_16x16x32_bf16 v[90:93], v[156:159], v[204:207], v[90:93]
	v_mfma_f32_16x16x32_bf16 v[82:85], v[164:167], v[204:207], v[82:85]
	v_mfma_f32_16x16x32_bf16 v[74:77], v[156:159], v[212:215], v[74:77]
	v_mfma_f32_16x16x32_bf16 v[58:61], v[164:167], v[212:215], v[58:61]
	s_setprio 0
	s_setprio 1
	v_mfma_f32_16x16x32_bf16 v[126:129], v[168:171], v[184:187], v[126:129]
	v_mfma_f32_16x16x32_bf16 v[118:121], v[176:179], v[184:187], v[118:121]
	v_mfma_f32_16x16x32_bf16 v[110:113], v[168:171], v[192:195], v[110:113]
	v_mfma_f32_16x16x32_bf16 v[102:105], v[176:179], v[192:195], v[102:105]
	v_mfma_f32_16x16x32_bf16 v[94:97], v[168:171], v[200:203], v[94:97]
	v_mfma_f32_16x16x32_bf16 v[86:89], v[176:179], v[200:203], v[86:89]
	v_mfma_f32_16x16x32_bf16 v[78:81], v[168:171], v[208:211], v[78:81]
	v_mfma_f32_16x16x32_bf16 v[66:69], v[176:179], v[208:211], v[66:69]
	v_mfma_f32_16x16x32_bf16 v[126:129], v[172:175], v[188:191], v[126:129]
	v_mfma_f32_16x16x32_bf16 v[118:121], v[180:183], v[188:191], v[118:121]
	v_mfma_f32_16x16x32_bf16 v[110:113], v[172:175], v[196:199], v[110:113]
	v_mfma_f32_16x16x32_bf16 v[102:105], v[180:183], v[196:199], v[102:105]
	v_mfma_f32_16x16x32_bf16 v[94:97], v[172:175], v[204:207], v[94:97]
	v_mfma_f32_16x16x32_bf16 v[86:89], v[180:183], v[204:207], v[86:89]
	v_mfma_f32_16x16x32_bf16 v[78:81], v[172:175], v[212:215], v[78:81]
	v_mfma_f32_16x16x32_bf16 v[66:69], v[180:183], v[212:215], v[66:69]
	s_barrier
	s_setprio 0
	s_mov_b32 m0, s87
	s_add_u32 s98, s98, 0x80
	s_addc_u32 s99, s99, 0
	s_add_u32 s100, s100, 0x80
	s_addc_u32 s101, s101, 0
	s_add_u32 s16, s66, 0x100080
	ds_read_b128 v[184:187], v148 offset:49152
	ds_read_b128 v[188:191], v148 offset:50176
	ds_read_b128 v[192:195], v148 offset:51200
	ds_read_b128 v[196:199], v148 offset:52224
	ds_read_b128 v[200:203], v148 offset:53248
	ds_read_b128 v[204:207], v148 offset:54272
	global_load_lds_dwordx4 v134, s[98:99]
	s_mov_b32 m0, s88
	s_addc_u32 s17, s67, 0
	global_load_lds_dwordx4 v130, s[98:99]
	s_mov_b32 m0, s89
	ds_read_b128 v[212:215], v148 offset:56320
	global_load_lds_dwordx4 v134, s[16:17]
	s_mov_b32 m0, s56
	ds_read_b128 v[208:211], v148 offset:55296
	global_load_lds_dwordx4 v130, s[16:17]
	s_waitcnt vmcnt(6) lgkmcnt(0)
	s_setprio 1
	s_barrier
	v_mfma_f32_16x16x32_bf16 v[62:65], v[152:155], v[184:187], v[62:65]
	v_mfma_f32_16x16x32_bf16 v[50:53], v[160:163], v[184:187], v[50:53]
	v_mfma_f32_16x16x32_bf16 v[42:45], v[152:155], v[192:195], v[42:45]
	v_mfma_f32_16x16x32_bf16 v[34:37], v[160:163], v[192:195], v[34:37]
	v_mfma_f32_16x16x32_bf16 v[26:29], v[152:155], v[200:203], v[26:29]
	v_mfma_f32_16x16x32_bf16 v[18:21], v[160:163], v[200:203], v[18:21]
	v_mfma_f32_16x16x32_bf16 v[10:13], v[152:155], v[208:211], v[10:13]
	v_mfma_f32_16x16x32_bf16 v[2:5], v[160:163], v[208:211], v[2:5]
	v_mfma_f32_16x16x32_bf16 v[62:65], v[156:159], v[188:191], v[62:65]
	v_mfma_f32_16x16x32_bf16 v[50:53], v[164:167], v[188:191], v[50:53]
	v_mfma_f32_16x16x32_bf16 v[42:45], v[156:159], v[196:199], v[42:45]
	v_mfma_f32_16x16x32_bf16 v[34:37], v[164:167], v[196:199], v[34:37]
	v_mfma_f32_16x16x32_bf16 v[26:29], v[156:159], v[204:207], v[26:29]
	v_mfma_f32_16x16x32_bf16 v[18:21], v[164:167], v[204:207], v[18:21]
	v_mfma_f32_16x16x32_bf16 v[10:13], v[156:159], v[212:215], v[10:13]
	v_mfma_f32_16x16x32_bf16 v[2:5], v[164:167], v[212:215], v[2:5]
	s_setprio 0
	s_setprio 1
	v_mfma_f32_16x16x32_bf16 v[70:73], v[168:171], v[184:187], v[70:73]
	v_mfma_f32_16x16x32_bf16 v[54:57], v[176:179], v[184:187], v[54:57]
	v_mfma_f32_16x16x32_bf16 v[46:49], v[168:171], v[192:195], v[46:49]
	v_mfma_f32_16x16x32_bf16 v[38:41], v[176:179], v[192:195], v[38:41]
	v_mfma_f32_16x16x32_bf16 v[30:33], v[168:171], v[200:203], v[30:33]
	v_mfma_f32_16x16x32_bf16 v[22:25], v[176:179], v[200:203], v[22:25]
	v_mfma_f32_16x16x32_bf16 v[14:17], v[168:171], v[208:211], v[14:17]
	v_mfma_f32_16x16x32_bf16 v[6:9], v[176:179], v[208:211], v[6:9]
	v_mfma_f32_16x16x32_bf16 v[70:73], v[172:175], v[188:191], v[70:73]
	v_mfma_f32_16x16x32_bf16 v[54:57], v[180:183], v[188:191], v[54:57]
	v_mfma_f32_16x16x32_bf16 v[46:49], v[172:175], v[196:199], v[46:49]
	v_mfma_f32_16x16x32_bf16 v[38:41], v[180:183], v[196:199], v[38:41]
	v_mfma_f32_16x16x32_bf16 v[30:33], v[172:175], v[204:207], v[30:33]
	v_mfma_f32_16x16x32_bf16 v[22:25], v[180:183], v[204:207], v[22:25]
	v_mfma_f32_16x16x32_bf16 v[14:17], v[172:175], v[212:215], v[14:17]
	v_mfma_f32_16x16x32_bf16 v[6:9], v[180:183], v[212:215], v[6:9]
	s_barrier
	s_setprio 0
	s_add_i32 s15, s15, 2
	s_add_u32 s70, s70, 0x100
	s_addc_u32 s71, s71, 0
	s_add_u32 s57, s57, 0x100
	s_addc_u32 s14, s14, 0
	s_cmp_gt_u32 s15, 61
	s_cbranch_scc0 .LBB0_249
	s_mov_b32 m0, s65
	s_nop 0
	global_load_lds_dwordx4 v136, s[100:101]
	s_mov_b32 m0, s76
	s_nop 0
	global_load_lds_dwordx4 v132, s[100:101]
	s_and_b64 vcc, exec, s[12:13]
	s_cbranch_vccz .LBB0_252
	s_barrier

.Lrb2_skip_9715:
	s_mov_b32 m0, s86
	ds_read_b128 v[164:167], v209
	ds_read_b128 v[168:171], v209 offset:1024
	ds_read_b128 v[172:175], v209 offset:2048
	ds_read_b128 v[194:197], v209 offset:3072
	ds_read_b128 v[198:201], v209 offset:4096
	ds_read_b128 v[202:205], v209 offset:5120
	ds_read_b128 v[210:213], v209 offset:6144
	global_load_lds_dwordx4 v186, s[66:67]
	s_mov_b32 m0, s87
	ds_read_b128 v[214:217], v209 offset:7168
	global_load_lds_dwordx4 v188, s[66:67]
	s_waitcnt vmcnt(8) lgkmcnt(0)
	s_setprio 1
	s_barrier
	v_mfma_f32_16x16x32_bf16 v[122:125], v[132:135], v[164:167], v[122:125]
	v_mfma_f32_16x16x32_bf16 v[118:121], v[140:143], v[164:167], v[118:121]
	v_mfma_f32_16x16x32_bf16 v[110:113], v[132:135], v[172:175], v[110:113]
	v_mfma_f32_16x16x32_bf16 v[106:109], v[140:143], v[172:175], v[106:109]
	v_mfma_f32_16x16x32_bf16 v[94:97], v[132:135], v[198:201], v[94:97]
	v_mfma_f32_16x16x32_bf16 v[90:93], v[140:143], v[198:201], v[90:93]
	v_mfma_f32_16x16x32_bf16 v[78:81], v[132:135], v[210:213], v[78:81]
	v_mfma_f32_16x16x32_bf16 v[74:77], v[140:143], v[210:213], v[74:77]
	v_mfma_f32_16x16x32_bf16 v[122:125], v[136:139], v[168:171], v[122:125]
	v_mfma_f32_16x16x32_bf16 v[118:121], v[144:147], v[168:171], v[118:121]
	v_mfma_f32_16x16x32_bf16 v[110:113], v[136:139], v[194:197], v[110:113]
	v_mfma_f32_16x16x32_bf16 v[106:109], v[144:147], v[194:197], v[106:109]
	v_mfma_f32_16x16x32_bf16 v[94:97], v[136:139], v[202:205], v[94:97]
	v_mfma_f32_16x16x32_bf16 v[90:93], v[144:147], v[202:205], v[90:93]
	v_mfma_f32_16x16x32_bf16 v[78:81], v[136:139], v[214:217], v[78:81]
	v_mfma_f32_16x16x32_bf16 v[74:77], v[144:147], v[214:217], v[74:77]
	s_setprio 0
	s_setprio 1
	v_mfma_f32_16x16x32_bf16 v[126:129], v[148:151], v[164:167], v[126:129]
	v_mfma_f32_16x16x32_bf16 v[114:117], v[156:159], v[164:167], v[114:117]
	v_mfma_f32_16x16x32_bf16 v[102:105], v[148:151], v[172:175], v[102:105]
	v_mfma_f32_16x16x32_bf16 v[98:101], v[156:159], v[172:175], v[98:101]
	v_mfma_f32_16x16x32_bf16 v[86:89], v[148:151], v[198:201], v[86:89]
	v_mfma_f32_16x16x32_bf16 v[82:85], v[156:159], v[198:201], v[82:85]
	v_mfma_f32_16x16x32_bf16 v[70:73], v[148:151], v[210:213], v[70:73]
	v_mfma_f32_16x16x32_bf16 v[66:69], v[156:159], v[210:213], v[66:69]
	v_mfma_f32_16x16x32_bf16 v[126:129], v[152:155], v[168:171], v[126:129]
	v_mfma_f32_16x16x32_bf16 v[114:117], v[160:163], v[168:171], v[114:117]
	v_mfma_f32_16x16x32_bf16 v[102:105], v[152:155], v[194:197], v[102:105]
	v_mfma_f32_16x16x32_bf16 v[98:101], v[160:163], v[194:197], v[98:101]
	v_mfma_f32_16x16x32_bf16 v[86:89], v[152:155], v[202:205], v[86:89]
	v_mfma_f32_16x16x32_bf16 v[82:85], v[160:163], v[202:205], v[82:85]
	v_mfma_f32_16x16x32_bf16 v[70:73], v[152:155], v[214:217], v[70:73]
	v_mfma_f32_16x16x32_bf16 v[66:69], v[160:163], v[214:217], v[66:69]
	s_barrier
	s_setprio 0
	s_mov_b32 m0, s88
	s_mov_b64 s[98:99], s[70:71]
	s_add_u32 s16, s70, 0x2b0000
	ds_read_b128 v[164:167], v209 offset:16384
	ds_read_b128 v[168:171], v209 offset:17408
	ds_read_b128 v[172:175], v209 offset:18432
	ds_read_b128 v[194:197], v209 offset:19456
	ds_read_b128 v[198:201], v209 offset:20480
	ds_read_b128 v[202:205], v209 offset:21504
	ds_read_b128 v[210:213], v209 offset:22528
	global_load_lds_dwordx4 v180, s[70:71]
	s_mov_b32 m0, s84
	s_addc_u32 s17, s71, 0
	global_load_lds_dwordx4 v184, s[70:71]
	s_mov_b32 m0, s85
	s_mov_b64 s[100:101], s[74:75]
	global_load_lds_dwordx4 v180, s[16:17]
	s_mov_b32 m0, s46
	ds_read_b128 v[214:217], v209 offset:23552
	global_load_lds_dwordx4 v184, s[16:17]
	s_waitcnt vmcnt(6) lgkmcnt(0)
	s_setprio 1
	s_barrier
	v_mfma_f32_16x16x32_bf16 v[58:61], v[132:135], v[164:167], v[58:61]
	v_mfma_f32_16x16x32_bf16 v[54:57], v[140:143], v[164:167], v[54:57]
	v_mfma_f32_16x16x32_bf16 v[46:49], v[132:135], v[172:175], v[46:49]
	v_mfma_f32_16x16x32_bf16 v[42:45], v[140:143], v[172:175], v[42:45]
	v_mfma_f32_16x16x32_bf16 v[30:33], v[132:135], v[198:201], v[30:33]
	v_mfma_f32_16x16x32_bf16 v[26:29], v[140:143], v[198:201], v[26:29]
	v_mfma_f32_16x16x32_bf16 v[14:17], v[132:135], v[210:213], v[14:17]
	v_mfma_f32_16x16x32_bf16 v[10:13], v[140:143], v[210:213], v[10:13]
	v_mfma_f32_16x16x32_bf16 v[58:61], v[136:139], v[168:171], v[58:61]
	v_mfma_f32_16x16x32_bf16 v[54:57], v[144:147], v[168:171], v[54:57]
	v_mfma_f32_16x16x32_bf16 v[46:49], v[136:139], v[194:197], v[46:49]
	v_mfma_f32_16x16x32_bf16 v[42:45], v[144:147], v[194:197], v[42:45]
	v_mfma_f32_16x16x32_bf16 v[30:33], v[136:139], v[202:205], v[30:33]
	v_mfma_f32_16x16x32_bf16 v[26:29], v[144:147], v[202:205], v[26:29]
	v_mfma_f32_16x16x32_bf16 v[14:17], v[136:139], v[214:217], v[14:17]
	v_mfma_f32_16x16x32_bf16 v[10:13], v[144:147], v[214:217], v[10:13]
	s_setprio 0
	s_setprio 1
	v_mfma_f32_16x16x32_bf16 v[62:65], v[148:151], v[164:167], v[62:65]
	v_mfma_f32_16x16x32_bf16 v[50:53], v[156:159], v[164:167], v[50:53]
	v_mfma_f32_16x16x32_bf16 v[38:41], v[148:151], v[172:175], v[38:41]
	v_mfma_f32_16x16x32_bf16 v[34:37], v[156:159], v[172:175], v[34:37]
	v_mfma_f32_16x16x32_bf16 v[22:25], v[148:151], v[198:201], v[22:25]
	v_mfma_f32_16x16x32_bf16 v[18:21], v[156:159], v[198:201], v[18:21]
	v_mfma_f32_16x16x32_bf16 v[6:9], v[148:151], v[210:213], v[6:9]
	v_mfma_f32_16x16x32_bf16 v[2:5], v[156:159], v[210:213], v[2:5]
	v_mfma_f32_16x16x32_bf16 v[62:65], v[152:155], v[168:171], v[62:65]
	v_mfma_f32_16x16x32_bf16 v[50:53], v[160:163], v[168:171], v[50:53]
	v_mfma_f32_16x16x32_bf16 v[38:41], v[152:155], v[194:197], v[38:41]
	v_mfma_f32_16x16x32_bf16 v[34:37], v[160:163], v[194:197], v[34:37]
	v_mfma_f32_16x16x32_bf16 v[22:25], v[152:155], v[202:205], v[22:25]
	v_mfma_f32_16x16x32_bf16 v[18:21], v[160:163], v[202:205], v[18:21]
	v_mfma_f32_16x16x32_bf16 v[6:9], v[152:155], v[214:217], v[6:9]
	v_mfma_f32_16x16x32_bf16 v[2:5], v[160:163], v[214:217], v[2:5]
	s_barrier
;     ...
;         for (int t = 2; t < nt; t += 2) PG8_KITER(t);
	s_setprio 0
	ds_read_b128 v[132:135], v130
	ds_read_b128 v[136:139], v130 offset:1024
	ds_read_b128 v[140:143], v130 offset:2048
	ds_read_b128 v[144:147], v130 offset:3072
	ds_read_b128 v[148:151], v131
	ds_read_b128 v[152:155], v131 offset:1024
	s_add_u32 s16, s74, 0x2b0000
	s_addc_u32 s17, s75, 0
	s_mov_b32 m0, s11
	ds_read_b128 v[160:163], v131 offset:3072
	global_load_lds_dwordx4 v178, s[100:101]
	s_mov_b32 m0, s12
	ds_read_b128 v[156:159], v131 offset:2048
	global_load_lds_dwordx4 v182, s[100:101]
	s_mov_b32 m0, s13
	ds_read_b128 v[164:167], v209 offset:32768
	ds_read_b128 v[168:171], v209 offset:33792
	ds_read_b128 v[172:175], v209 offset:34816
	ds_read_b128 v[194:197], v209 offset:35840
	ds_read_b128 v[198:201], v209 offset:36864
	ds_read_b128 v[202:205], v209 offset:37888
	ds_read_b128 v[210:213], v209 offset:38912
	global_load_lds_dwordx4 v178, s[16:17]
	s_mov_b32 m0, s29
	ds_read_b128 v[214:217], v209 offset:39936
	global_load_lds_dwordx4 v182, s[16:17]
	s_waitcnt vmcnt(8) lgkmcnt(0)
	s_setprio 1
	s_barrier
	v_mfma_f32_16x16x32_bf16 v[122:125], v[132:135], v[164:167], v[122:125]
	v_mfma_f32_16x16x32_bf16 v[118:121], v[140:143], v[164:167], v[118:121]
	v_mfma_f32_16x16x32_bf16 v[110:113], v[132:135], v[172:175], v[110:113]
	v_mfma_f32_16x16x32_bf16 v[106:109], v[140:143], v[172:175], v[106:109]
	v_mfma_f32_16x16x32_bf16 v[94:97], v[132:135], v[198:201], v[94:97]
	v_mfma_f32_16x16x32_bf16 v[90:93], v[140:143], v[198:201], v[90:93]
	v_mfma_f32_16x16x32_bf16 v[78:81], v[132:135], v[210:213], v[78:81]
	v_mfma_f32_16x16x32_bf16 v[74:77], v[140:143], v[210:213], v[74:77]
	v_mfma_f32_16x16x32_bf16 v[122:125], v[136:139], v[168:171], v[122:125]
	v_mfma_f32_16x16x32_bf16 v[118:121], v[144:147], v[168:171], v[118:121]
	v_mfma_f32_16x16x32_bf16 v[110:113], v[136:139], v[194:197], v[110:113]
	v_mfma_f32_16x16x32_bf16 v[106:109], v[144:147], v[194:197], v[106:109]
	v_mfma_f32_16x16x32_bf16 v[94:97], v[136:139], v[202:205], v[94:97]
	v_mfma_f32_16x16x32_bf16 v[90:93], v[144:147], v[202:205], v[90:93]
	v_mfma_f32_16x16x32_bf16 v[78:81], v[136:139], v[214:217], v[78:81]
	v_mfma_f32_16x16x32_bf16 v[74:77], v[144:147], v[214:217], v[74:77]
	s_setprio 0
	s_setprio 1
	v_mfma_f32_16x16x32_bf16 v[126:129], v[148:151], v[164:167], v[126:129]
	v_mfma_f32_16x16x32_bf16 v[114:117], v[156:159], v[164:167], v[114:117]
	v_mfma_f32_16x16x32_bf16 v[102:105], v[148:151], v[172:175], v[102:105]
	v_mfma_f32_16x16x32_bf16 v[98:101], v[156:159], v[172:175], v[98:101]
	v_mfma_f32_16x16x32_bf16 v[86:89], v[148:151], v[198:201], v[86:89]
	v_mfma_f32_16x16x32_bf16 v[82:85], v[156:159], v[198:201], v[82:85]
	v_mfma_f32_16x16x32_bf16 v[70:73], v[148:151], v[210:213], v[70:73]
	v_mfma_f32_16x16x32_bf16 v[66:69], v[156:159], v[210:213], v[66:69]
	v_mfma_f32_16x16x32_bf16 v[126:129], v[152:155], v[168:171], v[126:129]
	v_mfma_f32_16x16x32_bf16 v[114:117], v[160:163], v[168:171], v[114:117]
	v_mfma_f32_16x16x32_bf16 v[102:105], v[152:155], v[194:197], v[102:105]
	v_mfma_f32_16x16x32_bf16 v[98:101], v[160:163], v[194:197], v[98:101]
	v_mfma_f32_16x16x32_bf16 v[86:89], v[152:155], v[202:205], v[86:89]
	v_mfma_f32_16x16x32_bf16 v[82:85], v[160:163], v[202:205], v[82:85]
	v_mfma_f32_16x16x32_bf16 v[70:73], v[152:155], v[214:217], v[70:73]
	v_mfma_f32_16x16x32_bf16 v[66:69], v[160:163], v[214:217], v[66:69]
	s_barrier
	s_setprio 0
	s_mov_b32 m0, s47
	s_add_u32 s98, s98, 0x80
	s_addc_u32 s99, s99, 0
	s_add_u32 s100, s100, 0x80
	s_addc_u32 s101, s101, 0
	s_add_u32 s16, s70, 0x2b0080
	ds_read_b128 v[164:167], v209 offset:49152
	ds_read_b128 v[168:171], v209 offset:50176
	ds_read_b128 v[172:175], v209 offset:51200
	ds_read_b128 v[194:197], v209 offset:52224
	ds_read_b128 v[198:201], v209 offset:53248
	ds_read_b128 v[202:205], v209 offset:54272
	global_load_lds_dwordx4 v180, s[98:99]
	s_mov_b32 m0, s89
	s_addc_u32 s17, s71, 0
	global_load_lds_dwordx4 v184, s[98:99]
	s_mov_b32 m0, s56
	ds_read_b128 v[214:217], v209 offset:56320
	global_load_lds_dwordx4 v180, s[16:17]
	s_mov_b32 m0, s57
	ds_read_b128 v[210:213], v209 offset:55296
	global_load_lds_dwordx4 v184, s[16:17]
	s_waitcnt vmcnt(6) lgkmcnt(0)
	s_setprio 1
	s_barrier
	v_mfma_f32_16x16x32_bf16 v[58:61], v[132:135], v[164:167], v[58:61]
	v_mfma_f32_16x16x32_bf16 v[54:57], v[140:143], v[164:167], v[54:57]
	v_mfma_f32_16x16x32_bf16 v[46:49], v[132:135], v[172:175], v[46:49]
	v_mfma_f32_16x16x32_bf16 v[42:45], v[140:143], v[172:175], v[42:45]
	v_mfma_f32_16x16x32_bf16 v[30:33], v[132:135], v[198:201], v[30:33]
	v_mfma_f32_16x16x32_bf16 v[26:29], v[140:143], v[198:201], v[26:29]
	v_mfma_f32_16x16x32_bf16 v[14:17], v[132:135], v[210:213], v[14:17]
	v_mfma_f32_16x16x32_bf16 v[10:13], v[140:143], v[210:213], v[10:13]
	v_mfma_f32_16x16x32_bf16 v[58:61], v[136:139], v[168:171], v[58:61]
	v_mfma_f32_16x16x32_bf16 v[54:57], v[144:147], v[168:171], v[54:57]
	v_mfma_f32_16x16x32_bf16 v[46:49], v[136:139], v[194:197], v[46:49]
	v_mfma_f32_16x16x32_bf16 v[42:45], v[144:147], v[194:197], v[42:45]
	v_mfma_f32_16x16x32_bf16 v[30:33], v[136:139], v[202:205], v[30:33]
	v_mfma_f32_16x16x32_bf16 v[26:29], v[144:147], v[202:205], v[26:29]
	v_mfma_f32_16x16x32_bf16 v[14:17], v[136:139], v[214:217], v[14:17]
	v_mfma_f32_16x16x32_bf16 v[10:13], v[144:147], v[214:217], v[10:13]
	s_setprio 0
	s_setprio 1
	v_mfma_f32_16x16x32_bf16 v[62:65], v[148:151], v[164:167], v[62:65]
	v_mfma_f32_16x16x32_bf16 v[50:53], v[156:159], v[164:167], v[50:53]
	v_mfma_f32_16x16x32_bf16 v[38:41], v[148:151], v[172:175], v[38:41]
	v_mfma_f32_16x16x32_bf16 v[34:37], v[156:159], v[172:175], v[34:37]
	v_mfma_f32_16x16x32_bf16 v[22:25], v[148:151], v[198:201], v[22:25]
	v_mfma_f32_16x16x32_bf16 v[18:21], v[156:159], v[198:201], v[18:21]
	v_mfma_f32_16x16x32_bf16 v[6:9], v[148:151], v[210:213], v[6:9]
	v_mfma_f32_16x16x32_bf16 v[2:5], v[156:159], v[210:213], v[2:5]
	v_mfma_f32_16x16x32_bf16 v[62:65], v[152:155], v[168:171], v[62:65]
	v_mfma_f32_16x16x32_bf16 v[50:53], v[160:163], v[168:171], v[50:53]
	v_mfma_f32_16x16x32_bf16 v[38:41], v[152:155], v[194:197], v[38:41]
	v_mfma_f32_16x16x32_bf16 v[34:37], v[160:163], v[194:197], v[34:37]
	v_mfma_f32_16x16x32_bf16 v[22:25], v[152:155], v[202:205], v[22:25]
	v_mfma_f32_16x16x32_bf16 v[18:21], v[160:163], v[202:205], v[18:21]
	v_mfma_f32_16x16x32_bf16 v[6:9], v[152:155], v[214:217], v[6:9]
	v_mfma_f32_16x16x32_bf16 v[2:5], v[160:163], v[214:217], v[2:5]
	s_barrier
	s_setprio 0
	s_add_i32 s15, s15, 2
	s_add_u32 s66, s66, 0x100
	s_addc_u32 s67, s67, 0
	s_add_u32 s90, s90, 0x100
	s_addc_u32 s14, s14, 0
	s_cmpk_gt_u32 s15, 0xa9
	s_cbranch_scc0 .LBB0_331
	s_mov_b32 m0, s58
	s_nop 0
	global_load_lds_dwordx4 v178, s[100:101]
	s_mov_b32 m0, s59
	s_nop 0
	global_load_lds_dwordx4 v182, s[100:101]
	s_and_b64 vcc, exec, s[30:31]
	s_cbranch_vccz .LBB0_334
	s_barrier

.Lrb2_skip_11871:
	s_mov_b32 m0, s89
	ds_read_b128 v[188:191], v165
	ds_read_b128 v[192:195], v165 offset:1024
	ds_read_b128 v[196:199], v165 offset:2048
	ds_read_b128 v[200:203], v165 offset:3072
	ds_read_b128 v[204:207], v165 offset:4096
	ds_read_b128 v[208:211], v165 offset:5120
	ds_read_b128 v[212:215], v165 offset:6144
	global_load_lds_dwordx4 v140, s[80:81]
	s_mov_b32 m0, s92
	ds_read_b128 v[216:219], v165 offset:7168
	global_load_lds_dwordx4 v142, s[80:81]
	s_waitcnt vmcnt(8) lgkmcnt(0)
	s_setprio 1
	s_barrier
	v_mfma_f32_16x16x32_bf16 v[118:121], v[150:153], v[188:191], v[118:121]
	v_mfma_f32_16x16x32_bf16 v[114:117], v[158:161], v[188:191], v[114:117]
	v_mfma_f32_16x16x32_bf16 v[102:105], v[150:153], v[196:199], v[102:105]
	v_mfma_f32_16x16x32_bf16 v[98:101], v[158:161], v[196:199], v[98:101]
	v_mfma_f32_16x16x32_bf16 v[86:89], v[150:153], v[204:207], v[86:89]
	v_mfma_f32_16x16x32_bf16 v[82:85], v[158:161], v[204:207], v[82:85]
	v_mfma_f32_16x16x32_bf16 v[70:73], v[150:153], v[212:215], v[70:73]
	v_mfma_f32_16x16x32_bf16 v[66:69], v[158:161], v[212:215], v[66:69]
	v_mfma_f32_16x16x32_bf16 v[118:121], v[154:157], v[192:195], v[118:121]
	v_mfma_f32_16x16x32_bf16 v[114:117], v[168:171], v[192:195], v[114:117]
	v_mfma_f32_16x16x32_bf16 v[102:105], v[154:157], v[200:203], v[102:105]
	v_mfma_f32_16x16x32_bf16 v[98:101], v[168:171], v[200:203], v[98:101]
	v_mfma_f32_16x16x32_bf16 v[86:89], v[154:157], v[208:211], v[86:89]
	v_mfma_f32_16x16x32_bf16 v[82:85], v[168:171], v[208:211], v[82:85]
	v_mfma_f32_16x16x32_bf16 v[70:73], v[154:157], v[216:219], v[70:73]
	v_mfma_f32_16x16x32_bf16 v[66:69], v[168:171], v[216:219], v[66:69]
	s_setprio 0
	s_setprio 1
	v_mfma_f32_16x16x32_bf16 v[126:129], v[172:175], v[188:191], v[126:129]
	v_mfma_f32_16x16x32_bf16 v[122:125], v[180:183], v[188:191], v[122:125]
	v_mfma_f32_16x16x32_bf16 v[110:113], v[172:175], v[196:199], v[110:113]
	v_mfma_f32_16x16x32_bf16 v[106:109], v[180:183], v[196:199], v[106:109]
	v_mfma_f32_16x16x32_bf16 v[94:97], v[172:175], v[204:207], v[94:97]
	v_mfma_f32_16x16x32_bf16 v[90:93], v[180:183], v[204:207], v[90:93]
	v_mfma_f32_16x16x32_bf16 v[78:81], v[172:175], v[212:215], v[78:81]
	v_mfma_f32_16x16x32_bf16 v[74:77], v[180:183], v[212:215], v[74:77]
	v_mfma_f32_16x16x32_bf16 v[126:129], v[176:179], v[192:195], v[126:129]
	v_mfma_f32_16x16x32_bf16 v[122:125], v[184:187], v[192:195], v[122:125]
	v_mfma_f32_16x16x32_bf16 v[110:113], v[176:179], v[200:203], v[110:113]
	v_mfma_f32_16x16x32_bf16 v[106:109], v[184:187], v[200:203], v[106:109]
	v_mfma_f32_16x16x32_bf16 v[94:97], v[176:179], v[208:211], v[94:97]
	v_mfma_f32_16x16x32_bf16 v[90:93], v[184:187], v[208:211], v[90:93]
	v_mfma_f32_16x16x32_bf16 v[78:81], v[176:179], v[216:219], v[78:81]
	v_mfma_f32_16x16x32_bf16 v[74:77], v[184:187], v[216:219], v[74:77]
	s_barrier
	s_setprio 0
	s_mov_b32 m0, vcc_hi
	s_mov_b64 s[98:99], s[6:7]
	s_add_u32 s16, s6, 0x100000
	ds_read_b128 v[188:191], v165 offset:16384
	ds_read_b128 v[192:195], v165 offset:17408
	ds_read_b128 v[196:199], v165 offset:18432
	ds_read_b128 v[200:203], v165 offset:19456
	ds_read_b128 v[204:207], v165 offset:20480
	ds_read_b128 v[208:211], v165 offset:21504
	ds_read_b128 v[212:215], v165 offset:22528
	global_load_lds_dwordx4 v134, s[6:7]
	s_mov_b32 m0, s84
	s_addc_u32 s17, s7, 0
	global_load_lds_dwordx4 v130, s[6:7]
	s_mov_b32 m0, s85
	s_mov_b64 s[100:101], s[82:83]
	global_load_lds_dwordx4 v134, s[16:17]
	s_mov_b32 m0, s46
	ds_read_b128 v[216:219], v165 offset:23552
	global_load_lds_dwordx4 v130, s[16:17]
	s_waitcnt vmcnt(6) lgkmcnt(0)
	s_setprio 1
	s_barrier
	v_mfma_f32_16x16x32_bf16 v[54:57], v[150:153], v[188:191], v[54:57]
	v_mfma_f32_16x16x32_bf16 v[50:53], v[158:161], v[188:191], v[50:53]
	v_mfma_f32_16x16x32_bf16 v[38:41], v[150:153], v[196:199], v[38:41]
	v_mfma_f32_16x16x32_bf16 v[34:37], v[158:161], v[196:199], v[34:37]
	v_mfma_f32_16x16x32_bf16 v[22:25], v[150:153], v[204:207], v[22:25]
	v_mfma_f32_16x16x32_bf16 v[18:21], v[158:161], v[204:207], v[18:21]
	v_mfma_f32_16x16x32_bf16 v[6:9], v[150:153], v[212:215], v[6:9]
	v_mfma_f32_16x16x32_bf16 v[2:5], v[158:161], v[212:215], v[2:5]
	v_mfma_f32_16x16x32_bf16 v[54:57], v[154:157], v[192:195], v[54:57]
	v_mfma_f32_16x16x32_bf16 v[50:53], v[168:171], v[192:195], v[50:53]
	v_mfma_f32_16x16x32_bf16 v[38:41], v[154:157], v[200:203], v[38:41]
	v_mfma_f32_16x16x32_bf16 v[34:37], v[168:171], v[200:203], v[34:37]
	v_mfma_f32_16x16x32_bf16 v[22:25], v[154:157], v[208:211], v[22:25]
	v_mfma_f32_16x16x32_bf16 v[18:21], v[168:171], v[208:211], v[18:21]
	v_mfma_f32_16x16x32_bf16 v[6:9], v[154:157], v[216:219], v[6:9]
	v_mfma_f32_16x16x32_bf16 v[2:5], v[168:171], v[216:219], v[2:5]
	s_setprio 0
	s_setprio 1
	v_mfma_f32_16x16x32_bf16 v[62:65], v[172:175], v[188:191], v[62:65]
	v_mfma_f32_16x16x32_bf16 v[58:61], v[180:183], v[188:191], v[58:61]
	v_mfma_f32_16x16x32_bf16 v[46:49], v[172:175], v[196:199], v[46:49]
	v_mfma_f32_16x16x32_bf16 v[42:45], v[180:183], v[196:199], v[42:45]
	v_mfma_f32_16x16x32_bf16 v[30:33], v[172:175], v[204:207], v[30:33]
	v_mfma_f32_16x16x32_bf16 v[26:29], v[180:183], v[204:207], v[26:29]
	v_mfma_f32_16x16x32_bf16 v[14:17], v[172:175], v[212:215], v[14:17]
	v_mfma_f32_16x16x32_bf16 v[10:13], v[180:183], v[212:215], v[10:13]
	v_mfma_f32_16x16x32_bf16 v[62:65], v[176:179], v[192:195], v[62:65]
	v_mfma_f32_16x16x32_bf16 v[58:61], v[184:187], v[192:195], v[58:61]
	v_mfma_f32_16x16x32_bf16 v[46:49], v[176:179], v[200:203], v[46:49]
	v_mfma_f32_16x16x32_bf16 v[42:45], v[184:187], v[200:203], v[42:45]
	v_mfma_f32_16x16x32_bf16 v[30:33], v[176:179], v[208:211], v[30:33]
	v_mfma_f32_16x16x32_bf16 v[26:29], v[184:187], v[208:211], v[26:29]
	v_mfma_f32_16x16x32_bf16 v[14:17], v[176:179], v[216:219], v[14:17]
	v_mfma_f32_16x16x32_bf16 v[10:13], v[184:187], v[216:219], v[10:13]
	s_barrier
;     ...
;         for (int t = 2; t < nt; t += 2) PG8_KITER(t);
	s_setprio 0
	ds_read_b128 v[150:153], v138
	ds_read_b128 v[154:157], v138 offset:1024
	ds_read_b128 v[158:161], v138 offset:2048
	ds_read_b128 v[168:171], v138 offset:3072
	ds_read_b128 v[172:175], v148
	ds_read_b128 v[176:179], v148 offset:1024
	s_add_u32 s16, s82, 0x100000
	s_addc_u32 s17, s83, 0
	s_mov_b32 m0, s86
	ds_read_b128 v[184:187], v148 offset:3072
	global_load_lds_dwordx4 v136, s[100:101]
	s_mov_b32 m0, s93
	ds_read_b128 v[180:183], v148 offset:2048
	global_load_lds_dwordx4 v132, s[100:101]
	s_mov_b32 m0, s94
	ds_read_b128 v[188:191], v165 offset:32768
	ds_read_b128 v[192:195], v165 offset:33792
	ds_read_b128 v[196:199], v165 offset:34816
	ds_read_b128 v[200:203], v165 offset:35840
	ds_read_b128 v[204:207], v165 offset:36864
	ds_read_b128 v[208:211], v165 offset:37888
	ds_read_b128 v[212:215], v165 offset:38912
	global_load_lds_dwordx4 v136, s[16:17]
	s_mov_b32 m0, s95
	ds_read_b128 v[216:219], v165 offset:39936
	global_load_lds_dwordx4 v132, s[16:17]
	s_waitcnt vmcnt(8) lgkmcnt(0)
	s_setprio 1
	s_barrier
	v_mfma_f32_16x16x32_bf16 v[118:121], v[150:153], v[188:191], v[118:121]
	v_mfma_f32_16x16x32_bf16 v[114:117], v[158:161], v[188:191], v[114:117]
	v_mfma_f32_16x16x32_bf16 v[102:105], v[150:153], v[196:199], v[102:105]
	v_mfma_f32_16x16x32_bf16 v[98:101], v[158:161], v[196:199], v[98:101]
	v_mfma_f32_16x16x32_bf16 v[86:89], v[150:153], v[204:207], v[86:89]
	v_mfma_f32_16x16x32_bf16 v[82:85], v[158:161], v[204:207], v[82:85]
	v_mfma_f32_16x16x32_bf16 v[70:73], v[150:153], v[212:215], v[70:73]
	v_mfma_f32_16x16x32_bf16 v[66:69], v[158:161], v[212:215], v[66:69]
	v_mfma_f32_16x16x32_bf16 v[118:121], v[154:157], v[192:195], v[118:121]
	v_mfma_f32_16x16x32_bf16 v[114:117], v[168:171], v[192:195], v[114:117]
	v_mfma_f32_16x16x32_bf16 v[102:105], v[154:157], v[200:203], v[102:105]
	v_mfma_f32_16x16x32_bf16 v[98:101], v[168:171], v[200:203], v[98:101]
	v_mfma_f32_16x16x32_bf16 v[86:89], v[154:157], v[208:211], v[86:89]
	v_mfma_f32_16x16x32_bf16 v[82:85], v[168:171], v[208:211], v[82:85]
	v_mfma_f32_16x16x32_bf16 v[70:73], v[154:157], v[216:219], v[70:73]
	v_mfma_f32_16x16x32_bf16 v[66:69], v[168:171], v[216:219], v[66:69]
	s_setprio 0
	s_setprio 1
	v_mfma_f32_16x16x32_bf16 v[126:129], v[172:175], v[188:191], v[126:129]
	v_mfma_f32_16x16x32_bf16 v[122:125], v[180:183], v[188:191], v[122:125]
	v_mfma_f32_16x16x32_bf16 v[110:113], v[172:175], v[196:199], v[110:113]
	v_mfma_f32_16x16x32_bf16 v[106:109], v[180:183], v[196:199], v[106:109]
	v_mfma_f32_16x16x32_bf16 v[94:97], v[172:175], v[204:207], v[94:97]
	v_mfma_f32_16x16x32_bf16 v[90:93], v[180:183], v[204:207], v[90:93]
	v_mfma_f32_16x16x32_bf16 v[78:81], v[172:175], v[212:215], v[78:81]
	v_mfma_f32_16x16x32_bf16 v[74:77], v[180:183], v[212:215], v[74:77]
	v_mfma_f32_16x16x32_bf16 v[126:129], v[176:179], v[192:195], v[126:129]
	v_mfma_f32_16x16x32_bf16 v[122:125], v[184:187], v[192:195], v[122:125]
	v_mfma_f32_16x16x32_bf16 v[110:113], v[176:179], v[200:203], v[110:113]
	v_mfma_f32_16x16x32_bf16 v[106:109], v[184:187], v[200:203], v[106:109]
	v_mfma_f32_16x16x32_bf16 v[94:97], v[176:179], v[208:211], v[94:97]
	v_mfma_f32_16x16x32_bf16 v[90:93], v[184:187], v[208:211], v[90:93]
	v_mfma_f32_16x16x32_bf16 v[78:81], v[176:179], v[216:219], v[78:81]
	v_mfma_f32_16x16x32_bf16 v[74:77], v[184:187], v[216:219], v[74:77]
	s_barrier
	s_setprio 0
	s_mov_b32 m0, s47
	s_add_u32 s98, s98, 0x80
	s_addc_u32 s99, s99, 0
	s_add_u32 s100, s100, 0x80
	s_addc_u32 s101, s101, 0
	s_add_u32 s6, s6, 0x100080
	ds_read_b128 v[188:191], v165 offset:49152
	ds_read_b128 v[192:195], v165 offset:50176
	ds_read_b128 v[196:199], v165 offset:51200
	ds_read_b128 v[200:203], v165 offset:52224
	ds_read_b128 v[204:207], v165 offset:53248
	ds_read_b128 v[208:211], v165 offset:54272
	global_load_lds_dwordx4 v134, s[98:99]
	s_mov_b32 m0, s91
	s_addc_u32 s7, s7, 0
	global_load_lds_dwordx4 v130, s[98:99]
	s_mov_b32 m0, s56
	ds_read_b128 v[216:219], v165 offset:56320
	global_load_lds_dwordx4 v134, s[6:7]
	s_mov_b32 m0, s57
	ds_read_b128 v[212:215], v165 offset:55296
	global_load_lds_dwordx4 v130, s[6:7]
	s_waitcnt vmcnt(6) lgkmcnt(0)
	s_setprio 1
	s_barrier
	v_mfma_f32_16x16x32_bf16 v[54:57], v[150:153], v[188:191], v[54:57]
	v_mfma_f32_16x16x32_bf16 v[50:53], v[158:161], v[188:191], v[50:53]
	v_mfma_f32_16x16x32_bf16 v[38:41], v[150:153], v[196:199], v[38:41]
	v_mfma_f32_16x16x32_bf16 v[34:37], v[158:161], v[196:199], v[34:37]
	v_mfma_f32_16x16x32_bf16 v[22:25], v[150:153], v[204:207], v[22:25]
	v_mfma_f32_16x16x32_bf16 v[18:21], v[158:161], v[204:207], v[18:21]
	v_mfma_f32_16x16x32_bf16 v[6:9], v[150:153], v[212:215], v[6:9]
	v_mfma_f32_16x16x32_bf16 v[2:5], v[158:161], v[212:215], v[2:5]
	v_mfma_f32_16x16x32_bf16 v[54:57], v[154:157], v[192:195], v[54:57]
	v_mfma_f32_16x16x32_bf16 v[50:53], v[168:171], v[192:195], v[50:53]
	v_mfma_f32_16x16x32_bf16 v[38:41], v[154:157], v[200:203], v[38:41]
	v_mfma_f32_16x16x32_bf16 v[34:37], v[168:171], v[200:203], v[34:37]
	v_mfma_f32_16x16x32_bf16 v[22:25], v[154:157], v[208:211], v[22:25]
	v_mfma_f32_16x16x32_bf16 v[18:21], v[168:171], v[208:211], v[18:21]
	v_mfma_f32_16x16x32_bf16 v[6:9], v[154:157], v[216:219], v[6:9]
	v_mfma_f32_16x16x32_bf16 v[2:5], v[168:171], v[216:219], v[2:5]
	s_setprio 0
	s_setprio 1
	v_mfma_f32_16x16x32_bf16 v[62:65], v[172:175], v[188:191], v[62:65]
	v_mfma_f32_16x16x32_bf16 v[58:61], v[180:183], v[188:191], v[58:61]
	v_mfma_f32_16x16x32_bf16 v[46:49], v[172:175], v[196:199], v[46:49]
	v_mfma_f32_16x16x32_bf16 v[42:45], v[180:183], v[196:199], v[42:45]
	v_mfma_f32_16x16x32_bf16 v[30:33], v[172:175], v[204:207], v[30:33]
	v_mfma_f32_16x16x32_bf16 v[26:29], v[180:183], v[204:207], v[26:29]
	v_mfma_f32_16x16x32_bf16 v[14:17], v[172:175], v[212:215], v[14:17]
	v_mfma_f32_16x16x32_bf16 v[10:13], v[180:183], v[212:215], v[10:13]
	v_mfma_f32_16x16x32_bf16 v[62:65], v[176:179], v[192:195], v[62:65]
	v_mfma_f32_16x16x32_bf16 v[58:61], v[184:187], v[192:195], v[58:61]
	v_mfma_f32_16x16x32_bf16 v[46:49], v[176:179], v[200:203], v[46:49]
	v_mfma_f32_16x16x32_bf16 v[42:45], v[184:187], v[200:203], v[42:45]
	v_mfma_f32_16x16x32_bf16 v[30:33], v[176:179], v[208:211], v[30:33]
	v_mfma_f32_16x16x32_bf16 v[26:29], v[184:187], v[208:211], v[26:29]
	v_mfma_f32_16x16x32_bf16 v[14:17], v[176:179], v[216:219], v[14:17]
	v_mfma_f32_16x16x32_bf16 v[10:13], v[184:187], v[216:219], v[10:13]
	s_barrier
	s_setprio 0
	s_add_i32 s15, s15, 2
	s_add_u32 s80, s80, 0x100
	s_addc_u32 s81, s81, 0
	s_add_u32 s30, s30, 0x100
	s_addc_u32 s14, s14, 0
	s_cmp_gt_u32 s15, 61
	s_cbranch_scc0 .LBB0_415
	s_mov_b32 m0, s96
	s_nop 0
	global_load_lds_dwordx4 v136, s[100:101]
	s_mov_b32 m0, s97
	s_nop 0
	global_load_lds_dwordx4 v132, s[100:101]
	s_and_b64 vcc, exec, s[64:65]
	s_cbranch_vccz .LBB0_418
	s_barrier

.Lrb2_skip_14078:
	s_mov_b32 m0, s96
	ds_read_b128 v[178:181], v143
	ds_read_b128 v[182:185], v143 offset:1024
	ds_read_b128 v[186:189], v143 offset:2048
	ds_read_b128 v[190:193], v143 offset:3072
	ds_read_b128 v[194:197], v143 offset:4096
	ds_read_b128 v[198:201], v143 offset:5120
	ds_read_b128 v[202:205], v143 offset:6144
	global_load_lds_dwordx4 v136, s[78:79]
	s_mov_b32 m0, s97
	ds_read_b128 v[206:209], v143 offset:7168
	global_load_lds_dwordx4 v138, s[78:79]
	s_waitcnt vmcnt(8) lgkmcnt(0)
	s_setprio 1
	s_barrier
	v_mfma_f32_16x16x32_bf16 v[34:37], v[146:149], v[178:181], v[34:37]
	v_mfma_f32_16x16x32_bf16 v[38:41], v[154:157], v[178:181], v[38:41]
	v_mfma_f32_16x16x32_bf16 v[18:21], v[146:149], v[186:189], v[18:21]
	v_mfma_f32_16x16x32_bf16 v[22:25], v[154:157], v[186:189], v[22:25]
	v_mfma_f32_16x16x32_bf16 v[10:13], v[146:149], v[194:197], v[10:13]
	v_mfma_f32_16x16x32_bf16 v[14:17], v[154:157], v[194:197], v[14:17]
	v_mfma_f32_16x16x32_bf16 v[2:5], v[146:149], v[202:205], v[2:5]
	v_mfma_f32_16x16x32_bf16 v[6:9], v[154:157], v[202:205], v[6:9]
	v_mfma_f32_16x16x32_bf16 v[34:37], v[150:153], v[182:185], v[34:37]
	v_mfma_f32_16x16x32_bf16 v[38:41], v[158:161], v[182:185], v[38:41]
	v_mfma_f32_16x16x32_bf16 v[18:21], v[150:153], v[190:193], v[18:21]
	v_mfma_f32_16x16x32_bf16 v[22:25], v[158:161], v[190:193], v[22:25]
	v_mfma_f32_16x16x32_bf16 v[10:13], v[150:153], v[198:201], v[10:13]
	v_mfma_f32_16x16x32_bf16 v[14:17], v[158:161], v[198:201], v[14:17]
	v_mfma_f32_16x16x32_bf16 v[2:5], v[150:153], v[206:209], v[2:5]
	v_mfma_f32_16x16x32_bf16 v[6:9], v[158:161], v[206:209], v[6:9]
	s_setprio 0
	s_setprio 1
	v_mfma_f32_16x16x32_bf16 v[66:69], v[162:165], v[178:181], v[66:69]
	v_mfma_f32_16x16x32_bf16 v[70:73], v[170:173], v[178:181], v[70:73]
	v_mfma_f32_16x16x32_bf16 v[54:57], v[162:165], v[186:189], v[54:57]
	v_mfma_f32_16x16x32_bf16 v[62:65], v[170:173], v[186:189], v[62:65]
	v_mfma_f32_16x16x32_bf16 v[42:45], v[162:165], v[194:197], v[42:45]
	v_mfma_f32_16x16x32_bf16 v[46:49], v[170:173], v[194:197], v[46:49]
	v_mfma_f32_16x16x32_bf16 v[26:29], v[162:165], v[202:205], v[26:29]
	v_mfma_f32_16x16x32_bf16 v[30:33], v[170:173], v[202:205], v[30:33]
	v_mfma_f32_16x16x32_bf16 v[66:69], v[166:169], v[182:185], v[66:69]
	v_mfma_f32_16x16x32_bf16 v[70:73], v[174:177], v[182:185], v[70:73]
	v_mfma_f32_16x16x32_bf16 v[54:57], v[166:169], v[190:193], v[54:57]
	v_mfma_f32_16x16x32_bf16 v[62:65], v[174:177], v[190:193], v[62:65]
	v_mfma_f32_16x16x32_bf16 v[42:45], v[166:169], v[198:201], v[42:45]
	v_mfma_f32_16x16x32_bf16 v[46:49], v[174:177], v[198:201], v[46:49]
	v_mfma_f32_16x16x32_bf16 v[26:29], v[166:169], v[206:209], v[26:29]
	v_mfma_f32_16x16x32_bf16 v[30:33], v[174:177], v[206:209], v[30:33]
	s_barrier
	s_setprio 0
	s_mov_b32 m0, vcc_lo
	s_mov_b64 s[98:99], s[76:77]
	s_add_u32 s20, s76, 0x100000
	ds_read_b128 v[178:181], v143 offset:16384
	ds_read_b128 v[182:185], v143 offset:17408
	ds_read_b128 v[186:189], v143 offset:18432
	ds_read_b128 v[190:193], v143 offset:19456
	ds_read_b128 v[194:197], v143 offset:20480
	ds_read_b128 v[198:201], v143 offset:21504
	ds_read_b128 v[202:205], v143 offset:22528
	global_load_lds_dwordx4 v132, s[76:77]
	s_mov_b32 m0, s84
	s_addc_u32 s21, s77, 0
	global_load_lds_dwordx4 v130, s[76:77]
	s_mov_b32 m0, s85
	s_mov_b64 s[100:101], s[80:81]
	global_load_lds_dwordx4 v132, s[20:21]
	s_mov_b32 m0, s46
	ds_read_b128 v[206:209], v143 offset:23552
	global_load_lds_dwordx4 v130, s[20:21]
	s_waitcnt vmcnt(6) lgkmcnt(0)
	s_setprio 1
	s_barrier
	v_mfma_f32_16x16x32_bf16 v[102:105], v[146:149], v[178:181], v[102:105]
	v_mfma_f32_16x16x32_bf16 v[110:113], v[154:157], v[178:181], v[110:113]
	v_mfma_f32_16x16x32_bf16 v[90:93], v[146:149], v[186:189], v[90:93]
	v_mfma_f32_16x16x32_bf16 v[94:97], v[154:157], v[186:189], v[94:97]
	v_mfma_f32_16x16x32_bf16 v[74:77], v[146:149], v[194:197], v[74:77]
	v_mfma_f32_16x16x32_bf16 v[78:81], v[154:157], v[194:197], v[78:81]
	v_mfma_f32_16x16x32_bf16 v[50:53], v[146:149], v[202:205], v[50:53]
	v_mfma_f32_16x16x32_bf16 v[58:61], v[154:157], v[202:205], v[58:61]
	v_mfma_f32_16x16x32_bf16 v[102:105], v[150:153], v[182:185], v[102:105]
	v_mfma_f32_16x16x32_bf16 v[110:113], v[158:161], v[182:185], v[110:113]
	v_mfma_f32_16x16x32_bf16 v[90:93], v[150:153], v[190:193], v[90:93]
	v_mfma_f32_16x16x32_bf16 v[94:97], v[158:161], v[190:193], v[94:97]
	v_mfma_f32_16x16x32_bf16 v[74:77], v[150:153], v[198:201], v[74:77]
	v_mfma_f32_16x16x32_bf16 v[78:81], v[158:161], v[198:201], v[78:81]
	v_mfma_f32_16x16x32_bf16 v[50:53], v[150:153], v[206:209], v[50:53]
	v_mfma_f32_16x16x32_bf16 v[58:61], v[158:161], v[206:209], v[58:61]
	s_setprio 0
	s_setprio 1
	v_mfma_f32_16x16x32_bf16 v[122:125], v[162:165], v[178:181], v[122:125]
	v_mfma_f32_16x16x32_bf16 v[126:129], v[170:173], v[178:181], v[126:129]
	v_mfma_f32_16x16x32_bf16 v[114:117], v[162:165], v[186:189], v[114:117]
	v_mfma_f32_16x16x32_bf16 v[118:121], v[170:173], v[186:189], v[118:121]
	v_mfma_f32_16x16x32_bf16 v[98:101], v[162:165], v[194:197], v[98:101]
	v_mfma_f32_16x16x32_bf16 v[106:109], v[170:173], v[194:197], v[106:109]
	v_mfma_f32_16x16x32_bf16 v[82:85], v[162:165], v[202:205], v[82:85]
	v_mfma_f32_16x16x32_bf16 v[86:89], v[170:173], v[202:205], v[86:89]
	v_mfma_f32_16x16x32_bf16 v[122:125], v[166:169], v[182:185], v[122:125]
	v_mfma_f32_16x16x32_bf16 v[126:129], v[174:177], v[182:185], v[126:129]
	v_mfma_f32_16x16x32_bf16 v[114:117], v[166:169], v[190:193], v[114:117]
	v_mfma_f32_16x16x32_bf16 v[118:121], v[174:177], v[190:193], v[118:121]
	v_mfma_f32_16x16x32_bf16 v[98:101], v[166:169], v[198:201], v[98:101]
	v_mfma_f32_16x16x32_bf16 v[106:109], v[174:177], v[198:201], v[106:109]
	v_mfma_f32_16x16x32_bf16 v[82:85], v[166:169], v[206:209], v[82:85]
	v_mfma_f32_16x16x32_bf16 v[86:89], v[174:177], v[206:209], v[86:89]
	s_barrier
;     ...
;         for (int t = 2; t < nt; t += 2) PG8_KITER(t);
	s_setprio 0
	ds_read_b128 v[146:149], v134
	ds_read_b128 v[150:153], v134 offset:1024
	ds_read_b128 v[154:157], v134 offset:2048
	ds_read_b128 v[158:161], v134 offset:3072
	ds_read_b128 v[162:165], v144
	ds_read_b128 v[166:169], v144 offset:1024
	s_add_u32 s20, s80, 0x100000
	s_addc_u32 s21, s81, 0
	s_mov_b32 m0, s59
	ds_read_b128 v[174:177], v144 offset:3072
	global_load_lds_dwordx4 v132, s[100:101]
	s_mov_b32 m0, s82
	ds_read_b128 v[170:173], v144 offset:2048
	global_load_lds_dwordx4 v130, s[100:101]
	s_mov_b32 m0, s83
	ds_read_b128 v[178:181], v143 offset:32768
	ds_read_b128 v[182:185], v143 offset:33792
	ds_read_b128 v[186:189], v143 offset:34816
	ds_read_b128 v[190:193], v143 offset:35840
	ds_read_b128 v[194:197], v143 offset:36864
	ds_read_b128 v[198:201], v143 offset:37888
	ds_read_b128 v[202:205], v143 offset:38912
	global_load_lds_dwordx4 v132, s[20:21]
	s_mov_b32 m0, s86
	ds_read_b128 v[206:209], v143 offset:39936
	global_load_lds_dwordx4 v130, s[20:21]
	s_waitcnt vmcnt(8) lgkmcnt(0)
	s_setprio 1
	s_barrier
	v_mfma_f32_16x16x32_bf16 v[34:37], v[146:149], v[178:181], v[34:37]
	v_mfma_f32_16x16x32_bf16 v[38:41], v[154:157], v[178:181], v[38:41]
	v_mfma_f32_16x16x32_bf16 v[18:21], v[146:149], v[186:189], v[18:21]
	v_mfma_f32_16x16x32_bf16 v[22:25], v[154:157], v[186:189], v[22:25]
	v_mfma_f32_16x16x32_bf16 v[10:13], v[146:149], v[194:197], v[10:13]
	v_mfma_f32_16x16x32_bf16 v[14:17], v[154:157], v[194:197], v[14:17]
	v_mfma_f32_16x16x32_bf16 v[2:5], v[146:149], v[202:205], v[2:5]
	v_mfma_f32_16x16x32_bf16 v[6:9], v[154:157], v[202:205], v[6:9]
	v_mfma_f32_16x16x32_bf16 v[34:37], v[150:153], v[182:185], v[34:37]
	v_mfma_f32_16x16x32_bf16 v[38:41], v[158:161], v[182:185], v[38:41]
	v_mfma_f32_16x16x32_bf16 v[18:21], v[150:153], v[190:193], v[18:21]
	v_mfma_f32_16x16x32_bf16 v[22:25], v[158:161], v[190:193], v[22:25]
	v_mfma_f32_16x16x32_bf16 v[10:13], v[150:153], v[198:201], v[10:13]
	v_mfma_f32_16x16x32_bf16 v[14:17], v[158:161], v[198:201], v[14:17]
	v_mfma_f32_16x16x32_bf16 v[2:5], v[150:153], v[206:209], v[2:5]
	v_mfma_f32_16x16x32_bf16 v[6:9], v[158:161], v[206:209], v[6:9]
	s_setprio 0
	s_setprio 1
	v_mfma_f32_16x16x32_bf16 v[66:69], v[162:165], v[178:181], v[66:69]
	v_mfma_f32_16x16x32_bf16 v[70:73], v[170:173], v[178:181], v[70:73]
	v_mfma_f32_16x16x32_bf16 v[54:57], v[162:165], v[186:189], v[54:57]
	v_mfma_f32_16x16x32_bf16 v[62:65], v[170:173], v[186:189], v[62:65]
	v_mfma_f32_16x16x32_bf16 v[42:45], v[162:165], v[194:197], v[42:45]
	v_mfma_f32_16x16x32_bf16 v[46:49], v[170:173], v[194:197], v[46:49]
	v_mfma_f32_16x16x32_bf16 v[26:29], v[162:165], v[202:205], v[26:29]
	v_mfma_f32_16x16x32_bf16 v[30:33], v[170:173], v[202:205], v[30:33]
	v_mfma_f32_16x16x32_bf16 v[66:69], v[166:169], v[182:185], v[66:69]
	v_mfma_f32_16x16x32_bf16 v[70:73], v[174:177], v[182:185], v[70:73]
	v_mfma_f32_16x16x32_bf16 v[54:57], v[166:169], v[190:193], v[54:57]
	v_mfma_f32_16x16x32_bf16 v[62:65], v[174:177], v[190:193], v[62:65]
	v_mfma_f32_16x16x32_bf16 v[42:45], v[166:169], v[198:201], v[42:45]
	v_mfma_f32_16x16x32_bf16 v[46:49], v[174:177], v[198:201], v[46:49]
	v_mfma_f32_16x16x32_bf16 v[26:29], v[166:169], v[206:209], v[26:29]
	v_mfma_f32_16x16x32_bf16 v[30:33], v[174:177], v[206:209], v[30:33]
	s_barrier
	s_setprio 0
	s_mov_b32 m0, s47
	s_add_u32 s98, s98, 0x80
	s_addc_u32 s99, s99, 0
	s_add_u32 s100, s100, 0x80
	s_addc_u32 s101, s101, 0
	s_add_u32 s20, s76, 0x100080
	ds_read_b128 v[178:181], v143 offset:49152
	ds_read_b128 v[182:185], v143 offset:50176
	ds_read_b128 v[186:189], v143 offset:51200
	ds_read_b128 v[190:193], v143 offset:52224
	ds_read_b128 v[194:197], v143 offset:53248
	ds_read_b128 v[198:201], v143 offset:54272
	global_load_lds_dwordx4 v132, s[98:99]
	s_mov_b32 m0, vcc_hi
	s_addc_u32 s21, s77, 0
	global_load_lds_dwordx4 v130, s[98:99]
	s_mov_b32 m0, s56
	ds_read_b128 v[206:209], v143 offset:56320
	global_load_lds_dwordx4 v132, s[20:21]
	s_mov_b32 m0, s57
	ds_read_b128 v[202:205], v143 offset:55296
	global_load_lds_dwordx4 v130, s[20:21]
	s_waitcnt vmcnt(6) lgkmcnt(0)
	s_setprio 1
	s_barrier
	v_mfma_f32_16x16x32_bf16 v[102:105], v[146:149], v[178:181], v[102:105]
	v_mfma_f32_16x16x32_bf16 v[110:113], v[154:157], v[178:181], v[110:113]
	v_mfma_f32_16x16x32_bf16 v[90:93], v[146:149], v[186:189], v[90:93]
	v_mfma_f32_16x16x32_bf16 v[94:97], v[154:157], v[186:189], v[94:97]
	v_mfma_f32_16x16x32_bf16 v[74:77], v[146:149], v[194:197], v[74:77]
	v_mfma_f32_16x16x32_bf16 v[78:81], v[154:157], v[194:197], v[78:81]
	v_mfma_f32_16x16x32_bf16 v[50:53], v[146:149], v[202:205], v[50:53]
	v_mfma_f32_16x16x32_bf16 v[58:61], v[154:157], v[202:205], v[58:61]
	v_mfma_f32_16x16x32_bf16 v[102:105], v[150:153], v[182:185], v[102:105]
	v_mfma_f32_16x16x32_bf16 v[110:113], v[158:161], v[182:185], v[110:113]
	v_mfma_f32_16x16x32_bf16 v[90:93], v[150:153], v[190:193], v[90:93]
	v_mfma_f32_16x16x32_bf16 v[94:97], v[158:161], v[190:193], v[94:97]
	v_mfma_f32_16x16x32_bf16 v[74:77], v[150:153], v[198:201], v[74:77]
	v_mfma_f32_16x16x32_bf16 v[78:81], v[158:161], v[198:201], v[78:81]
	v_mfma_f32_16x16x32_bf16 v[50:53], v[150:153], v[206:209], v[50:53]
	v_mfma_f32_16x16x32_bf16 v[58:61], v[158:161], v[206:209], v[58:61]
	s_setprio 0
	s_setprio 1
	v_mfma_f32_16x16x32_bf16 v[122:125], v[162:165], v[178:181], v[122:125]
	v_mfma_f32_16x16x32_bf16 v[126:129], v[170:173], v[178:181], v[126:129]
	v_mfma_f32_16x16x32_bf16 v[114:117], v[162:165], v[186:189], v[114:117]
	v_mfma_f32_16x16x32_bf16 v[118:121], v[170:173], v[186:189], v[118:121]
	v_mfma_f32_16x16x32_bf16 v[98:101], v[162:165], v[194:197], v[98:101]
	v_mfma_f32_16x16x32_bf16 v[106:109], v[170:173], v[194:197], v[106:109]
	v_mfma_f32_16x16x32_bf16 v[82:85], v[162:165], v[202:205], v[82:85]
	v_mfma_f32_16x16x32_bf16 v[86:89], v[170:173], v[202:205], v[86:89]
	v_mfma_f32_16x16x32_bf16 v[122:125], v[166:169], v[182:185], v[122:125]
	v_mfma_f32_16x16x32_bf16 v[126:129], v[174:177], v[182:185], v[126:129]
	v_mfma_f32_16x16x32_bf16 v[114:117], v[166:169], v[190:193], v[114:117]
	v_mfma_f32_16x16x32_bf16 v[118:121], v[174:177], v[190:193], v[118:121]
	v_mfma_f32_16x16x32_bf16 v[98:101], v[166:169], v[198:201], v[98:101]
	v_mfma_f32_16x16x32_bf16 v[106:109], v[174:177], v[198:201], v[106:109]
	v_mfma_f32_16x16x32_bf16 v[82:85], v[166:169], v[206:209], v[82:85]
	v_mfma_f32_16x16x32_bf16 v[86:89], v[174:177], v[206:209], v[86:89]
	s_barrier
	s_setprio 0
	s_add_i32 s16, s16, 2
	s_add_u32 s78, s78, 0x100
	s_addc_u32 s79, s79, 0
	s_add_u32 s14, s14, 0x100
	s_addc_u32 s15, s15, 0
	s_cmp_gt_u32 s16, 61
	s_cbranch_scc0 .LBB0_435
	s_mov_b32 m0, s88
	s_nop 0
	global_load_lds_dwordx4 v132, s[100:101]
	s_mov_b32 m0, s89
	s_nop 0
	global_load_lds_dwordx4 v130, s[100:101]
	s_and_b64 vcc, exec, s[30:31]
	s_cbranch_vccz .LBB0_438
	s_barrier

.Lrb2_skip_18937:
	s_mov_b32 m0, s69
	ds_read_b128 v[182:185], v151
	ds_read_b128 v[186:189], v151 offset:1024
	ds_read_b128 v[190:193], v151 offset:2048
	ds_read_b128 v[194:197], v151 offset:3072
	ds_read_b128 v[198:201], v151 offset:4096
	ds_read_b128 v[202:205], v151 offset:5120
	ds_read_b128 v[206:209], v151 offset:6144
	global_load_lds_dwordx4 v138, s[62:63]
	s_mov_b32 m0, s70
	ds_read_b128 v[210:213], v151 offset:7168
	global_load_lds_dwordx4 v140, s[62:63]
	s_waitcnt vmcnt(8) lgkmcnt(0)
	s_setprio 1
	s_barrier
	v_mfma_f32_16x16x32_bf16 v[122:125], v[146:149], v[182:185], v[122:125]
	v_mfma_f32_16x16x32_bf16 v[114:117], v[158:161], v[182:185], v[114:117]
	v_mfma_f32_16x16x32_bf16 v[106:109], v[146:149], v[190:193], v[106:109]
	v_mfma_f32_16x16x32_bf16 v[98:101], v[158:161], v[190:193], v[98:101]
	v_mfma_f32_16x16x32_bf16 v[90:93], v[146:149], v[198:201], v[90:93]
	v_mfma_f32_16x16x32_bf16 v[82:85], v[158:161], v[198:201], v[82:85]
	v_mfma_f32_16x16x32_bf16 v[58:61], v[146:149], v[206:209], v[58:61]
	v_mfma_f32_16x16x32_bf16 v[50:53], v[158:161], v[206:209], v[50:53]
	v_mfma_f32_16x16x32_bf16 v[122:125], v[154:157], v[186:189], v[122:125]
	v_mfma_f32_16x16x32_bf16 v[114:117], v[162:165], v[186:189], v[114:117]
	v_mfma_f32_16x16x32_bf16 v[106:109], v[154:157], v[194:197], v[106:109]
	v_mfma_f32_16x16x32_bf16 v[98:101], v[162:165], v[194:197], v[98:101]
	v_mfma_f32_16x16x32_bf16 v[90:93], v[154:157], v[202:205], v[90:93]
	v_mfma_f32_16x16x32_bf16 v[82:85], v[162:165], v[202:205], v[82:85]
	v_mfma_f32_16x16x32_bf16 v[58:61], v[154:157], v[210:213], v[58:61]
	v_mfma_f32_16x16x32_bf16 v[50:53], v[162:165], v[210:213], v[50:53]
	s_setprio 0
	s_setprio 1
	v_mfma_f32_16x16x32_bf16 v[126:129], v[166:169], v[182:185], v[126:129]
	v_mfma_f32_16x16x32_bf16 v[118:121], v[174:177], v[182:185], v[118:121]
	v_mfma_f32_16x16x32_bf16 v[110:113], v[166:169], v[190:193], v[110:113]
	v_mfma_f32_16x16x32_bf16 v[102:105], v[174:177], v[190:193], v[102:105]
	v_mfma_f32_16x16x32_bf16 v[94:97], v[166:169], v[198:201], v[94:97]
	v_mfma_f32_16x16x32_bf16 v[86:89], v[174:177], v[198:201], v[86:89]
	v_mfma_f32_16x16x32_bf16 v[62:65], v[166:169], v[206:209], v[62:65]
	v_mfma_f32_16x16x32_bf16 v[54:57], v[174:177], v[206:209], v[54:57]
	v_mfma_f32_16x16x32_bf16 v[126:129], v[170:173], v[186:189], v[126:129]
	v_mfma_f32_16x16x32_bf16 v[118:121], v[178:181], v[186:189], v[118:121]
	v_mfma_f32_16x16x32_bf16 v[110:113], v[170:173], v[194:197], v[110:113]
	v_mfma_f32_16x16x32_bf16 v[102:105], v[178:181], v[194:197], v[102:105]
	v_mfma_f32_16x16x32_bf16 v[94:97], v[170:173], v[202:205], v[94:97]
	v_mfma_f32_16x16x32_bf16 v[86:89], v[178:181], v[202:205], v[86:89]
	v_mfma_f32_16x16x32_bf16 v[62:65], v[170:173], v[210:213], v[62:65]
	v_mfma_f32_16x16x32_bf16 v[54:57], v[178:181], v[210:213], v[54:57]
	s_barrier
	s_setprio 0
	s_mov_b32 m0, s72
	s_mov_b64 s[98:99], s[54:55]
	s_add_u32 s46, s54, 0x40000
	ds_read_b128 v[182:185], v151 offset:16384
	ds_read_b128 v[186:189], v151 offset:17408
	ds_read_b128 v[190:193], v151 offset:18432
	ds_read_b128 v[194:197], v151 offset:19456
	ds_read_b128 v[198:201], v151 offset:20480
	ds_read_b128 v[202:205], v151 offset:21504
	ds_read_b128 v[206:209], v151 offset:22528
	global_load_lds_dwordx4 v134, s[54:55]
	s_mov_b32 m0, s73
	s_addc_u32 s47, s55, 0
	global_load_lds_dwordx4 v130, s[54:55]
	s_mov_b32 m0, s74
	s_mov_b64 s[100:101], s[64:65]
	global_load_lds_dwordx4 v134, s[46:47]
	s_mov_b32 m0, s75
	ds_read_b128 v[210:213], v151 offset:23552
	global_load_lds_dwordx4 v130, s[46:47]
	s_waitcnt vmcnt(6) lgkmcnt(0)
	s_setprio 1
	s_barrier
	v_mfma_f32_16x16x32_bf16 v[74:77], v[146:149], v[182:185], v[74:77]
	v_mfma_f32_16x16x32_bf16 v[66:69], v[158:161], v[182:185], v[66:69]
	v_mfma_f32_16x16x32_bf16 v[42:45], v[146:149], v[190:193], v[42:45]
	v_mfma_f32_16x16x32_bf16 v[34:37], v[158:161], v[190:193], v[34:37]
	v_mfma_f32_16x16x32_bf16 v[26:29], v[146:149], v[198:201], v[26:29]
	v_mfma_f32_16x16x32_bf16 v[18:21], v[158:161], v[198:201], v[18:21]
	v_mfma_f32_16x16x32_bf16 v[10:13], v[146:149], v[206:209], v[10:13]
	v_mfma_f32_16x16x32_bf16 v[2:5], v[158:161], v[206:209], v[2:5]
	v_mfma_f32_16x16x32_bf16 v[74:77], v[154:157], v[186:189], v[74:77]
	v_mfma_f32_16x16x32_bf16 v[66:69], v[162:165], v[186:189], v[66:69]
	v_mfma_f32_16x16x32_bf16 v[42:45], v[154:157], v[194:197], v[42:45]
	v_mfma_f32_16x16x32_bf16 v[34:37], v[162:165], v[194:197], v[34:37]
	v_mfma_f32_16x16x32_bf16 v[26:29], v[154:157], v[202:205], v[26:29]
	v_mfma_f32_16x16x32_bf16 v[18:21], v[162:165], v[202:205], v[18:21]
	v_mfma_f32_16x16x32_bf16 v[10:13], v[154:157], v[210:213], v[10:13]
	v_mfma_f32_16x16x32_bf16 v[2:5], v[162:165], v[210:213], v[2:5]
	s_setprio 0
	s_setprio 1
	v_mfma_f32_16x16x32_bf16 v[78:81], v[166:169], v[182:185], v[78:81]
	v_mfma_f32_16x16x32_bf16 v[70:73], v[174:177], v[182:185], v[70:73]
	v_mfma_f32_16x16x32_bf16 v[46:49], v[166:169], v[190:193], v[46:49]
	v_mfma_f32_16x16x32_bf16 v[38:41], v[174:177], v[190:193], v[38:41]
	v_mfma_f32_16x16x32_bf16 v[30:33], v[166:169], v[198:201], v[30:33]
	v_mfma_f32_16x16x32_bf16 v[22:25], v[174:177], v[198:201], v[22:25]
	v_mfma_f32_16x16x32_bf16 v[14:17], v[166:169], v[206:209], v[14:17]
	v_mfma_f32_16x16x32_bf16 v[6:9], v[174:177], v[206:209], v[6:9]
	v_mfma_f32_16x16x32_bf16 v[78:81], v[170:173], v[186:189], v[78:81]
	v_mfma_f32_16x16x32_bf16 v[70:73], v[178:181], v[186:189], v[70:73]
	v_mfma_f32_16x16x32_bf16 v[46:49], v[170:173], v[194:197], v[46:49]
	v_mfma_f32_16x16x32_bf16 v[38:41], v[178:181], v[194:197], v[38:41]
	v_mfma_f32_16x16x32_bf16 v[30:33], v[170:173], v[202:205], v[30:33]
	v_mfma_f32_16x16x32_bf16 v[22:25], v[178:181], v[202:205], v[22:25]
	v_mfma_f32_16x16x32_bf16 v[14:17], v[170:173], v[210:213], v[14:17]
	v_mfma_f32_16x16x32_bf16 v[6:9], v[178:181], v[210:213], v[6:9]
	s_barrier
;     ...
;         for (int t = 2; t < nt; t += 2) PG8_KITER(t);
	s_setprio 0
	ds_read_b128 v[146:149], v152
	ds_read_b128 v[154:157], v152 offset:1024
	ds_read_b128 v[158:161], v152 offset:2048
	ds_read_b128 v[162:165], v152 offset:3072
	ds_read_b128 v[166:169], v153
	ds_read_b128 v[170:173], v153 offset:1024
	s_add_u32 s46, s64, 0x40000
	s_addc_u32 s47, s65, 0
	s_mov_b32 m0, s33
	ds_read_b128 v[178:181], v153 offset:3072
	global_load_lds_dwordx4 v136, s[100:101]
	s_mov_b32 m0, s41
	ds_read_b128 v[174:177], v153 offset:2048
	global_load_lds_dwordx4 v132, s[100:101]
	s_mov_b32 m0, s58
	ds_read_b128 v[182:185], v151 offset:32768
	ds_read_b128 v[186:189], v151 offset:33792
	ds_read_b128 v[190:193], v151 offset:34816
	ds_read_b128 v[194:197], v151 offset:35840
	ds_read_b128 v[198:201], v151 offset:36864
	ds_read_b128 v[202:205], v151 offset:37888
	ds_read_b128 v[206:209], v151 offset:38912
	global_load_lds_dwordx4 v136, s[46:47]
	s_mov_b32 m0, s59
	ds_read_b128 v[210:213], v151 offset:39936
	global_load_lds_dwordx4 v132, s[46:47]
	s_waitcnt vmcnt(8) lgkmcnt(0)
	s_setprio 1
	s_barrier
	v_mfma_f32_16x16x32_bf16 v[122:125], v[146:149], v[182:185], v[122:125]
	v_mfma_f32_16x16x32_bf16 v[114:117], v[158:161], v[182:185], v[114:117]
	v_mfma_f32_16x16x32_bf16 v[106:109], v[146:149], v[190:193], v[106:109]
	v_mfma_f32_16x16x32_bf16 v[98:101], v[158:161], v[190:193], v[98:101]
	v_mfma_f32_16x16x32_bf16 v[90:93], v[146:149], v[198:201], v[90:93]
	v_mfma_f32_16x16x32_bf16 v[82:85], v[158:161], v[198:201], v[82:85]
	v_mfma_f32_16x16x32_bf16 v[58:61], v[146:149], v[206:209], v[58:61]
	v_mfma_f32_16x16x32_bf16 v[50:53], v[158:161], v[206:209], v[50:53]
	v_mfma_f32_16x16x32_bf16 v[122:125], v[154:157], v[186:189], v[122:125]
	v_mfma_f32_16x16x32_bf16 v[114:117], v[162:165], v[186:189], v[114:117]
	v_mfma_f32_16x16x32_bf16 v[106:109], v[154:157], v[194:197], v[106:109]
	v_mfma_f32_16x16x32_bf16 v[98:101], v[162:165], v[194:197], v[98:101]
	v_mfma_f32_16x16x32_bf16 v[90:93], v[154:157], v[202:205], v[90:93]
	v_mfma_f32_16x16x32_bf16 v[82:85], v[162:165], v[202:205], v[82:85]
	v_mfma_f32_16x16x32_bf16 v[58:61], v[154:157], v[210:213], v[58:61]
	v_mfma_f32_16x16x32_bf16 v[50:53], v[162:165], v[210:213], v[50:53]
	s_setprio 0
	s_setprio 1
	v_mfma_f32_16x16x32_bf16 v[126:129], v[166:169], v[182:185], v[126:129]
	v_mfma_f32_16x16x32_bf16 v[118:121], v[174:177], v[182:185], v[118:121]
	v_mfma_f32_16x16x32_bf16 v[110:113], v[166:169], v[190:193], v[110:113]
	v_mfma_f32_16x16x32_bf16 v[102:105], v[174:177], v[190:193], v[102:105]
	v_mfma_f32_16x16x32_bf16 v[94:97], v[166:169], v[198:201], v[94:97]
	v_mfma_f32_16x16x32_bf16 v[86:89], v[174:177], v[198:201], v[86:89]
	v_mfma_f32_16x16x32_bf16 v[62:65], v[166:169], v[206:209], v[62:65]
	v_mfma_f32_16x16x32_bf16 v[54:57], v[174:177], v[206:209], v[54:57]
	v_mfma_f32_16x16x32_bf16 v[126:129], v[170:173], v[186:189], v[126:129]
	v_mfma_f32_16x16x32_bf16 v[118:121], v[178:181], v[186:189], v[118:121]
	v_mfma_f32_16x16x32_bf16 v[110:113], v[170:173], v[194:197], v[110:113]
	v_mfma_f32_16x16x32_bf16 v[102:105], v[178:181], v[194:197], v[102:105]
	v_mfma_f32_16x16x32_bf16 v[94:97], v[170:173], v[202:205], v[94:97]
	v_mfma_f32_16x16x32_bf16 v[86:89], v[178:181], v[202:205], v[86:89]
	v_mfma_f32_16x16x32_bf16 v[62:65], v[170:173], v[210:213], v[62:65]
	v_mfma_f32_16x16x32_bf16 v[54:57], v[178:181], v[210:213], v[54:57]
	s_barrier
	s_setprio 0
	s_mov_b32 m0, s76
	s_add_u32 s98, s98, 0x80
	s_addc_u32 s99, s99, 0
	s_add_u32 s100, s100, 0x80
	s_addc_u32 s101, s101, 0
	s_add_u32 s46, s54, 0x40080
	ds_read_b128 v[182:185], v151 offset:49152
	ds_read_b128 v[186:189], v151 offset:50176
	ds_read_b128 v[190:193], v151 offset:51200
	ds_read_b128 v[194:197], v151 offset:52224
	ds_read_b128 v[198:201], v151 offset:53248
	ds_read_b128 v[202:205], v151 offset:54272
	global_load_lds_dwordx4 v134, s[98:99]
	s_mov_b32 m0, s77
	s_addc_u32 s47, s55, 0
	global_load_lds_dwordx4 v130, s[98:99]
	s_mov_b32 m0, s78
	ds_read_b128 v[210:213], v151 offset:56320
	global_load_lds_dwordx4 v134, s[46:47]
	s_mov_b32 m0, s79
	ds_read_b128 v[206:209], v151 offset:55296
	global_load_lds_dwordx4 v130, s[46:47]
	s_waitcnt vmcnt(6) lgkmcnt(0)
	s_setprio 1
	s_barrier
	v_mfma_f32_16x16x32_bf16 v[74:77], v[146:149], v[182:185], v[74:77]
	v_mfma_f32_16x16x32_bf16 v[66:69], v[158:161], v[182:185], v[66:69]
	v_mfma_f32_16x16x32_bf16 v[42:45], v[146:149], v[190:193], v[42:45]
	v_mfma_f32_16x16x32_bf16 v[34:37], v[158:161], v[190:193], v[34:37]
	v_mfma_f32_16x16x32_bf16 v[26:29], v[146:149], v[198:201], v[26:29]
	v_mfma_f32_16x16x32_bf16 v[18:21], v[158:161], v[198:201], v[18:21]
	v_mfma_f32_16x16x32_bf16 v[10:13], v[146:149], v[206:209], v[10:13]
	v_mfma_f32_16x16x32_bf16 v[2:5], v[158:161], v[206:209], v[2:5]
	v_mfma_f32_16x16x32_bf16 v[74:77], v[154:157], v[186:189], v[74:77]
	v_mfma_f32_16x16x32_bf16 v[66:69], v[162:165], v[186:189], v[66:69]
	v_mfma_f32_16x16x32_bf16 v[42:45], v[154:157], v[194:197], v[42:45]
	v_mfma_f32_16x16x32_bf16 v[34:37], v[162:165], v[194:197], v[34:37]
	v_mfma_f32_16x16x32_bf16 v[26:29], v[154:157], v[202:205], v[26:29]
	v_mfma_f32_16x16x32_bf16 v[18:21], v[162:165], v[202:205], v[18:21]
	v_mfma_f32_16x16x32_bf16 v[10:13], v[154:157], v[210:213], v[10:13]
	v_mfma_f32_16x16x32_bf16 v[2:5], v[162:165], v[210:213], v[2:5]
	s_setprio 0
	s_setprio 1
	v_mfma_f32_16x16x32_bf16 v[78:81], v[166:169], v[182:185], v[78:81]
	v_mfma_f32_16x16x32_bf16 v[70:73], v[174:177], v[182:185], v[70:73]
	v_mfma_f32_16x16x32_bf16 v[46:49], v[166:169], v[190:193], v[46:49]
	v_mfma_f32_16x16x32_bf16 v[38:41], v[174:177], v[190:193], v[38:41]
	v_mfma_f32_16x16x32_bf16 v[30:33], v[166:169], v[198:201], v[30:33]
	v_mfma_f32_16x16x32_bf16 v[22:25], v[174:177], v[198:201], v[22:25]
	v_mfma_f32_16x16x32_bf16 v[14:17], v[166:169], v[206:209], v[14:17]
	v_mfma_f32_16x16x32_bf16 v[6:9], v[174:177], v[206:209], v[6:9]
	v_mfma_f32_16x16x32_bf16 v[78:81], v[170:173], v[186:189], v[78:81]
	v_mfma_f32_16x16x32_bf16 v[70:73], v[178:181], v[186:189], v[70:73]
	v_mfma_f32_16x16x32_bf16 v[46:49], v[170:173], v[194:197], v[46:49]
	v_mfma_f32_16x16x32_bf16 v[38:41], v[178:181], v[194:197], v[38:41]
	v_mfma_f32_16x16x32_bf16 v[30:33], v[170:173], v[202:205], v[30:33]
	v_mfma_f32_16x16x32_bf16 v[22:25], v[178:181], v[202:205], v[22:25]
	v_mfma_f32_16x16x32_bf16 v[14:17], v[170:173], v[210:213], v[14:17]
	v_mfma_f32_16x16x32_bf16 v[6:9], v[178:181], v[210:213], v[6:9]
	s_barrier
	s_setprio 0
	s_add_i32 s26, s26, 2
	s_add_u32 s62, s62, 0x100
	s_addc_u32 s63, s63, 0
	s_add_u32 s14, s14, 0x100
	s_addc_u32 s15, s15, 0
	s_cmp_gt_u32 s26, 13
	s_cbranch_scc0 .LBB0_644
	s_mov_b32 m0, s66
	s_nop 0
	global_load_lds_dwordx4 v136, s[100:101]
	s_mov_b32 m0, s67
	s_nop 0
	global_load_lds_dwordx4 v132, s[100:101]
	s_and_b64 vcc, exec, s[16:17]
	s_cbranch_vccz .LBB0_647
	s_barrier

.Lrb2_skip_20202:
	s_mov_b32 m0, s81
	ds_read_b128 v[186:189], v160
	ds_read_b128 v[190:193], v160 offset:1024
	ds_read_b128 v[194:197], v160 offset:2048
	ds_read_b128 v[198:201], v160 offset:3072
	ds_read_b128 v[202:205], v160 offset:4096
	ds_read_b128 v[206:209], v160 offset:5120
	ds_read_b128 v[210:213], v160 offset:6144
	global_load_lds_dwordx4 v146, s[64:65]
	s_mov_b32 m0, s82
	ds_read_b128 v[214:217], v160 offset:7168
	global_load_lds_dwordx4 v148, s[64:65]
	s_waitcnt vmcnt(8) lgkmcnt(0)
	s_setprio 1
	s_barrier
	v_mfma_f32_16x16x32_bf16 v[118:121], v[132:135], v[186:189], v[118:121]
	v_mfma_f32_16x16x32_bf16 v[114:117], v[162:165], v[186:189], v[114:117]
	v_mfma_f32_16x16x32_bf16 v[110:113], v[132:135], v[194:197], v[110:113]
	v_mfma_f32_16x16x32_bf16 v[98:101], v[162:165], v[194:197], v[98:101]
	v_mfma_f32_16x16x32_bf16 v[94:97], v[132:135], v[202:205], v[94:97]
	v_mfma_f32_16x16x32_bf16 v[90:93], v[162:165], v[202:205], v[90:93]
	v_mfma_f32_16x16x32_bf16 v[78:81], v[132:135], v[210:213], v[78:81]
	v_mfma_f32_16x16x32_bf16 v[70:73], v[162:165], v[210:213], v[70:73]
	v_mfma_f32_16x16x32_bf16 v[118:121], v[154:157], v[190:193], v[118:121]
	v_mfma_f32_16x16x32_bf16 v[114:117], v[166:169], v[190:193], v[114:117]
	v_mfma_f32_16x16x32_bf16 v[110:113], v[154:157], v[198:201], v[110:113]
	v_mfma_f32_16x16x32_bf16 v[98:101], v[166:169], v[198:201], v[98:101]
	v_mfma_f32_16x16x32_bf16 v[94:97], v[154:157], v[206:209], v[94:97]
	v_mfma_f32_16x16x32_bf16 v[90:93], v[166:169], v[206:209], v[90:93]
	v_mfma_f32_16x16x32_bf16 v[78:81], v[154:157], v[214:217], v[78:81]
	v_mfma_f32_16x16x32_bf16 v[70:73], v[166:169], v[214:217], v[70:73]
	s_setprio 0
	s_setprio 1
	v_mfma_f32_16x16x32_bf16 v[126:129], v[170:173], v[186:189], v[126:129]
	v_mfma_f32_16x16x32_bf16 v[122:125], v[178:181], v[186:189], v[122:125]
	v_mfma_f32_16x16x32_bf16 v[106:109], v[170:173], v[194:197], v[106:109]
	v_mfma_f32_16x16x32_bf16 v[102:105], v[178:181], v[194:197], v[102:105]
	v_mfma_f32_16x16x32_bf16 v[86:89], v[170:173], v[202:205], v[86:89]
	v_mfma_f32_16x16x32_bf16 v[82:85], v[178:181], v[202:205], v[82:85]
	v_mfma_f32_16x16x32_bf16 v[62:65], v[170:173], v[210:213], v[62:65]
	v_mfma_f32_16x16x32_bf16 v[58:61], v[178:181], v[210:213], v[58:61]
	v_mfma_f32_16x16x32_bf16 v[126:129], v[174:177], v[190:193], v[126:129]
	v_mfma_f32_16x16x32_bf16 v[122:125], v[182:185], v[190:193], v[122:125]
	v_mfma_f32_16x16x32_bf16 v[106:109], v[174:177], v[198:201], v[106:109]
	v_mfma_f32_16x16x32_bf16 v[102:105], v[182:185], v[198:201], v[102:105]
	v_mfma_f32_16x16x32_bf16 v[86:89], v[174:177], v[206:209], v[86:89]
	v_mfma_f32_16x16x32_bf16 v[82:85], v[182:185], v[206:209], v[82:85]
	v_mfma_f32_16x16x32_bf16 v[62:65], v[174:177], v[214:217], v[62:65]
	v_mfma_f32_16x16x32_bf16 v[58:61], v[182:185], v[214:217], v[58:61]
	s_barrier
	s_setprio 0
	s_mov_b32 m0, s83
	s_mov_b64 s[98:99], s[6:7]
	s_add_u32 s88, s6, 0x20000
	ds_read_b128 v[186:189], v160 offset:16384
	ds_read_b128 v[190:193], v160 offset:17408
	ds_read_b128 v[194:197], v160 offset:18432
	ds_read_b128 v[198:201], v160 offset:19456
	ds_read_b128 v[202:205], v160 offset:20480
	ds_read_b128 v[206:209], v160 offset:21504
	ds_read_b128 v[210:213], v160 offset:22528
	global_load_lds_dwordx4 v140, s[6:7]
	s_mov_b32 m0, s84
	s_addc_u32 s89, s7, 0
	global_load_lds_dwordx4 v144, s[6:7]
	s_mov_b32 m0, s85
	s_mov_b64 s[100:101], s[66:67]
	global_load_lds_dwordx4 v140, s[88:89]
	s_mov_b32 m0, s46
	ds_read_b128 v[214:217], v160 offset:23552
	global_load_lds_dwordx4 v144, s[88:89]
	s_waitcnt vmcnt(6) lgkmcnt(0)
	s_setprio 1
	s_barrier
	v_mfma_f32_16x16x32_bf16 v[74:77], v[132:135], v[186:189], v[74:77]
	v_mfma_f32_16x16x32_bf16 v[66:69], v[162:165], v[186:189], v[66:69]
	v_mfma_f32_16x16x32_bf16 v[46:49], v[132:135], v[194:197], v[46:49]
	v_mfma_f32_16x16x32_bf16 v[42:45], v[162:165], v[194:197], v[42:45]
	v_mfma_f32_16x16x32_bf16 v[30:33], v[132:135], v[202:205], v[30:33]
	v_mfma_f32_16x16x32_bf16 v[26:29], v[162:165], v[202:205], v[26:29]
	v_mfma_f32_16x16x32_bf16 v[14:17], v[132:135], v[210:213], v[14:17]
	v_mfma_f32_16x16x32_bf16 v[10:13], v[162:165], v[210:213], v[10:13]
	v_mfma_f32_16x16x32_bf16 v[74:77], v[154:157], v[190:193], v[74:77]
	v_mfma_f32_16x16x32_bf16 v[66:69], v[166:169], v[190:193], v[66:69]
	v_mfma_f32_16x16x32_bf16 v[46:49], v[154:157], v[198:201], v[46:49]
	v_mfma_f32_16x16x32_bf16 v[42:45], v[166:169], v[198:201], v[42:45]
	v_mfma_f32_16x16x32_bf16 v[30:33], v[154:157], v[206:209], v[30:33]
	v_mfma_f32_16x16x32_bf16 v[26:29], v[166:169], v[206:209], v[26:29]
	v_mfma_f32_16x16x32_bf16 v[14:17], v[154:157], v[214:217], v[14:17]
	v_mfma_f32_16x16x32_bf16 v[10:13], v[166:169], v[214:217], v[10:13]
	s_setprio 0
	s_setprio 1
	v_mfma_f32_16x16x32_bf16 v[54:57], v[170:173], v[186:189], v[54:57]
	v_mfma_f32_16x16x32_bf16 v[50:53], v[178:181], v[186:189], v[50:53]
	v_mfma_f32_16x16x32_bf16 v[38:41], v[170:173], v[194:197], v[38:41]
	v_mfma_f32_16x16x32_bf16 v[34:37], v[178:181], v[194:197], v[34:37]
	v_mfma_f32_16x16x32_bf16 v[22:25], v[170:173], v[202:205], v[22:25]
	v_mfma_f32_16x16x32_bf16 v[18:21], v[178:181], v[202:205], v[18:21]
	v_mfma_f32_16x16x32_bf16 v[6:9], v[170:173], v[210:213], v[6:9]
	v_mfma_f32_16x16x32_bf16 v[2:5], v[178:181], v[210:213], v[2:5]
	v_mfma_f32_16x16x32_bf16 v[54:57], v[174:177], v[190:193], v[54:57]
	v_mfma_f32_16x16x32_bf16 v[50:53], v[182:185], v[190:193], v[50:53]
	v_mfma_f32_16x16x32_bf16 v[38:41], v[174:177], v[198:201], v[38:41]
	v_mfma_f32_16x16x32_bf16 v[34:37], v[182:185], v[198:201], v[34:37]
	v_mfma_f32_16x16x32_bf16 v[22:25], v[174:177], v[206:209], v[22:25]
	v_mfma_f32_16x16x32_bf16 v[18:21], v[182:185], v[206:209], v[18:21]
	v_mfma_f32_16x16x32_bf16 v[6:9], v[174:177], v[214:217], v[6:9]
	v_mfma_f32_16x16x32_bf16 v[2:5], v[182:185], v[214:217], v[2:5]
	s_barrier
;     ...
;         for (int t = 2; t < nt; t += 2) PG8_KITER(t);
	s_setprio 0
	ds_read_b128 v[132:135], v130
	ds_read_b128 v[154:157], v130 offset:1024
	ds_read_b128 v[162:165], v130 offset:2048
	ds_read_b128 v[166:169], v130 offset:3072
	ds_read_b128 v[170:173], v131
	ds_read_b128 v[174:177], v131 offset:1024
	s_add_u32 s66, s66, 0x20000
	s_addc_u32 s67, s67, 0
	s_mov_b32 m0, s58
	ds_read_b128 v[182:185], v131 offset:3072
	global_load_lds_dwordx4 v138, s[100:101]
	s_mov_b32 m0, s59
	ds_read_b128 v[178:181], v131 offset:2048
	global_load_lds_dwordx4 v142, s[100:101]
	s_mov_b32 m0, s63
	ds_read_b128 v[186:189], v160 offset:32768
	ds_read_b128 v[190:193], v160 offset:33792
	ds_read_b128 v[194:197], v160 offset:34816
	ds_read_b128 v[198:201], v160 offset:35840
	ds_read_b128 v[202:205], v160 offset:36864
	ds_read_b128 v[206:209], v160 offset:37888
	ds_read_b128 v[210:213], v160 offset:38912
	global_load_lds_dwordx4 v138, s[66:67]
	s_mov_b32 m0, s68
	ds_read_b128 v[214:217], v160 offset:39936
	global_load_lds_dwordx4 v142, s[66:67]
	s_waitcnt vmcnt(8) lgkmcnt(0)
	s_setprio 1
	s_barrier
	v_mfma_f32_16x16x32_bf16 v[118:121], v[132:135], v[186:189], v[118:121]
	v_mfma_f32_16x16x32_bf16 v[114:117], v[162:165], v[186:189], v[114:117]
	v_mfma_f32_16x16x32_bf16 v[110:113], v[132:135], v[194:197], v[110:113]
	v_mfma_f32_16x16x32_bf16 v[98:101], v[162:165], v[194:197], v[98:101]
	v_mfma_f32_16x16x32_bf16 v[94:97], v[132:135], v[202:205], v[94:97]
	v_mfma_f32_16x16x32_bf16 v[90:93], v[162:165], v[202:205], v[90:93]
	v_mfma_f32_16x16x32_bf16 v[78:81], v[132:135], v[210:213], v[78:81]
	v_mfma_f32_16x16x32_bf16 v[70:73], v[162:165], v[210:213], v[70:73]
	v_mfma_f32_16x16x32_bf16 v[118:121], v[154:157], v[190:193], v[118:121]
	v_mfma_f32_16x16x32_bf16 v[114:117], v[166:169], v[190:193], v[114:117]
	v_mfma_f32_16x16x32_bf16 v[110:113], v[154:157], v[198:201], v[110:113]
	v_mfma_f32_16x16x32_bf16 v[98:101], v[166:169], v[198:201], v[98:101]
	v_mfma_f32_16x16x32_bf16 v[94:97], v[154:157], v[206:209], v[94:97]
	v_mfma_f32_16x16x32_bf16 v[90:93], v[166:169], v[206:209], v[90:93]
	v_mfma_f32_16x16x32_bf16 v[78:81], v[154:157], v[214:217], v[78:81]
	v_mfma_f32_16x16x32_bf16 v[70:73], v[166:169], v[214:217], v[70:73]
	s_setprio 0
	s_setprio 1
	v_mfma_f32_16x16x32_bf16 v[126:129], v[170:173], v[186:189], v[126:129]
	v_mfma_f32_16x16x32_bf16 v[122:125], v[178:181], v[186:189], v[122:125]
	v_mfma_f32_16x16x32_bf16 v[106:109], v[170:173], v[194:197], v[106:109]
	v_mfma_f32_16x16x32_bf16 v[102:105], v[178:181], v[194:197], v[102:105]
	v_mfma_f32_16x16x32_bf16 v[86:89], v[170:173], v[202:205], v[86:89]
	v_mfma_f32_16x16x32_bf16 v[82:85], v[178:181], v[202:205], v[82:85]
	v_mfma_f32_16x16x32_bf16 v[62:65], v[170:173], v[210:213], v[62:65]
	v_mfma_f32_16x16x32_bf16 v[58:61], v[178:181], v[210:213], v[58:61]
	v_mfma_f32_16x16x32_bf16 v[126:129], v[174:177], v[190:193], v[126:129]
	v_mfma_f32_16x16x32_bf16 v[122:125], v[182:185], v[190:193], v[122:125]
	v_mfma_f32_16x16x32_bf16 v[106:109], v[174:177], v[198:201], v[106:109]
	v_mfma_f32_16x16x32_bf16 v[102:105], v[182:185], v[198:201], v[102:105]
	v_mfma_f32_16x16x32_bf16 v[86:89], v[174:177], v[206:209], v[86:89]
	v_mfma_f32_16x16x32_bf16 v[82:85], v[182:185], v[206:209], v[82:85]
	v_mfma_f32_16x16x32_bf16 v[62:65], v[174:177], v[214:217], v[62:65]
	v_mfma_f32_16x16x32_bf16 v[58:61], v[182:185], v[214:217], v[58:61]
	s_barrier
	s_setprio 0
	s_mov_b32 m0, s47
	s_add_u32 s98, s98, 0x80
	s_addc_u32 s99, s99, 0
	s_add_u32 s100, s100, 0x80
	s_addc_u32 s101, s101, 0
	s_add_u32 s6, s6, 0x20080
	ds_read_b128 v[186:189], v160 offset:49152
	ds_read_b128 v[190:193], v160 offset:50176
	ds_read_b128 v[194:197], v160 offset:51200
	ds_read_b128 v[198:201], v160 offset:52224
	ds_read_b128 v[202:205], v160 offset:53248
	ds_read_b128 v[206:209], v160 offset:54272
	global_load_lds_dwordx4 v140, s[98:99]
	s_mov_b32 m0, s86
	s_addc_u32 s7, s7, 0
	global_load_lds_dwordx4 v144, s[98:99]
	s_mov_b32 m0, s56
	ds_read_b128 v[214:217], v160 offset:56320
	global_load_lds_dwordx4 v140, s[6:7]
	s_mov_b32 m0, s57
	ds_read_b128 v[210:213], v160 offset:55296
	global_load_lds_dwordx4 v144, s[6:7]
	s_waitcnt vmcnt(6) lgkmcnt(0)
	s_setprio 1
	s_barrier
	v_mfma_f32_16x16x32_bf16 v[74:77], v[132:135], v[186:189], v[74:77]
	v_mfma_f32_16x16x32_bf16 v[66:69], v[162:165], v[186:189], v[66:69]
	v_mfma_f32_16x16x32_bf16 v[46:49], v[132:135], v[194:197], v[46:49]
	v_mfma_f32_16x16x32_bf16 v[42:45], v[162:165], v[194:197], v[42:45]
	v_mfma_f32_16x16x32_bf16 v[30:33], v[132:135], v[202:205], v[30:33]
	v_mfma_f32_16x16x32_bf16 v[26:29], v[162:165], v[202:205], v[26:29]
	v_mfma_f32_16x16x32_bf16 v[14:17], v[132:135], v[210:213], v[14:17]
	v_mfma_f32_16x16x32_bf16 v[10:13], v[162:165], v[210:213], v[10:13]
	v_mfma_f32_16x16x32_bf16 v[74:77], v[154:157], v[190:193], v[74:77]
	v_mfma_f32_16x16x32_bf16 v[66:69], v[166:169], v[190:193], v[66:69]
	v_mfma_f32_16x16x32_bf16 v[46:49], v[154:157], v[198:201], v[46:49]
	v_mfma_f32_16x16x32_bf16 v[42:45], v[166:169], v[198:201], v[42:45]
	v_mfma_f32_16x16x32_bf16 v[30:33], v[154:157], v[206:209], v[30:33]
	v_mfma_f32_16x16x32_bf16 v[26:29], v[166:169], v[206:209], v[26:29]
	v_mfma_f32_16x16x32_bf16 v[14:17], v[154:157], v[214:217], v[14:17]
	v_mfma_f32_16x16x32_bf16 v[10:13], v[166:169], v[214:217], v[10:13]
	s_setprio 0
	s_setprio 1
	v_mfma_f32_16x16x32_bf16 v[54:57], v[170:173], v[186:189], v[54:57]
	v_mfma_f32_16x16x32_bf16 v[50:53], v[178:181], v[186:189], v[50:53]
	v_mfma_f32_16x16x32_bf16 v[38:41], v[170:173], v[194:197], v[38:41]
	v_mfma_f32_16x16x32_bf16 v[34:37], v[178:181], v[194:197], v[34:37]
	v_mfma_f32_16x16x32_bf16 v[22:25], v[170:173], v[202:205], v[22:25]
	v_mfma_f32_16x16x32_bf16 v[18:21], v[178:181], v[202:205], v[18:21]
	v_mfma_f32_16x16x32_bf16 v[6:9], v[170:173], v[210:213], v[6:9]
	v_mfma_f32_16x16x32_bf16 v[2:5], v[178:181], v[210:213], v[2:5]
	v_mfma_f32_16x16x32_bf16 v[54:57], v[174:177], v[190:193], v[54:57]
	v_mfma_f32_16x16x32_bf16 v[50:53], v[182:185], v[190:193], v[50:53]
	v_mfma_f32_16x16x32_bf16 v[38:41], v[174:177], v[198:201], v[38:41]
	v_mfma_f32_16x16x32_bf16 v[34:37], v[182:185], v[198:201], v[34:37]
	v_mfma_f32_16x16x32_bf16 v[22:25], v[174:177], v[206:209], v[22:25]
	v_mfma_f32_16x16x32_bf16 v[18:21], v[182:185], v[206:209], v[18:21]
	v_mfma_f32_16x16x32_bf16 v[6:9], v[174:177], v[214:217], v[6:9]
	v_mfma_f32_16x16x32_bf16 v[2:5], v[182:185], v[214:217], v[2:5]
	s_barrier
	s_setprio 0
	s_add_i32 s26, s26, 2
	s_add_u32 s64, s64, 0x100
	s_addc_u32 s65, s65, 0
	s_add_u32 s14, s14, 0x100
	s_addc_u32 s15, s15, 0
	s_cmp_gt_u32 s26, 5
	s_cbranch_scc0 .LBB0_670
	s_mov_b32 m0, s69
	s_nop 0
	global_load_lds_dwordx4 v138, s[100:101]
	s_mov_b32 m0, s70
	s_nop 0
	global_load_lds_dwordx4 v142, s[100:101]
	s_and_b64 vcc, exec, s[18:19]
	s_cbranch_vccz .LBB0_673
	s_barrier

.Lrb2_skip_21903:
	s_mov_b32 m0, s23
	ds_read_b128 v[188:191], v166
	ds_read_b128 v[192:195], v166 offset:1024
	ds_read_b128 v[196:199], v166 offset:2048
	ds_read_b128 v[200:203], v166 offset:3072
	ds_read_b128 v[204:207], v166 offset:4096
	ds_read_b128 v[208:211], v166 offset:5120
	ds_read_b128 v[212:215], v166 offset:6144
	global_load_lds_dwordx4 v154, s[62:63]
	s_mov_b32 m0, s77
	ds_read_b128 v[216:219], v166 offset:7168
	global_load_lds_dwordx4 v156, s[62:63]
	s_waitcnt vmcnt(8) lgkmcnt(0)
	s_setprio 1
	s_barrier
	v_mfma_f32_16x16x32_bf16 v[102:105], v[132:135], v[188:191], v[102:105]
	v_mfma_f32_16x16x32_bf16 v[98:101], v[140:143], v[188:191], v[98:101]
	v_mfma_f32_16x16x32_bf16 v[94:97], v[132:135], v[196:199], v[94:97]
	v_mfma_f32_16x16x32_bf16 v[90:93], v[140:143], v[196:199], v[90:93]
	v_mfma_f32_16x16x32_bf16 v[86:89], v[132:135], v[204:207], v[86:89]
	v_mfma_f32_16x16x32_bf16 v[82:85], v[140:143], v[204:207], v[82:85]
	v_mfma_f32_16x16x32_bf16 v[78:81], v[132:135], v[212:215], v[78:81]
	v_mfma_f32_16x16x32_bf16 v[62:65], v[140:143], v[212:215], v[62:65]
	v_mfma_f32_16x16x32_bf16 v[102:105], v[136:139], v[192:195], v[102:105]
	v_mfma_f32_16x16x32_bf16 v[98:101], v[168:171], v[192:195], v[98:101]
	v_mfma_f32_16x16x32_bf16 v[94:97], v[136:139], v[200:203], v[94:97]
	v_mfma_f32_16x16x32_bf16 v[90:93], v[168:171], v[200:203], v[90:93]
	v_mfma_f32_16x16x32_bf16 v[86:89], v[136:139], v[208:211], v[86:89]
	v_mfma_f32_16x16x32_bf16 v[82:85], v[168:171], v[208:211], v[82:85]
	v_mfma_f32_16x16x32_bf16 v[78:81], v[136:139], v[216:219], v[78:81]
	v_mfma_f32_16x16x32_bf16 v[62:65], v[168:171], v[216:219], v[62:65]
	s_setprio 0
	s_setprio 1
	v_mfma_f32_16x16x32_bf16 v[126:129], v[172:175], v[188:191], v[126:129]
	v_mfma_f32_16x16x32_bf16 v[122:125], v[180:183], v[188:191], v[122:125]
	v_mfma_f32_16x16x32_bf16 v[118:121], v[172:175], v[196:199], v[118:121]
	v_mfma_f32_16x16x32_bf16 v[114:117], v[180:183], v[196:199], v[114:117]
	v_mfma_f32_16x16x32_bf16 v[110:113], v[172:175], v[204:207], v[110:113]
	v_mfma_f32_16x16x32_bf16 v[106:109], v[180:183], v[204:207], v[106:109]
	v_mfma_f32_16x16x32_bf16 v[54:57], v[172:175], v[212:215], v[54:57]
	v_mfma_f32_16x16x32_bf16 v[50:53], v[180:183], v[212:215], v[50:53]
	v_mfma_f32_16x16x32_bf16 v[126:129], v[176:179], v[192:195], v[126:129]
	v_mfma_f32_16x16x32_bf16 v[122:125], v[184:187], v[192:195], v[122:125]
	v_mfma_f32_16x16x32_bf16 v[118:121], v[176:179], v[200:203], v[118:121]
	v_mfma_f32_16x16x32_bf16 v[114:117], v[184:187], v[200:203], v[114:117]
	v_mfma_f32_16x16x32_bf16 v[110:113], v[176:179], v[208:211], v[110:113]
	v_mfma_f32_16x16x32_bf16 v[106:109], v[184:187], v[208:211], v[106:109]
	v_mfma_f32_16x16x32_bf16 v[54:57], v[176:179], v[216:219], v[54:57]
	v_mfma_f32_16x16x32_bf16 v[50:53], v[184:187], v[216:219], v[50:53]
	s_barrier
	s_setprio 0
	s_mov_b32 m0, s78
	s_mov_b64 s[98:99], s[50:51]
	s_add_u32 s82, s50, 0x80000
	ds_read_b128 v[188:191], v166 offset:16384
	ds_read_b128 v[192:195], v166 offset:17408
	ds_read_b128 v[196:199], v166 offset:18432
	ds_read_b128 v[200:203], v166 offset:19456
	ds_read_b128 v[204:207], v166 offset:20480
	ds_read_b128 v[208:211], v166 offset:21504
	ds_read_b128 v[212:215], v166 offset:22528
	global_load_lds_dwordx4 v148, s[50:51]
	s_mov_b32 m0, s79
	s_addc_u32 s83, s51, 0
	global_load_lds_dwordx4 v152, s[50:51]
	s_mov_b32 m0, s80
	s_mov_b64 s[100:101], s[64:65]
	global_load_lds_dwordx4 v148, s[82:83]
	s_mov_b32 m0, s46
	ds_read_b128 v[216:219], v166 offset:23552
	global_load_lds_dwordx4 v152, s[82:83]
	s_waitcnt vmcnt(6) lgkmcnt(0)
	s_setprio 1
	s_barrier
	v_mfma_f32_16x16x32_bf16 v[74:77], v[132:135], v[188:191], v[74:77]
	v_mfma_f32_16x16x32_bf16 v[70:73], v[140:143], v[188:191], v[70:73]
	v_mfma_f32_16x16x32_bf16 v[46:49], v[132:135], v[196:199], v[46:49]
	v_mfma_f32_16x16x32_bf16 v[42:45], v[140:143], v[196:199], v[42:45]
	v_mfma_f32_16x16x32_bf16 v[30:33], v[132:135], v[204:207], v[30:33]
	v_mfma_f32_16x16x32_bf16 v[26:29], v[140:143], v[204:207], v[26:29]
	v_mfma_f32_16x16x32_bf16 v[14:17], v[132:135], v[212:215], v[14:17]
	v_mfma_f32_16x16x32_bf16 v[10:13], v[140:143], v[212:215], v[10:13]
	v_mfma_f32_16x16x32_bf16 v[74:77], v[136:139], v[192:195], v[74:77]
	v_mfma_f32_16x16x32_bf16 v[70:73], v[168:171], v[192:195], v[70:73]
	v_mfma_f32_16x16x32_bf16 v[46:49], v[136:139], v[200:203], v[46:49]
	v_mfma_f32_16x16x32_bf16 v[42:45], v[168:171], v[200:203], v[42:45]
	v_mfma_f32_16x16x32_bf16 v[30:33], v[136:139], v[208:211], v[30:33]
	v_mfma_f32_16x16x32_bf16 v[26:29], v[168:171], v[208:211], v[26:29]
	v_mfma_f32_16x16x32_bf16 v[14:17], v[136:139], v[216:219], v[14:17]
	v_mfma_f32_16x16x32_bf16 v[10:13], v[168:171], v[216:219], v[10:13]
	s_setprio 0
	s_setprio 1
	v_mfma_f32_16x16x32_bf16 v[66:69], v[172:175], v[188:191], v[66:69]
	v_mfma_f32_16x16x32_bf16 v[58:61], v[180:183], v[188:191], v[58:61]
	v_mfma_f32_16x16x32_bf16 v[38:41], v[172:175], v[196:199], v[38:41]
	v_mfma_f32_16x16x32_bf16 v[34:37], v[180:183], v[196:199], v[34:37]
	v_mfma_f32_16x16x32_bf16 v[22:25], v[172:175], v[204:207], v[22:25]
	v_mfma_f32_16x16x32_bf16 v[18:21], v[180:183], v[204:207], v[18:21]
	v_mfma_f32_16x16x32_bf16 v[6:9], v[172:175], v[212:215], v[6:9]
	v_mfma_f32_16x16x32_bf16 v[2:5], v[180:183], v[212:215], v[2:5]
	v_mfma_f32_16x16x32_bf16 v[66:69], v[176:179], v[192:195], v[66:69]
	v_mfma_f32_16x16x32_bf16 v[58:61], v[184:187], v[192:195], v[58:61]
	v_mfma_f32_16x16x32_bf16 v[38:41], v[176:179], v[200:203], v[38:41]
	v_mfma_f32_16x16x32_bf16 v[34:37], v[184:187], v[200:203], v[34:37]
	v_mfma_f32_16x16x32_bf16 v[22:25], v[176:179], v[208:211], v[22:25]
	v_mfma_f32_16x16x32_bf16 v[18:21], v[184:187], v[208:211], v[18:21]
	v_mfma_f32_16x16x32_bf16 v[6:9], v[176:179], v[216:219], v[6:9]
	v_mfma_f32_16x16x32_bf16 v[2:5], v[184:187], v[216:219], v[2:5]
	s_barrier
;     ...
;         for (int t = 2; t < nt; t += 2) PG8_KITER(t);
	s_setprio 0
	ds_read_b128 v[132:135], v130
	ds_read_b128 v[136:139], v130 offset:1024
	ds_read_b128 v[140:143], v130 offset:2048
	ds_read_b128 v[168:171], v130 offset:3072
	ds_read_b128 v[172:175], v131
	ds_read_b128 v[176:179], v131 offset:1024
	s_add_u32 s64, s64, 0x80000
	s_addc_u32 s65, s65, 0
	s_mov_b32 m0, s59
	ds_read_b128 v[184:187], v131 offset:3072
	global_load_lds_dwordx4 v146, s[100:101]
	s_mov_b32 m0, s31
	ds_read_b128 v[180:183], v131 offset:2048
	global_load_lds_dwordx4 v150, s[100:101]
	s_mov_b32 m0, s66
	ds_read_b128 v[188:191], v166 offset:32768
	ds_read_b128 v[192:195], v166 offset:33792
	ds_read_b128 v[196:199], v166 offset:34816
	ds_read_b128 v[200:203], v166 offset:35840
	ds_read_b128 v[204:207], v166 offset:36864
	ds_read_b128 v[208:211], v166 offset:37888
	ds_read_b128 v[212:215], v166 offset:38912
	global_load_lds_dwordx4 v146, s[64:65]
	s_mov_b32 m0, s67
	ds_read_b128 v[216:219], v166 offset:39936
	global_load_lds_dwordx4 v150, s[64:65]
	s_waitcnt vmcnt(8) lgkmcnt(0)
	s_setprio 1
	s_barrier
	v_mfma_f32_16x16x32_bf16 v[102:105], v[132:135], v[188:191], v[102:105]
	v_mfma_f32_16x16x32_bf16 v[98:101], v[140:143], v[188:191], v[98:101]
	v_mfma_f32_16x16x32_bf16 v[94:97], v[132:135], v[196:199], v[94:97]
	v_mfma_f32_16x16x32_bf16 v[90:93], v[140:143], v[196:199], v[90:93]
	v_mfma_f32_16x16x32_bf16 v[86:89], v[132:135], v[204:207], v[86:89]
	v_mfma_f32_16x16x32_bf16 v[82:85], v[140:143], v[204:207], v[82:85]
	v_mfma_f32_16x16x32_bf16 v[78:81], v[132:135], v[212:215], v[78:81]
	v_mfma_f32_16x16x32_bf16 v[62:65], v[140:143], v[212:215], v[62:65]
	v_mfma_f32_16x16x32_bf16 v[102:105], v[136:139], v[192:195], v[102:105]
	v_mfma_f32_16x16x32_bf16 v[98:101], v[168:171], v[192:195], v[98:101]
	v_mfma_f32_16x16x32_bf16 v[94:97], v[136:139], v[200:203], v[94:97]
	v_mfma_f32_16x16x32_bf16 v[90:93], v[168:171], v[200:203], v[90:93]
	v_mfma_f32_16x16x32_bf16 v[86:89], v[136:139], v[208:211], v[86:89]
	v_mfma_f32_16x16x32_bf16 v[82:85], v[168:171], v[208:211], v[82:85]
	v_mfma_f32_16x16x32_bf16 v[78:81], v[136:139], v[216:219], v[78:81]
	v_mfma_f32_16x16x32_bf16 v[62:65], v[168:171], v[216:219], v[62:65]
	s_setprio 0
	s_setprio 1
	v_mfma_f32_16x16x32_bf16 v[126:129], v[172:175], v[188:191], v[126:129]
	v_mfma_f32_16x16x32_bf16 v[122:125], v[180:183], v[188:191], v[122:125]
	v_mfma_f32_16x16x32_bf16 v[118:121], v[172:175], v[196:199], v[118:121]
	v_mfma_f32_16x16x32_bf16 v[114:117], v[180:183], v[196:199], v[114:117]
	v_mfma_f32_16x16x32_bf16 v[110:113], v[172:175], v[204:207], v[110:113]
	v_mfma_f32_16x16x32_bf16 v[106:109], v[180:183], v[204:207], v[106:109]
	v_mfma_f32_16x16x32_bf16 v[54:57], v[172:175], v[212:215], v[54:57]
	v_mfma_f32_16x16x32_bf16 v[50:53], v[180:183], v[212:215], v[50:53]
	v_mfma_f32_16x16x32_bf16 v[126:129], v[176:179], v[192:195], v[126:129]
	v_mfma_f32_16x16x32_bf16 v[122:125], v[184:187], v[192:195], v[122:125]
	v_mfma_f32_16x16x32_bf16 v[118:121], v[176:179], v[200:203], v[118:121]
	v_mfma_f32_16x16x32_bf16 v[114:117], v[184:187], v[200:203], v[114:117]
	v_mfma_f32_16x16x32_bf16 v[110:113], v[176:179], v[208:211], v[110:113]
	v_mfma_f32_16x16x32_bf16 v[106:109], v[184:187], v[208:211], v[106:109]
	v_mfma_f32_16x16x32_bf16 v[54:57], v[176:179], v[216:219], v[54:57]
	v_mfma_f32_16x16x32_bf16 v[50:53], v[184:187], v[216:219], v[50:53]
	s_barrier
	s_setprio 0
	s_mov_b32 m0, s47
	s_add_u32 s98, s98, 0x80
	s_addc_u32 s99, s99, 0
	s_add_u32 s100, s100, 0x80
	s_addc_u32 s101, s101, 0
	s_add_u32 s50, s50, 0x80080
	ds_read_b128 v[188:191], v166 offset:49152
	ds_read_b128 v[192:195], v166 offset:50176
	ds_read_b128 v[196:199], v166 offset:51200
	ds_read_b128 v[200:203], v166 offset:52224
	ds_read_b128 v[204:207], v166 offset:53248
	ds_read_b128 v[208:211], v166 offset:54272
	global_load_lds_dwordx4 v148, s[98:99]
	s_mov_b32 m0, s81
	s_addc_u32 s51, s51, 0
	global_load_lds_dwordx4 v152, s[98:99]
	s_mov_b32 m0, s56
	ds_read_b128 v[216:219], v166 offset:56320
	global_load_lds_dwordx4 v148, s[50:51]
	s_mov_b32 m0, s57
	ds_read_b128 v[212:215], v166 offset:55296
	global_load_lds_dwordx4 v152, s[50:51]
	s_waitcnt vmcnt(6) lgkmcnt(0)
	s_setprio 1
	s_barrier
	v_mfma_f32_16x16x32_bf16 v[74:77], v[132:135], v[188:191], v[74:77]
	v_mfma_f32_16x16x32_bf16 v[70:73], v[140:143], v[188:191], v[70:73]
	v_mfma_f32_16x16x32_bf16 v[46:49], v[132:135], v[196:199], v[46:49]
	v_mfma_f32_16x16x32_bf16 v[42:45], v[140:143], v[196:199], v[42:45]
	v_mfma_f32_16x16x32_bf16 v[30:33], v[132:135], v[204:207], v[30:33]
	v_mfma_f32_16x16x32_bf16 v[26:29], v[140:143], v[204:207], v[26:29]
	v_mfma_f32_16x16x32_bf16 v[14:17], v[132:135], v[212:215], v[14:17]
	v_mfma_f32_16x16x32_bf16 v[10:13], v[140:143], v[212:215], v[10:13]
	v_mfma_f32_16x16x32_bf16 v[74:77], v[136:139], v[192:195], v[74:77]
	v_mfma_f32_16x16x32_bf16 v[70:73], v[168:171], v[192:195], v[70:73]
	v_mfma_f32_16x16x32_bf16 v[46:49], v[136:139], v[200:203], v[46:49]
	v_mfma_f32_16x16x32_bf16 v[42:45], v[168:171], v[200:203], v[42:45]
	v_mfma_f32_16x16x32_bf16 v[30:33], v[136:139], v[208:211], v[30:33]
	v_mfma_f32_16x16x32_bf16 v[26:29], v[168:171], v[208:211], v[26:29]
	v_mfma_f32_16x16x32_bf16 v[14:17], v[136:139], v[216:219], v[14:17]
	v_mfma_f32_16x16x32_bf16 v[10:13], v[168:171], v[216:219], v[10:13]
	s_setprio 0
	s_setprio 1
	v_mfma_f32_16x16x32_bf16 v[66:69], v[172:175], v[188:191], v[66:69]
	v_mfma_f32_16x16x32_bf16 v[58:61], v[180:183], v[188:191], v[58:61]
	v_mfma_f32_16x16x32_bf16 v[38:41], v[172:175], v[196:199], v[38:41]
	v_mfma_f32_16x16x32_bf16 v[34:37], v[180:183], v[196:199], v[34:37]
	v_mfma_f32_16x16x32_bf16 v[22:25], v[172:175], v[204:207], v[22:25]
	v_mfma_f32_16x16x32_bf16 v[18:21], v[180:183], v[204:207], v[18:21]
	v_mfma_f32_16x16x32_bf16 v[6:9], v[172:175], v[212:215], v[6:9]
	v_mfma_f32_16x16x32_bf16 v[2:5], v[180:183], v[212:215], v[2:5]
	v_mfma_f32_16x16x32_bf16 v[66:69], v[176:179], v[192:195], v[66:69]
	v_mfma_f32_16x16x32_bf16 v[58:61], v[184:187], v[192:195], v[58:61]
	v_mfma_f32_16x16x32_bf16 v[38:41], v[176:179], v[200:203], v[38:41]
	v_mfma_f32_16x16x32_bf16 v[34:37], v[184:187], v[200:203], v[34:37]
	v_mfma_f32_16x16x32_bf16 v[22:25], v[176:179], v[208:211], v[22:25]
	v_mfma_f32_16x16x32_bf16 v[18:21], v[184:187], v[208:211], v[18:21]
	v_mfma_f32_16x16x32_bf16 v[6:9], v[176:179], v[216:219], v[6:9]
	v_mfma_f32_16x16x32_bf16 v[2:5], v[184:187], v[216:219], v[2:5]
	s_barrier
	s_setprio 0
	s_add_i32 s26, s26, 2
	s_add_u32 s62, s62, 0x100
	s_addc_u32 s63, s63, 0
	s_add_u32 s14, s14, 0x100
	s_addc_u32 s15, s15, 0
	s_cmp_gt_u32 s26, 5
	s_cbranch_scc0 .LBB0_716
	s_mov_b32 m0, s69
	s_nop 0
	global_load_lds_dwordx4 v146, s[100:101]
	s_mov_b32 m0, s70
	s_nop 0
	global_load_lds_dwordx4 v150, s[100:101]
	s_and_b64 vcc, exec, s[16:17]
	s_cbranch_vccz .LBB0_719
	s_barrier

.Lrb2_skip_28568:
	s_mov_b32 m0, s0
	ds_read_b128 v[186:189], v172
	ds_read_b128 v[190:193], v172 offset:1024
	ds_read_b128 v[194:197], v172 offset:2048
	ds_read_b128 v[198:201], v172 offset:3072
	ds_read_b128 v[202:205], v172 offset:4096
	ds_read_b128 v[206:209], v172 offset:5120
	ds_read_b128 v[210:213], v172 offset:6144
	global_load_lds_dwordx4 v160, s[62:63]
	s_mov_b32 m0, s11
	ds_read_b128 v[214:217], v172 offset:7168
	global_load_lds_dwordx4 v162, s[62:63]
	s_waitcnt vmcnt(8) lgkmcnt(0)
	s_setprio 1
	s_barrier
	v_mfma_f32_16x16x32_bf16 v[126:129], v[134:137], v[186:189], v[126:129]
	v_mfma_f32_16x16x32_bf16 v[122:125], v[142:145], v[186:189], v[122:125]
	v_mfma_f32_16x16x32_bf16 v[118:121], v[134:137], v[194:197], v[118:121]
	v_mfma_f32_16x16x32_bf16 v[114:117], v[142:145], v[194:197], v[114:117]
	v_mfma_f32_16x16x32_bf16 v[110:113], v[134:137], v[202:205], v[110:113]
	v_mfma_f32_16x16x32_bf16 v[106:109], v[142:145], v[202:205], v[106:109]
	v_mfma_f32_16x16x32_bf16 v[102:105], v[134:137], v[210:213], v[102:105]
	v_mfma_f32_16x16x32_bf16 v[98:101], v[142:145], v[210:213], v[98:101]
	v_mfma_f32_16x16x32_bf16 v[126:129], v[138:141], v[190:193], v[126:129]
	v_mfma_f32_16x16x32_bf16 v[122:125], v[146:149], v[190:193], v[122:125]
	v_mfma_f32_16x16x32_bf16 v[118:121], v[138:141], v[198:201], v[118:121]
	v_mfma_f32_16x16x32_bf16 v[114:117], v[146:149], v[198:201], v[114:117]
	v_mfma_f32_16x16x32_bf16 v[110:113], v[138:141], v[206:209], v[110:113]
	v_mfma_f32_16x16x32_bf16 v[106:109], v[146:149], v[206:209], v[106:109]
	v_mfma_f32_16x16x32_bf16 v[102:105], v[138:141], v[214:217], v[102:105]
	v_mfma_f32_16x16x32_bf16 v[98:101], v[146:149], v[214:217], v[98:101]
	s_setprio 0
	s_setprio 1
	v_mfma_f32_16x16x32_bf16 v[94:97], v[168:171], v[186:189], v[94:97]
	v_mfma_f32_16x16x32_bf16 v[90:93], v[178:181], v[186:189], v[90:93]
	v_mfma_f32_16x16x32_bf16 v[86:89], v[168:171], v[194:197], v[86:89]
	v_mfma_f32_16x16x32_bf16 v[82:85], v[178:181], v[194:197], v[82:85]
	v_mfma_f32_16x16x32_bf16 v[78:81], v[168:171], v[202:205], v[78:81]
	v_mfma_f32_16x16x32_bf16 v[74:77], v[178:181], v[202:205], v[74:77]
	v_mfma_f32_16x16x32_bf16 v[70:73], v[168:171], v[210:213], v[70:73]
	v_mfma_f32_16x16x32_bf16 v[66:69], v[178:181], v[210:213], v[66:69]
	v_mfma_f32_16x16x32_bf16 v[94:97], v[174:177], v[190:193], v[94:97]
	v_mfma_f32_16x16x32_bf16 v[90:93], v[182:185], v[190:193], v[90:93]
	v_mfma_f32_16x16x32_bf16 v[86:89], v[174:177], v[198:201], v[86:89]
	v_mfma_f32_16x16x32_bf16 v[82:85], v[182:185], v[198:201], v[82:85]
	v_mfma_f32_16x16x32_bf16 v[78:81], v[174:177], v[206:209], v[78:81]
	v_mfma_f32_16x16x32_bf16 v[74:77], v[182:185], v[206:209], v[74:77]
	v_mfma_f32_16x16x32_bf16 v[70:73], v[174:177], v[214:217], v[70:73]
	v_mfma_f32_16x16x32_bf16 v[66:69], v[182:185], v[214:217], v[66:69]
	s_barrier
	s_setprio 0
	s_mov_b32 m0, s12
	s_mov_b64 s[98:99], s[50:51]
	s_add_u32 s58, s50, 0x80000
	ds_read_b128 v[186:189], v172 offset:16384
	ds_read_b128 v[190:193], v172 offset:17408
	ds_read_b128 v[194:197], v172 offset:18432
	ds_read_b128 v[198:201], v172 offset:19456
	ds_read_b128 v[202:205], v172 offset:20480
	ds_read_b128 v[206:209], v172 offset:21504
	ds_read_b128 v[210:213], v172 offset:22528
	global_load_lds_dwordx4 v152, s[50:51]
	s_mov_b32 m0, s13
	s_addc_u32 s59, s51, 0
	global_load_lds_dwordx4 v156, s[50:51]
	s_mov_b32 m0, s43
	s_mov_b64 s[100:101], s[64:65]
	global_load_lds_dwordx4 v152, s[58:59]
	s_mov_b32 m0, s46
	ds_read_b128 v[214:217], v172 offset:23552
	global_load_lds_dwordx4 v156, s[58:59]
	s_waitcnt vmcnt(6) lgkmcnt(0)
	s_setprio 1
	s_barrier
	v_mfma_f32_16x16x32_bf16 v[62:65], v[134:137], v[186:189], v[62:65]
	v_mfma_f32_16x16x32_bf16 v[58:61], v[142:145], v[186:189], v[58:61]
	v_mfma_f32_16x16x32_bf16 v[54:57], v[134:137], v[194:197], v[54:57]
	v_mfma_f32_16x16x32_bf16 v[50:53], v[142:145], v[194:197], v[50:53]
	v_mfma_f32_16x16x32_bf16 v[46:49], v[134:137], v[202:205], v[46:49]
	v_mfma_f32_16x16x32_bf16 v[42:45], v[142:145], v[202:205], v[42:45]
	v_mfma_f32_16x16x32_bf16 v[38:41], v[134:137], v[210:213], v[38:41]
	v_mfma_f32_16x16x32_bf16 v[34:37], v[142:145], v[210:213], v[34:37]
	v_mfma_f32_16x16x32_bf16 v[62:65], v[138:141], v[190:193], v[62:65]
	v_mfma_f32_16x16x32_bf16 v[58:61], v[146:149], v[190:193], v[58:61]
	v_mfma_f32_16x16x32_bf16 v[54:57], v[138:141], v[198:201], v[54:57]
	v_mfma_f32_16x16x32_bf16 v[50:53], v[146:149], v[198:201], v[50:53]
	v_mfma_f32_16x16x32_bf16 v[46:49], v[138:141], v[206:209], v[46:49]
	v_mfma_f32_16x16x32_bf16 v[42:45], v[146:149], v[206:209], v[42:45]
	v_mfma_f32_16x16x32_bf16 v[38:41], v[138:141], v[214:217], v[38:41]
	v_mfma_f32_16x16x32_bf16 v[34:37], v[146:149], v[214:217], v[34:37]
	s_setprio 0
	s_setprio 1
	v_mfma_f32_16x16x32_bf16 v[30:33], v[168:171], v[186:189], v[30:33]
	v_mfma_f32_16x16x32_bf16 v[26:29], v[178:181], v[186:189], v[26:29]
	v_mfma_f32_16x16x32_bf16 v[22:25], v[168:171], v[194:197], v[22:25]
	v_mfma_f32_16x16x32_bf16 v[18:21], v[178:181], v[194:197], v[18:21]
	v_mfma_f32_16x16x32_bf16 v[14:17], v[168:171], v[202:205], v[14:17]
	v_mfma_f32_16x16x32_bf16 v[10:13], v[178:181], v[202:205], v[10:13]
	v_mfma_f32_16x16x32_bf16 v[6:9], v[168:171], v[210:213], v[6:9]
	v_mfma_f32_16x16x32_bf16 v[2:5], v[178:181], v[210:213], v[2:5]
	v_mfma_f32_16x16x32_bf16 v[30:33], v[174:177], v[190:193], v[30:33]
	v_mfma_f32_16x16x32_bf16 v[26:29], v[182:185], v[190:193], v[26:29]
	v_mfma_f32_16x16x32_bf16 v[22:25], v[174:177], v[198:201], v[22:25]
	v_mfma_f32_16x16x32_bf16 v[18:21], v[182:185], v[198:201], v[18:21]
	v_mfma_f32_16x16x32_bf16 v[14:17], v[174:177], v[206:209], v[14:17]
	v_mfma_f32_16x16x32_bf16 v[10:13], v[182:185], v[206:209], v[10:13]
	v_mfma_f32_16x16x32_bf16 v[6:9], v[174:177], v[214:217], v[6:9]
	v_mfma_f32_16x16x32_bf16 v[2:5], v[182:185], v[214:217], v[2:5]
	s_barrier
;     ...
;         for (int t = 2; t < nt; t += 2) PG8_KITER(t);
	s_setprio 0
	ds_read_b128 v[134:137], v132
	ds_read_b128 v[138:141], v132 offset:1024
	ds_read_b128 v[142:145], v132 offset:2048
	ds_read_b128 v[146:149], v132 offset:3072
	ds_read_b128 v[168:171], v133
	ds_read_b128 v[174:177], v133 offset:1024
	s_add_u32 s58, s64, 0x80000
	s_addc_u32 s59, s65, 0
	s_mov_b32 m0, s69
	ds_read_b128 v[182:185], v133 offset:3072
	global_load_lds_dwordx4 v150, s[100:101]
	s_mov_b32 m0, s70
	ds_read_b128 v[178:181], v133 offset:2048
	global_load_lds_dwordx4 v154, s[100:101]
	s_mov_b32 m0, s71
	ds_read_b128 v[186:189], v172 offset:32768
	ds_read_b128 v[190:193], v172 offset:33792
	ds_read_b128 v[194:197], v172 offset:34816
	ds_read_b128 v[198:201], v172 offset:35840
	ds_read_b128 v[202:205], v172 offset:36864
	ds_read_b128 v[206:209], v172 offset:37888
	ds_read_b128 v[210:213], v172 offset:38912
	global_load_lds_dwordx4 v150, s[58:59]
	s_mov_b32 m0, s72
	ds_read_b128 v[214:217], v172 offset:39936
	global_load_lds_dwordx4 v154, s[58:59]
	s_waitcnt vmcnt(8) lgkmcnt(0)
	s_setprio 1
	s_barrier
	v_mfma_f32_16x16x32_bf16 v[126:129], v[134:137], v[186:189], v[126:129]
	v_mfma_f32_16x16x32_bf16 v[122:125], v[142:145], v[186:189], v[122:125]
	v_mfma_f32_16x16x32_bf16 v[118:121], v[134:137], v[194:197], v[118:121]
	v_mfma_f32_16x16x32_bf16 v[114:117], v[142:145], v[194:197], v[114:117]
	v_mfma_f32_16x16x32_bf16 v[110:113], v[134:137], v[202:205], v[110:113]
	v_mfma_f32_16x16x32_bf16 v[106:109], v[142:145], v[202:205], v[106:109]
	v_mfma_f32_16x16x32_bf16 v[102:105], v[134:137], v[210:213], v[102:105]
	v_mfma_f32_16x16x32_bf16 v[98:101], v[142:145], v[210:213], v[98:101]
	v_mfma_f32_16x16x32_bf16 v[126:129], v[138:141], v[190:193], v[126:129]
	v_mfma_f32_16x16x32_bf16 v[122:125], v[146:149], v[190:193], v[122:125]
	v_mfma_f32_16x16x32_bf16 v[118:121], v[138:141], v[198:201], v[118:121]
	v_mfma_f32_16x16x32_bf16 v[114:117], v[146:149], v[198:201], v[114:117]
	v_mfma_f32_16x16x32_bf16 v[110:113], v[138:141], v[206:209], v[110:113]
	v_mfma_f32_16x16x32_bf16 v[106:109], v[146:149], v[206:209], v[106:109]
	v_mfma_f32_16x16x32_bf16 v[102:105], v[138:141], v[214:217], v[102:105]
	v_mfma_f32_16x16x32_bf16 v[98:101], v[146:149], v[214:217], v[98:101]
	s_setprio 0
	s_setprio 1
	v_mfma_f32_16x16x32_bf16 v[94:97], v[168:171], v[186:189], v[94:97]
	v_mfma_f32_16x16x32_bf16 v[90:93], v[178:181], v[186:189], v[90:93]
	v_mfma_f32_16x16x32_bf16 v[86:89], v[168:171], v[194:197], v[86:89]
	v_mfma_f32_16x16x32_bf16 v[82:85], v[178:181], v[194:197], v[82:85]
	v_mfma_f32_16x16x32_bf16 v[78:81], v[168:171], v[202:205], v[78:81]
	v_mfma_f32_16x16x32_bf16 v[74:77], v[178:181], v[202:205], v[74:77]
	v_mfma_f32_16x16x32_bf16 v[70:73], v[168:171], v[210:213], v[70:73]
	v_mfma_f32_16x16x32_bf16 v[66:69], v[178:181], v[210:213], v[66:69]
	v_mfma_f32_16x16x32_bf16 v[94:97], v[174:177], v[190:193], v[94:97]
	v_mfma_f32_16x16x32_bf16 v[90:93], v[182:185], v[190:193], v[90:93]
	v_mfma_f32_16x16x32_bf16 v[86:89], v[174:177], v[198:201], v[86:89]
	v_mfma_f32_16x16x32_bf16 v[82:85], v[182:185], v[198:201], v[82:85]
	v_mfma_f32_16x16x32_bf16 v[78:81], v[174:177], v[206:209], v[78:81]
	v_mfma_f32_16x16x32_bf16 v[74:77], v[182:185], v[206:209], v[74:77]
	v_mfma_f32_16x16x32_bf16 v[70:73], v[174:177], v[214:217], v[70:73]
	v_mfma_f32_16x16x32_bf16 v[66:69], v[182:185], v[214:217], v[66:69]
	s_barrier
	s_setprio 0
	s_mov_b32 m0, s47
	s_add_u32 s98, s98, 0x80
	s_addc_u32 s99, s99, 0
	s_add_u32 s100, s100, 0x80
	s_addc_u32 s101, s101, 0
	s_add_u32 s50, s50, 0x80080
	ds_read_b128 v[186:189], v172 offset:49152
	ds_read_b128 v[190:193], v172 offset:50176
	ds_read_b128 v[194:197], v172 offset:51200
	ds_read_b128 v[198:201], v172 offset:52224
	ds_read_b128 v[202:205], v172 offset:53248
	ds_read_b128 v[206:209], v172 offset:54272
	global_load_lds_dwordx4 v152, s[98:99]
	s_mov_b32 m0, s53
	s_addc_u32 s51, s51, 0
	global_load_lds_dwordx4 v156, s[98:99]
	s_mov_b32 m0, s55
	ds_read_b128 v[214:217], v172 offset:56320
	global_load_lds_dwordx4 v152, s[50:51]
	s_mov_b32 m0, s56
	ds_read_b128 v[210:213], v172 offset:55296
	global_load_lds_dwordx4 v156, s[50:51]
	s_waitcnt vmcnt(6) lgkmcnt(0)
	s_setprio 1
	s_barrier
	v_mfma_f32_16x16x32_bf16 v[62:65], v[134:137], v[186:189], v[62:65]
	v_mfma_f32_16x16x32_bf16 v[58:61], v[142:145], v[186:189], v[58:61]
	v_mfma_f32_16x16x32_bf16 v[54:57], v[134:137], v[194:197], v[54:57]
	v_mfma_f32_16x16x32_bf16 v[50:53], v[142:145], v[194:197], v[50:53]
	v_mfma_f32_16x16x32_bf16 v[46:49], v[134:137], v[202:205], v[46:49]
	v_mfma_f32_16x16x32_bf16 v[42:45], v[142:145], v[202:205], v[42:45]
	v_mfma_f32_16x16x32_bf16 v[38:41], v[134:137], v[210:213], v[38:41]
	v_mfma_f32_16x16x32_bf16 v[34:37], v[142:145], v[210:213], v[34:37]
	v_mfma_f32_16x16x32_bf16 v[62:65], v[138:141], v[190:193], v[62:65]
	v_mfma_f32_16x16x32_bf16 v[58:61], v[146:149], v[190:193], v[58:61]
	v_mfma_f32_16x16x32_bf16 v[54:57], v[138:141], v[198:201], v[54:57]
	v_mfma_f32_16x16x32_bf16 v[50:53], v[146:149], v[198:201], v[50:53]
	v_mfma_f32_16x16x32_bf16 v[46:49], v[138:141], v[206:209], v[46:49]
	v_mfma_f32_16x16x32_bf16 v[42:45], v[146:149], v[206:209], v[42:45]
	v_mfma_f32_16x16x32_bf16 v[38:41], v[138:141], v[214:217], v[38:41]
	v_mfma_f32_16x16x32_bf16 v[34:37], v[146:149], v[214:217], v[34:37]
	s_setprio 0
	s_setprio 1
	v_mfma_f32_16x16x32_bf16 v[30:33], v[168:171], v[186:189], v[30:33]
	v_mfma_f32_16x16x32_bf16 v[26:29], v[178:181], v[186:189], v[26:29]
	v_mfma_f32_16x16x32_bf16 v[22:25], v[168:171], v[194:197], v[22:25]
	v_mfma_f32_16x16x32_bf16 v[18:21], v[178:181], v[194:197], v[18:21]
	v_mfma_f32_16x16x32_bf16 v[14:17], v[168:171], v[202:205], v[14:17]
	v_mfma_f32_16x16x32_bf16 v[10:13], v[178:181], v[202:205], v[10:13]
	v_mfma_f32_16x16x32_bf16 v[6:9], v[168:171], v[210:213], v[6:9]
	v_mfma_f32_16x16x32_bf16 v[2:5], v[178:181], v[210:213], v[2:5]
	v_mfma_f32_16x16x32_bf16 v[30:33], v[174:177], v[190:193], v[30:33]
	v_mfma_f32_16x16x32_bf16 v[26:29], v[182:185], v[190:193], v[26:29]
	v_mfma_f32_16x16x32_bf16 v[22:25], v[174:177], v[198:201], v[22:25]
	v_mfma_f32_16x16x32_bf16 v[18:21], v[182:185], v[198:201], v[18:21]
	v_mfma_f32_16x16x32_bf16 v[14:17], v[174:177], v[206:209], v[14:17]
	v_mfma_f32_16x16x32_bf16 v[10:13], v[182:185], v[206:209], v[10:13]
	v_mfma_f32_16x16x32_bf16 v[6:9], v[174:177], v[214:217], v[6:9]
	v_mfma_f32_16x16x32_bf16 v[2:5], v[182:185], v[214:217], v[2:5]
	s_barrier
	s_setprio 0
	s_add_i32 s26, s26, 2
	s_add_u32 s62, s62, 0x100
	s_addc_u32 s63, s63, 0
	s_add_u32 s14, s14, 0x100
	s_addc_u32 s15, s15, 0
	s_cmp_gt_u32 s26, 29
	s_cbranch_scc0 .LBB0_930
	s_mov_b32 m0, s77
	s_nop 0
	global_load_lds_dwordx4 v150, s[100:101]
	s_mov_b32 m0, s78
	s_nop 0
	global_load_lds_dwordx4 v154, s[100:101]
	s_and_b64 vcc, exec, s[18:19]
	s_cbranch_vccz .LBB0_933
	s_barrier

.Lrb2_skip_31798:
	s_mov_b32 m0, s61
	ds_read_b128 v[186:189], v184
	ds_read_b128 v[190:193], v184 offset:1024
	ds_read_b128 v[194:197], v184 offset:2048
	ds_read_b128 v[198:201], v184 offset:3072
	ds_read_b128 v[202:205], v184 offset:4096
	ds_read_b128 v[206:209], v184 offset:5120
	ds_read_b128 v[210:213], v184 offset:6144
	global_load_lds_dwordx4 v162, s[48:49]
	s_mov_b32 m0, s62
	ds_read_b128 v[214:217], v184 offset:7168
	global_load_lds_dwordx4 v164, s[48:49]
	s_waitcnt vmcnt(8) lgkmcnt(0)
	s_setprio 1
	s_barrier
	v_mfma_f32_16x16x32_bf16 v[122:125], v[132:135], v[186:189], v[122:125]
	v_mfma_f32_16x16x32_bf16 v[118:121], v[140:143], v[186:189], v[118:121]
	v_mfma_f32_16x16x32_bf16 v[110:113], v[132:135], v[194:197], v[110:113]
	v_mfma_f32_16x16x32_bf16 v[106:109], v[140:143], v[194:197], v[106:109]
	v_mfma_f32_16x16x32_bf16 v[94:97], v[132:135], v[202:205], v[94:97]
	v_mfma_f32_16x16x32_bf16 v[90:93], v[140:143], v[202:205], v[90:93]
	v_mfma_f32_16x16x32_bf16 v[78:81], v[132:135], v[210:213], v[78:81]
	v_mfma_f32_16x16x32_bf16 v[74:77], v[140:143], v[210:213], v[74:77]
	v_mfma_f32_16x16x32_bf16 v[122:125], v[136:139], v[190:193], v[122:125]
	v_mfma_f32_16x16x32_bf16 v[118:121], v[144:147], v[190:193], v[118:121]
	v_mfma_f32_16x16x32_bf16 v[110:113], v[136:139], v[198:201], v[110:113]
	v_mfma_f32_16x16x32_bf16 v[106:109], v[144:147], v[198:201], v[106:109]
	v_mfma_f32_16x16x32_bf16 v[94:97], v[136:139], v[206:209], v[94:97]
	v_mfma_f32_16x16x32_bf16 v[90:93], v[144:147], v[206:209], v[90:93]
	v_mfma_f32_16x16x32_bf16 v[78:81], v[136:139], v[214:217], v[78:81]
	v_mfma_f32_16x16x32_bf16 v[74:77], v[144:147], v[214:217], v[74:77]
	s_setprio 0
	s_setprio 1
	v_mfma_f32_16x16x32_bf16 v[126:129], v[148:151], v[186:189], v[126:129]
	v_mfma_f32_16x16x32_bf16 v[114:117], v[174:177], v[186:189], v[114:117]
	v_mfma_f32_16x16x32_bf16 v[102:105], v[148:151], v[194:197], v[102:105]
	v_mfma_f32_16x16x32_bf16 v[98:101], v[174:177], v[194:197], v[98:101]
	v_mfma_f32_16x16x32_bf16 v[86:89], v[148:151], v[202:205], v[86:89]
	v_mfma_f32_16x16x32_bf16 v[82:85], v[174:177], v[202:205], v[82:85]
	v_mfma_f32_16x16x32_bf16 v[70:73], v[148:151], v[210:213], v[70:73]
	v_mfma_f32_16x16x32_bf16 v[66:69], v[174:177], v[210:213], v[66:69]
	v_mfma_f32_16x16x32_bf16 v[126:129], v[170:173], v[190:193], v[126:129]
	v_mfma_f32_16x16x32_bf16 v[114:117], v[178:181], v[190:193], v[114:117]
	v_mfma_f32_16x16x32_bf16 v[102:105], v[170:173], v[198:201], v[102:105]
	v_mfma_f32_16x16x32_bf16 v[98:101], v[178:181], v[198:201], v[98:101]
	v_mfma_f32_16x16x32_bf16 v[86:89], v[170:173], v[206:209], v[86:89]
	v_mfma_f32_16x16x32_bf16 v[82:85], v[178:181], v[206:209], v[82:85]
	v_mfma_f32_16x16x32_bf16 v[70:73], v[170:173], v[214:217], v[70:73]
	v_mfma_f32_16x16x32_bf16 v[66:69], v[178:181], v[214:217], v[66:69]
	s_barrier
	s_setprio 0
	s_mov_b32 m0, s63
	s_mov_b64 s[98:99], s[42:43]
	s_add_u32 s72, s42, 0x100000
	ds_read_b128 v[186:189], v184 offset:16384
	ds_read_b128 v[190:193], v184 offset:17408
	ds_read_b128 v[194:197], v184 offset:18432
	ds_read_b128 v[198:201], v184 offset:19456
	ds_read_b128 v[202:205], v184 offset:20480
	ds_read_b128 v[206:209], v184 offset:21504
	ds_read_b128 v[210:213], v184 offset:22528
	global_load_lds_dwordx4 v156, s[42:43]
	s_mov_b32 m0, s64
	s_addc_u32 s73, s43, 0
	global_load_lds_dwordx4 v160, s[42:43]
	s_mov_b32 m0, s69
	s_mov_b64 s[100:101], s[50:51]
	global_load_lds_dwordx4 v156, s[72:73]
	s_mov_b32 m0, s46
	ds_read_b128 v[214:217], v184 offset:23552
	global_load_lds_dwordx4 v160, s[72:73]
	s_waitcnt vmcnt(6) lgkmcnt(0)
	s_setprio 1
	s_barrier
	v_mfma_f32_16x16x32_bf16 v[58:61], v[132:135], v[186:189], v[58:61]
	v_mfma_f32_16x16x32_bf16 v[54:57], v[140:143], v[186:189], v[54:57]
	v_mfma_f32_16x16x32_bf16 v[46:49], v[132:135], v[194:197], v[46:49]
	v_mfma_f32_16x16x32_bf16 v[42:45], v[140:143], v[194:197], v[42:45]
	v_mfma_f32_16x16x32_bf16 v[30:33], v[132:135], v[202:205], v[30:33]
	v_mfma_f32_16x16x32_bf16 v[26:29], v[140:143], v[202:205], v[26:29]
	v_mfma_f32_16x16x32_bf16 v[14:17], v[132:135], v[210:213], v[14:17]
	v_mfma_f32_16x16x32_bf16 v[10:13], v[140:143], v[210:213], v[10:13]
	v_mfma_f32_16x16x32_bf16 v[58:61], v[136:139], v[190:193], v[58:61]
	v_mfma_f32_16x16x32_bf16 v[54:57], v[144:147], v[190:193], v[54:57]
	v_mfma_f32_16x16x32_bf16 v[46:49], v[136:139], v[198:201], v[46:49]
	v_mfma_f32_16x16x32_bf16 v[42:45], v[144:147], v[198:201], v[42:45]
	v_mfma_f32_16x16x32_bf16 v[30:33], v[136:139], v[206:209], v[30:33]
	v_mfma_f32_16x16x32_bf16 v[26:29], v[144:147], v[206:209], v[26:29]
	v_mfma_f32_16x16x32_bf16 v[14:17], v[136:139], v[214:217], v[14:17]
	v_mfma_f32_16x16x32_bf16 v[10:13], v[144:147], v[214:217], v[10:13]
	s_setprio 0
	s_setprio 1
	v_mfma_f32_16x16x32_bf16 v[62:65], v[148:151], v[186:189], v[62:65]
	v_mfma_f32_16x16x32_bf16 v[50:53], v[174:177], v[186:189], v[50:53]
	v_mfma_f32_16x16x32_bf16 v[38:41], v[148:151], v[194:197], v[38:41]
	v_mfma_f32_16x16x32_bf16 v[34:37], v[174:177], v[194:197], v[34:37]
	v_mfma_f32_16x16x32_bf16 v[22:25], v[148:151], v[202:205], v[22:25]
	v_mfma_f32_16x16x32_bf16 v[18:21], v[174:177], v[202:205], v[18:21]
	v_mfma_f32_16x16x32_bf16 v[6:9], v[148:151], v[210:213], v[6:9]
	v_mfma_f32_16x16x32_bf16 v[2:5], v[174:177], v[210:213], v[2:5]
	v_mfma_f32_16x16x32_bf16 v[62:65], v[170:173], v[190:193], v[62:65]
	v_mfma_f32_16x16x32_bf16 v[50:53], v[178:181], v[190:193], v[50:53]
	v_mfma_f32_16x16x32_bf16 v[38:41], v[170:173], v[198:201], v[38:41]
	v_mfma_f32_16x16x32_bf16 v[34:37], v[178:181], v[198:201], v[34:37]
	v_mfma_f32_16x16x32_bf16 v[22:25], v[170:173], v[206:209], v[22:25]
	v_mfma_f32_16x16x32_bf16 v[18:21], v[178:181], v[206:209], v[18:21]
	v_mfma_f32_16x16x32_bf16 v[6:9], v[170:173], v[214:217], v[6:9]
	v_mfma_f32_16x16x32_bf16 v[2:5], v[178:181], v[214:217], v[2:5]
	s_barrier
;     ...
;         for (int t = 2; t < nt; t += 2) PG8_KITER(t);
	s_setprio 0
	ds_read_b128 v[132:135], v130
	ds_read_b128 v[136:139], v130 offset:1024
	ds_read_b128 v[140:143], v130 offset:2048
	ds_read_b128 v[144:147], v130 offset:3072
	ds_read_b128 v[148:151], v131
	ds_read_b128 v[170:173], v131 offset:1024
	s_add_u32 s50, s50, 0x100000
	s_addc_u32 s51, s51, 0
	s_mov_b32 m0, s13
	ds_read_b128 v[178:181], v131 offset:3072
	global_load_lds_dwordx4 v154, s[100:101]
	s_mov_b32 m0, s33
	ds_read_b128 v[174:177], v131 offset:2048
	global_load_lds_dwordx4 v158, s[100:101]
	s_mov_b32 m0, s52
	ds_read_b128 v[186:189], v184 offset:32768
	ds_read_b128 v[190:193], v184 offset:33792
	ds_read_b128 v[194:197], v184 offset:34816
	ds_read_b128 v[198:201], v184 offset:35840
	ds_read_b128 v[202:205], v184 offset:36864
	ds_read_b128 v[206:209], v184 offset:37888
	ds_read_b128 v[210:213], v184 offset:38912
	global_load_lds_dwordx4 v154, s[50:51]
	s_mov_b32 m0, s53
	ds_read_b128 v[214:217], v184 offset:39936
	global_load_lds_dwordx4 v158, s[50:51]
	s_waitcnt vmcnt(8) lgkmcnt(0)
	s_setprio 1
	s_barrier
	v_mfma_f32_16x16x32_bf16 v[122:125], v[132:135], v[186:189], v[122:125]
	v_mfma_f32_16x16x32_bf16 v[118:121], v[140:143], v[186:189], v[118:121]
	v_mfma_f32_16x16x32_bf16 v[110:113], v[132:135], v[194:197], v[110:113]
	v_mfma_f32_16x16x32_bf16 v[106:109], v[140:143], v[194:197], v[106:109]
	v_mfma_f32_16x16x32_bf16 v[94:97], v[132:135], v[202:205], v[94:97]
	v_mfma_f32_16x16x32_bf16 v[90:93], v[140:143], v[202:205], v[90:93]
	v_mfma_f32_16x16x32_bf16 v[78:81], v[132:135], v[210:213], v[78:81]
	v_mfma_f32_16x16x32_bf16 v[74:77], v[140:143], v[210:213], v[74:77]
	v_mfma_f32_16x16x32_bf16 v[122:125], v[136:139], v[190:193], v[122:125]
	v_mfma_f32_16x16x32_bf16 v[118:121], v[144:147], v[190:193], v[118:121]
	v_mfma_f32_16x16x32_bf16 v[110:113], v[136:139], v[198:201], v[110:113]
	v_mfma_f32_16x16x32_bf16 v[106:109], v[144:147], v[198:201], v[106:109]
	v_mfma_f32_16x16x32_bf16 v[94:97], v[136:139], v[206:209], v[94:97]
	v_mfma_f32_16x16x32_bf16 v[90:93], v[144:147], v[206:209], v[90:93]
	v_mfma_f32_16x16x32_bf16 v[78:81], v[136:139], v[214:217], v[78:81]
	v_mfma_f32_16x16x32_bf16 v[74:77], v[144:147], v[214:217], v[74:77]
	s_setprio 0
	s_setprio 1
	v_mfma_f32_16x16x32_bf16 v[126:129], v[148:151], v[186:189], v[126:129]
	v_mfma_f32_16x16x32_bf16 v[114:117], v[174:177], v[186:189], v[114:117]
	v_mfma_f32_16x16x32_bf16 v[102:105], v[148:151], v[194:197], v[102:105]
	v_mfma_f32_16x16x32_bf16 v[98:101], v[174:177], v[194:197], v[98:101]
	v_mfma_f32_16x16x32_bf16 v[86:89], v[148:151], v[202:205], v[86:89]
	v_mfma_f32_16x16x32_bf16 v[82:85], v[174:177], v[202:205], v[82:85]
	v_mfma_f32_16x16x32_bf16 v[70:73], v[148:151], v[210:213], v[70:73]
	v_mfma_f32_16x16x32_bf16 v[66:69], v[174:177], v[210:213], v[66:69]
	v_mfma_f32_16x16x32_bf16 v[126:129], v[170:173], v[190:193], v[126:129]
	v_mfma_f32_16x16x32_bf16 v[114:117], v[178:181], v[190:193], v[114:117]
	v_mfma_f32_16x16x32_bf16 v[102:105], v[170:173], v[198:201], v[102:105]
	v_mfma_f32_16x16x32_bf16 v[98:101], v[178:181], v[198:201], v[98:101]
	v_mfma_f32_16x16x32_bf16 v[86:89], v[170:173], v[206:209], v[86:89]
	v_mfma_f32_16x16x32_bf16 v[82:85], v[178:181], v[206:209], v[82:85]
	v_mfma_f32_16x16x32_bf16 v[70:73], v[170:173], v[214:217], v[70:73]
	v_mfma_f32_16x16x32_bf16 v[66:69], v[178:181], v[214:217], v[66:69]
	s_barrier
	s_setprio 0
	s_mov_b32 m0, s47
	s_add_u32 s98, s98, 0x80
	s_addc_u32 s99, s99, 0
	s_add_u32 s100, s100, 0x80
	s_addc_u32 s101, s101, 0
	s_add_u32 s42, s42, 0x100080
	ds_read_b128 v[186:189], v184 offset:49152
	ds_read_b128 v[190:193], v184 offset:50176
	ds_read_b128 v[194:197], v184 offset:51200
	ds_read_b128 v[198:201], v184 offset:52224
	ds_read_b128 v[202:205], v184 offset:53248
	ds_read_b128 v[206:209], v184 offset:54272
	global_load_lds_dwordx4 v156, s[98:99]
	s_mov_b32 m0, s70
	s_addc_u32 s43, s43, 0
	global_load_lds_dwordx4 v160, s[98:99]
	s_mov_b32 m0, s56
	ds_read_b128 v[214:217], v184 offset:56320
	global_load_lds_dwordx4 v156, s[42:43]
	s_mov_b32 m0, s57
	ds_read_b128 v[210:213], v184 offset:55296
	global_load_lds_dwordx4 v160, s[42:43]
	s_waitcnt vmcnt(6) lgkmcnt(0)
	s_setprio 1
	s_barrier
	v_mfma_f32_16x16x32_bf16 v[58:61], v[132:135], v[186:189], v[58:61]
	v_mfma_f32_16x16x32_bf16 v[54:57], v[140:143], v[186:189], v[54:57]
	v_mfma_f32_16x16x32_bf16 v[46:49], v[132:135], v[194:197], v[46:49]
	v_mfma_f32_16x16x32_bf16 v[42:45], v[140:143], v[194:197], v[42:45]
	v_mfma_f32_16x16x32_bf16 v[30:33], v[132:135], v[202:205], v[30:33]
	v_mfma_f32_16x16x32_bf16 v[26:29], v[140:143], v[202:205], v[26:29]
	v_mfma_f32_16x16x32_bf16 v[14:17], v[132:135], v[210:213], v[14:17]
	v_mfma_f32_16x16x32_bf16 v[10:13], v[140:143], v[210:213], v[10:13]
	v_mfma_f32_16x16x32_bf16 v[58:61], v[136:139], v[190:193], v[58:61]
	v_mfma_f32_16x16x32_bf16 v[54:57], v[144:147], v[190:193], v[54:57]
	v_mfma_f32_16x16x32_bf16 v[46:49], v[136:139], v[198:201], v[46:49]
	v_mfma_f32_16x16x32_bf16 v[42:45], v[144:147], v[198:201], v[42:45]
	v_mfma_f32_16x16x32_bf16 v[30:33], v[136:139], v[206:209], v[30:33]
	v_mfma_f32_16x16x32_bf16 v[26:29], v[144:147], v[206:209], v[26:29]
	v_mfma_f32_16x16x32_bf16 v[14:17], v[136:139], v[214:217], v[14:17]
	v_mfma_f32_16x16x32_bf16 v[10:13], v[144:147], v[214:217], v[10:13]
	s_setprio 0
	s_setprio 1
	v_mfma_f32_16x16x32_bf16 v[62:65], v[148:151], v[186:189], v[62:65]
	v_mfma_f32_16x16x32_bf16 v[50:53], v[174:177], v[186:189], v[50:53]
	v_mfma_f32_16x16x32_bf16 v[38:41], v[148:151], v[194:197], v[38:41]
	v_mfma_f32_16x16x32_bf16 v[34:37], v[174:177], v[194:197], v[34:37]
	v_mfma_f32_16x16x32_bf16 v[22:25], v[148:151], v[202:205], v[22:25]
	v_mfma_f32_16x16x32_bf16 v[18:21], v[174:177], v[202:205], v[18:21]
	v_mfma_f32_16x16x32_bf16 v[6:9], v[148:151], v[210:213], v[6:9]
	v_mfma_f32_16x16x32_bf16 v[2:5], v[174:177], v[210:213], v[2:5]
	v_mfma_f32_16x16x32_bf16 v[62:65], v[170:173], v[190:193], v[62:65]
	v_mfma_f32_16x16x32_bf16 v[50:53], v[178:181], v[190:193], v[50:53]
	v_mfma_f32_16x16x32_bf16 v[38:41], v[170:173], v[198:201], v[38:41]
	v_mfma_f32_16x16x32_bf16 v[34:37], v[178:181], v[198:201], v[34:37]
	v_mfma_f32_16x16x32_bf16 v[22:25], v[170:173], v[206:209], v[22:25]
	v_mfma_f32_16x16x32_bf16 v[18:21], v[178:181], v[206:209], v[18:21]
	v_mfma_f32_16x16x32_bf16 v[6:9], v[170:173], v[214:217], v[6:9]
	v_mfma_f32_16x16x32_bf16 v[2:5], v[178:181], v[214:217], v[2:5]
	s_barrier
	s_setprio 0
	s_add_i32 s26, s26, 2
	s_add_u32 s48, s48, 0x100
	s_addc_u32 s49, s49, 0
	s_add_u32 s14, s14, 0x100
	s_addc_u32 s15, s15, 0
	s_cmp_gt_u32 s26, 61
	s_cbranch_scc0 .LBB0_1014
	s_mov_b32 m0, s54
	s_nop 0
	global_load_lds_dwordx4 v154, s[100:101]
	s_mov_b32 m0, s55
	s_nop 0
	global_load_lds_dwordx4 v158, s[100:101]
	s_and_b64 vcc, exec, s[18:19]
	s_cbranch_vccz .LBB0_1017
	s_barrier

.Lrb2_skip_34078:
	s_mov_b32 m0, s41
	ds_read_b128 v[184:187], v150
	ds_read_b128 v[188:191], v150 offset:1024
	ds_read_b128 v[192:195], v150 offset:2048
	ds_read_b128 v[196:199], v150 offset:3072
	ds_read_b128 v[200:203], v150 offset:4096
	ds_read_b128 v[204:207], v150 offset:5120
	ds_read_b128 v[208:211], v150 offset:6144
	global_load_lds_dwordx4 v136, s[0:1]
	s_mov_b32 m0, s73
	ds_read_b128 v[212:215], v150 offset:7168
	global_load_lds_dwordx4 v138, s[0:1]
	s_waitcnt vmcnt(8) lgkmcnt(0)
	s_setprio 1
	s_barrier
	v_mfma_f32_16x16x32_bf16 v[118:121], v[152:155], v[184:187], v[118:121]
	v_mfma_f32_16x16x32_bf16 v[114:117], v[160:163], v[184:187], v[114:117]
	v_mfma_f32_16x16x32_bf16 v[102:105], v[152:155], v[192:195], v[102:105]
	v_mfma_f32_16x16x32_bf16 v[98:101], v[160:163], v[192:195], v[98:101]
	v_mfma_f32_16x16x32_bf16 v[86:89], v[152:155], v[200:203], v[86:89]
	v_mfma_f32_16x16x32_bf16 v[82:85], v[160:163], v[200:203], v[82:85]
	v_mfma_f32_16x16x32_bf16 v[74:77], v[152:155], v[208:211], v[74:77]
	v_mfma_f32_16x16x32_bf16 v[54:57], v[160:163], v[208:211], v[54:57]
	v_mfma_f32_16x16x32_bf16 v[118:121], v[156:159], v[188:191], v[118:121]
	v_mfma_f32_16x16x32_bf16 v[114:117], v[164:167], v[188:191], v[114:117]
	v_mfma_f32_16x16x32_bf16 v[102:105], v[156:159], v[196:199], v[102:105]
	v_mfma_f32_16x16x32_bf16 v[98:101], v[164:167], v[196:199], v[98:101]
	v_mfma_f32_16x16x32_bf16 v[86:89], v[156:159], v[204:207], v[86:89]
	v_mfma_f32_16x16x32_bf16 v[82:85], v[164:167], v[204:207], v[82:85]
	v_mfma_f32_16x16x32_bf16 v[74:77], v[156:159], v[212:215], v[74:77]
	v_mfma_f32_16x16x32_bf16 v[54:57], v[164:167], v[212:215], v[54:57]
	s_setprio 0
	s_setprio 1
	v_mfma_f32_16x16x32_bf16 v[126:129], v[168:171], v[184:187], v[126:129]
	v_mfma_f32_16x16x32_bf16 v[122:125], v[176:179], v[184:187], v[122:125]
	v_mfma_f32_16x16x32_bf16 v[110:113], v[168:171], v[192:195], v[110:113]
	v_mfma_f32_16x16x32_bf16 v[106:109], v[176:179], v[192:195], v[106:109]
	v_mfma_f32_16x16x32_bf16 v[94:97], v[168:171], v[200:203], v[94:97]
	v_mfma_f32_16x16x32_bf16 v[90:93], v[176:179], v[200:203], v[90:93]
	v_mfma_f32_16x16x32_bf16 v[70:73], v[168:171], v[208:211], v[70:73]
	v_mfma_f32_16x16x32_bf16 v[50:53], v[176:179], v[208:211], v[50:53]
	v_mfma_f32_16x16x32_bf16 v[126:129], v[172:175], v[188:191], v[126:129]
	v_mfma_f32_16x16x32_bf16 v[122:125], v[180:183], v[188:191], v[122:125]
	v_mfma_f32_16x16x32_bf16 v[110:113], v[172:175], v[196:199], v[110:113]
	v_mfma_f32_16x16x32_bf16 v[106:109], v[180:183], v[196:199], v[106:109]
	v_mfma_f32_16x16x32_bf16 v[94:97], v[172:175], v[204:207], v[94:97]
	v_mfma_f32_16x16x32_bf16 v[90:93], v[180:183], v[204:207], v[90:93]
	v_mfma_f32_16x16x32_bf16 v[70:73], v[172:175], v[212:215], v[70:73]
	v_mfma_f32_16x16x32_bf16 v[50:53], v[180:183], v[212:215], v[50:53]
	s_barrier
	s_setprio 0
	s_mov_b32 m0, s74
	s_mov_b64 s[98:99], s[52:53]
	s_add_u32 s78, s52, 0x100000
	ds_read_b128 v[184:187], v150 offset:16384
	ds_read_b128 v[188:191], v150 offset:17408
	ds_read_b128 v[192:195], v150 offset:18432
	ds_read_b128 v[196:199], v150 offset:19456
	ds_read_b128 v[200:203], v150 offset:20480
	ds_read_b128 v[204:207], v150 offset:21504
	ds_read_b128 v[208:211], v150 offset:22528
	global_load_lds_dwordx4 v130, s[52:53]
	s_mov_b32 m0, s75
	s_addc_u32 s79, s53, 0
	global_load_lds_dwordx4 v132, s[52:53]
	s_mov_b32 m0, s76
	s_mov_b64 s[100:101], s[54:55]
	global_load_lds_dwordx4 v130, s[78:79]
	s_mov_b32 m0, s46
	ds_read_b128 v[212:215], v150 offset:23552
	global_load_lds_dwordx4 v132, s[78:79]
	s_waitcnt vmcnt(6) lgkmcnt(0)
	s_setprio 1
	s_barrier
	v_mfma_f32_16x16x32_bf16 v[66:69], v[152:155], v[184:187], v[66:69]
	v_mfma_f32_16x16x32_bf16 v[62:65], v[160:163], v[184:187], v[62:65]
	v_mfma_f32_16x16x32_bf16 v[42:45], v[152:155], v[192:195], v[42:45]
	v_mfma_f32_16x16x32_bf16 v[38:41], v[160:163], v[192:195], v[38:41]
	v_mfma_f32_16x16x32_bf16 v[26:29], v[152:155], v[200:203], v[26:29]
	v_mfma_f32_16x16x32_bf16 v[22:25], v[160:163], v[200:203], v[22:25]
	v_mfma_f32_16x16x32_bf16 v[6:9], v[152:155], v[208:211], v[6:9]
	v_mfma_f32_16x16x32_bf16 v[2:5], v[160:163], v[208:211], v[2:5]
	v_mfma_f32_16x16x32_bf16 v[66:69], v[156:159], v[188:191], v[66:69]
	v_mfma_f32_16x16x32_bf16 v[62:65], v[164:167], v[188:191], v[62:65]
	v_mfma_f32_16x16x32_bf16 v[42:45], v[156:159], v[196:199], v[42:45]
	v_mfma_f32_16x16x32_bf16 v[38:41], v[164:167], v[196:199], v[38:41]
	v_mfma_f32_16x16x32_bf16 v[26:29], v[156:159], v[204:207], v[26:29]
	v_mfma_f32_16x16x32_bf16 v[22:25], v[164:167], v[204:207], v[22:25]
	v_mfma_f32_16x16x32_bf16 v[6:9], v[156:159], v[212:215], v[6:9]
	v_mfma_f32_16x16x32_bf16 v[2:5], v[164:167], v[212:215], v[2:5]
	s_setprio 0
	s_setprio 1
	v_mfma_f32_16x16x32_bf16 v[78:81], v[168:171], v[184:187], v[78:81]
	v_mfma_f32_16x16x32_bf16 v[58:61], v[176:179], v[184:187], v[58:61]
	v_mfma_f32_16x16x32_bf16 v[46:49], v[168:171], v[192:195], v[46:49]
	v_mfma_f32_16x16x32_bf16 v[34:37], v[176:179], v[192:195], v[34:37]
	v_mfma_f32_16x16x32_bf16 v[30:33], v[168:171], v[200:203], v[30:33]
	v_mfma_f32_16x16x32_bf16 v[18:21], v[176:179], v[200:203], v[18:21]
	v_mfma_f32_16x16x32_bf16 v[14:17], v[168:171], v[208:211], v[14:17]
	v_mfma_f32_16x16x32_bf16 v[10:13], v[176:179], v[208:211], v[10:13]
	v_mfma_f32_16x16x32_bf16 v[78:81], v[172:175], v[188:191], v[78:81]
	v_mfma_f32_16x16x32_bf16 v[58:61], v[180:183], v[188:191], v[58:61]
	v_mfma_f32_16x16x32_bf16 v[46:49], v[172:175], v[196:199], v[46:49]
	v_mfma_f32_16x16x32_bf16 v[34:37], v[180:183], v[196:199], v[34:37]
	v_mfma_f32_16x16x32_bf16 v[30:33], v[172:175], v[204:207], v[30:33]
	v_mfma_f32_16x16x32_bf16 v[18:21], v[180:183], v[204:207], v[18:21]
	v_mfma_f32_16x16x32_bf16 v[14:17], v[172:175], v[212:215], v[14:17]
	v_mfma_f32_16x16x32_bf16 v[10:13], v[180:183], v[212:215], v[10:13]
	s_barrier
; #define PG8_BAR __builtin_amdgcn_s_barrier()
;     ...
;         for (int t = 2; t < nt; t += 2) PG8_KITER(t);
;         if constexpr (ALIGN_EPI) { if (wr == 0) PG8_BAR; }
	s_setprio 0
	ds_read_b128 v[152:155], v134
	ds_read_b128 v[156:159], v134 offset:1024
	ds_read_b128 v[160:163], v134 offset:2048
	ds_read_b128 v[164:167], v134 offset:3072
	ds_read_b128 v[168:171], v144
	ds_read_b128 v[172:175], v144 offset:1024
	s_add_u32 s54, s54, 0x100000
	s_addc_u32 s55, s55, 0
	s_mov_b32 m0, s33
	ds_read_b128 v[180:183], v144 offset:3072
	global_load_lds_dwordx4 v130, s[100:101]
	s_mov_b32 m0, s51
	ds_read_b128 v[176:179], v144 offset:2048
	global_load_lds_dwordx4 v132, s[100:101]
	s_mov_b32 m0, s58
	ds_read_b128 v[184:187], v150 offset:32768
	ds_read_b128 v[188:191], v150 offset:33792
	ds_read_b128 v[192:195], v150 offset:34816
	ds_read_b128 v[196:199], v150 offset:35840
	ds_read_b128 v[200:203], v150 offset:36864
	ds_read_b128 v[204:207], v150 offset:37888
	ds_read_b128 v[208:211], v150 offset:38912
	global_load_lds_dwordx4 v130, s[54:55]
	s_mov_b32 m0, s59
	ds_read_b128 v[212:215], v150 offset:39936
	global_load_lds_dwordx4 v132, s[54:55]
	s_waitcnt vmcnt(8) lgkmcnt(0)
	s_setprio 1
	s_barrier
	v_mfma_f32_16x16x32_bf16 v[118:121], v[152:155], v[184:187], v[118:121]
	v_mfma_f32_16x16x32_bf16 v[114:117], v[160:163], v[184:187], v[114:117]
	v_mfma_f32_16x16x32_bf16 v[102:105], v[152:155], v[192:195], v[102:105]
	v_mfma_f32_16x16x32_bf16 v[98:101], v[160:163], v[192:195], v[98:101]
	v_mfma_f32_16x16x32_bf16 v[86:89], v[152:155], v[200:203], v[86:89]
	v_mfma_f32_16x16x32_bf16 v[82:85], v[160:163], v[200:203], v[82:85]
	v_mfma_f32_16x16x32_bf16 v[74:77], v[152:155], v[208:211], v[74:77]
	v_mfma_f32_16x16x32_bf16 v[54:57], v[160:163], v[208:211], v[54:57]
	v_mfma_f32_16x16x32_bf16 v[118:121], v[156:159], v[188:191], v[118:121]
	v_mfma_f32_16x16x32_bf16 v[114:117], v[164:167], v[188:191], v[114:117]
	v_mfma_f32_16x16x32_bf16 v[102:105], v[156:159], v[196:199], v[102:105]
	v_mfma_f32_16x16x32_bf16 v[98:101], v[164:167], v[196:199], v[98:101]
	v_mfma_f32_16x16x32_bf16 v[86:89], v[156:159], v[204:207], v[86:89]
	v_mfma_f32_16x16x32_bf16 v[82:85], v[164:167], v[204:207], v[82:85]
	v_mfma_f32_16x16x32_bf16 v[74:77], v[156:159], v[212:215], v[74:77]
	v_mfma_f32_16x16x32_bf16 v[54:57], v[164:167], v[212:215], v[54:57]
	s_setprio 0
	s_setprio 1
	v_mfma_f32_16x16x32_bf16 v[126:129], v[168:171], v[184:187], v[126:129]
	v_mfma_f32_16x16x32_bf16 v[122:125], v[176:179], v[184:187], v[122:125]
	v_mfma_f32_16x16x32_bf16 v[110:113], v[168:171], v[192:195], v[110:113]
	v_mfma_f32_16x16x32_bf16 v[106:109], v[176:179], v[192:195], v[106:109]
	v_mfma_f32_16x16x32_bf16 v[94:97], v[168:171], v[200:203], v[94:97]
	v_mfma_f32_16x16x32_bf16 v[90:93], v[176:179], v[200:203], v[90:93]
	v_mfma_f32_16x16x32_bf16 v[70:73], v[168:171], v[208:211], v[70:73]
	v_mfma_f32_16x16x32_bf16 v[50:53], v[176:179], v[208:211], v[50:53]
	v_mfma_f32_16x16x32_bf16 v[126:129], v[172:175], v[188:191], v[126:129]
	v_mfma_f32_16x16x32_bf16 v[122:125], v[180:183], v[188:191], v[122:125]
	v_mfma_f32_16x16x32_bf16 v[110:113], v[172:175], v[196:199], v[110:113]
	v_mfma_f32_16x16x32_bf16 v[106:109], v[180:183], v[196:199], v[106:109]
	v_mfma_f32_16x16x32_bf16 v[94:97], v[172:175], v[204:207], v[94:97]
	v_mfma_f32_16x16x32_bf16 v[90:93], v[180:183], v[204:207], v[90:93]
	v_mfma_f32_16x16x32_bf16 v[70:73], v[172:175], v[212:215], v[70:73]
	v_mfma_f32_16x16x32_bf16 v[50:53], v[180:183], v[212:215], v[50:53]
	s_barrier
	s_setprio 0
	s_mov_b32 m0, s47
	s_add_u32 s98, s98, 0x80
	s_addc_u32 s99, s99, 0
	s_add_u32 s100, s100, 0x80
	s_addc_u32 s101, s101, 0
	s_add_u32 s52, s52, 0x100080
	ds_read_b128 v[184:187], v150 offset:49152
	ds_read_b128 v[188:191], v150 offset:50176
	ds_read_b128 v[192:195], v150 offset:51200
	ds_read_b128 v[196:199], v150 offset:52224
	ds_read_b128 v[200:203], v150 offset:53248
	ds_read_b128 v[204:207], v150 offset:54272
	global_load_lds_dwordx4 v130, s[98:99]
	s_mov_b32 m0, s77
	s_addc_u32 s53, s53, 0
	global_load_lds_dwordx4 v132, s[98:99]
	s_mov_b32 m0, s56
	ds_read_b128 v[212:215], v150 offset:56320
	global_load_lds_dwordx4 v130, s[52:53]
	s_mov_b32 m0, s57
	ds_read_b128 v[208:211], v150 offset:55296
	global_load_lds_dwordx4 v132, s[52:53]
	s_waitcnt vmcnt(6) lgkmcnt(0)
	s_setprio 1
	s_barrier
	v_mfma_f32_16x16x32_bf16 v[66:69], v[152:155], v[184:187], v[66:69]
	v_mfma_f32_16x16x32_bf16 v[62:65], v[160:163], v[184:187], v[62:65]
	v_mfma_f32_16x16x32_bf16 v[42:45], v[152:155], v[192:195], v[42:45]
	v_mfma_f32_16x16x32_bf16 v[38:41], v[160:163], v[192:195], v[38:41]
	v_mfma_f32_16x16x32_bf16 v[26:29], v[152:155], v[200:203], v[26:29]
	v_mfma_f32_16x16x32_bf16 v[22:25], v[160:163], v[200:203], v[22:25]
	v_mfma_f32_16x16x32_bf16 v[6:9], v[152:155], v[208:211], v[6:9]
	v_mfma_f32_16x16x32_bf16 v[2:5], v[160:163], v[208:211], v[2:5]
	v_mfma_f32_16x16x32_bf16 v[66:69], v[156:159], v[188:191], v[66:69]
	v_mfma_f32_16x16x32_bf16 v[62:65], v[164:167], v[188:191], v[62:65]
	v_mfma_f32_16x16x32_bf16 v[42:45], v[156:159], v[196:199], v[42:45]
	v_mfma_f32_16x16x32_bf16 v[38:41], v[164:167], v[196:199], v[38:41]
	v_mfma_f32_16x16x32_bf16 v[26:29], v[156:159], v[204:207], v[26:29]
	v_mfma_f32_16x16x32_bf16 v[22:25], v[164:167], v[204:207], v[22:25]
	v_mfma_f32_16x16x32_bf16 v[6:9], v[156:159], v[212:215], v[6:9]
	v_mfma_f32_16x16x32_bf16 v[2:5], v[164:167], v[212:215], v[2:5]
	s_setprio 0
	s_setprio 1
	v_mfma_f32_16x16x32_bf16 v[78:81], v[168:171], v[184:187], v[78:81]
	v_mfma_f32_16x16x32_bf16 v[58:61], v[176:179], v[184:187], v[58:61]
	v_mfma_f32_16x16x32_bf16 v[46:49], v[168:171], v[192:195], v[46:49]
	v_mfma_f32_16x16x32_bf16 v[34:37], v[176:179], v[192:195], v[34:37]
	v_mfma_f32_16x16x32_bf16 v[30:33], v[168:171], v[200:203], v[30:33]
	v_mfma_f32_16x16x32_bf16 v[18:21], v[176:179], v[200:203], v[18:21]
	v_mfma_f32_16x16x32_bf16 v[14:17], v[168:171], v[208:211], v[14:17]
	v_mfma_f32_16x16x32_bf16 v[10:13], v[176:179], v[208:211], v[10:13]
	v_mfma_f32_16x16x32_bf16 v[78:81], v[172:175], v[188:191], v[78:81]
	v_mfma_f32_16x16x32_bf16 v[58:61], v[180:183], v[188:191], v[58:61]
	v_mfma_f32_16x16x32_bf16 v[46:49], v[172:175], v[196:199], v[46:49]
	v_mfma_f32_16x16x32_bf16 v[34:37], v[180:183], v[196:199], v[34:37]
	v_mfma_f32_16x16x32_bf16 v[30:33], v[172:175], v[204:207], v[30:33]
	v_mfma_f32_16x16x32_bf16 v[18:21], v[180:183], v[204:207], v[18:21]
	v_mfma_f32_16x16x32_bf16 v[14:17], v[172:175], v[212:215], v[14:17]
	v_mfma_f32_16x16x32_bf16 v[10:13], v[180:183], v[212:215], v[10:13]
	s_barrier
	s_setprio 0
	s_add_i32 s26, s26, 2
	s_add_u32 s0, s0, 0x100
	s_addc_u32 s1, s1, 0
	s_add_u32 s14, s14, 0x100
	s_addc_u32 s15, s15, 0
	s_cmp_gt_u32 s26, 29
	s_cbranch_scc0 .LBB0_1110
	s_mov_b32 m0, s61
	s_nop 0
	global_load_lds_dwordx4 v130, s[100:101]
	s_mov_b32 m0, s62
	s_nop 0
	global_load_lds_dwordx4 v132, s[100:101]
	s_and_b64 vcc, exec, s[18:19]
	s_cbranch_vccz .LBB0_1113
	s_barrier

.Lrb2_skip_38305:
	s_mov_b32 m0, s59
	ds_read_b128 v[186:189], v184
	ds_read_b128 v[190:193], v184 offset:1024
	ds_read_b128 v[194:197], v184 offset:2048
	ds_read_b128 v[198:201], v184 offset:3072
	ds_read_b128 v[202:205], v184 offset:4096
	ds_read_b128 v[206:209], v184 offset:5120
	ds_read_b128 v[210:213], v184 offset:6144
	global_load_lds_dwordx4 v162, s[40:41]
	s_mov_b32 m0, s60
	ds_read_b128 v[214:217], v184 offset:7168
	global_load_lds_dwordx4 v164, s[40:41]
	s_waitcnt vmcnt(8) lgkmcnt(0)
	s_setprio 1
	s_barrier
	v_mfma_f32_16x16x32_bf16 v[122:125], v[132:135], v[186:189], v[122:125]
	v_mfma_f32_16x16x32_bf16 v[118:121], v[140:143], v[186:189], v[118:121]
	v_mfma_f32_16x16x32_bf16 v[110:113], v[132:135], v[194:197], v[110:113]
	v_mfma_f32_16x16x32_bf16 v[106:109], v[140:143], v[194:197], v[106:109]
	v_mfma_f32_16x16x32_bf16 v[94:97], v[132:135], v[202:205], v[94:97]
	v_mfma_f32_16x16x32_bf16 v[90:93], v[140:143], v[202:205], v[90:93]
	v_mfma_f32_16x16x32_bf16 v[78:81], v[132:135], v[210:213], v[78:81]
	v_mfma_f32_16x16x32_bf16 v[74:77], v[140:143], v[210:213], v[74:77]
	v_mfma_f32_16x16x32_bf16 v[122:125], v[136:139], v[190:193], v[122:125]
	v_mfma_f32_16x16x32_bf16 v[118:121], v[144:147], v[190:193], v[118:121]
	v_mfma_f32_16x16x32_bf16 v[110:113], v[136:139], v[198:201], v[110:113]
	v_mfma_f32_16x16x32_bf16 v[106:109], v[144:147], v[198:201], v[106:109]
	v_mfma_f32_16x16x32_bf16 v[94:97], v[136:139], v[206:209], v[94:97]
	v_mfma_f32_16x16x32_bf16 v[90:93], v[144:147], v[206:209], v[90:93]
	v_mfma_f32_16x16x32_bf16 v[78:81], v[136:139], v[214:217], v[78:81]
	v_mfma_f32_16x16x32_bf16 v[74:77], v[144:147], v[214:217], v[74:77]
	s_setprio 0
	s_setprio 1
	v_mfma_f32_16x16x32_bf16 v[126:129], v[148:151], v[186:189], v[126:129]
	v_mfma_f32_16x16x32_bf16 v[114:117], v[174:177], v[186:189], v[114:117]
	v_mfma_f32_16x16x32_bf16 v[102:105], v[148:151], v[194:197], v[102:105]
	v_mfma_f32_16x16x32_bf16 v[98:101], v[174:177], v[194:197], v[98:101]
	v_mfma_f32_16x16x32_bf16 v[86:89], v[148:151], v[202:205], v[86:89]
	v_mfma_f32_16x16x32_bf16 v[82:85], v[174:177], v[202:205], v[82:85]
	v_mfma_f32_16x16x32_bf16 v[70:73], v[148:151], v[210:213], v[70:73]
	v_mfma_f32_16x16x32_bf16 v[66:69], v[174:177], v[210:213], v[66:69]
	v_mfma_f32_16x16x32_bf16 v[126:129], v[170:173], v[190:193], v[126:129]
	v_mfma_f32_16x16x32_bf16 v[114:117], v[178:181], v[190:193], v[114:117]
	v_mfma_f32_16x16x32_bf16 v[102:105], v[170:173], v[198:201], v[102:105]
	v_mfma_f32_16x16x32_bf16 v[98:101], v[178:181], v[198:201], v[98:101]
	v_mfma_f32_16x16x32_bf16 v[86:89], v[170:173], v[206:209], v[86:89]
	v_mfma_f32_16x16x32_bf16 v[82:85], v[178:181], v[206:209], v[82:85]
	v_mfma_f32_16x16x32_bf16 v[70:73], v[170:173], v[214:217], v[70:73]
	v_mfma_f32_16x16x32_bf16 v[66:69], v[178:181], v[214:217], v[66:69]
	s_barrier
	s_setprio 0
	s_mov_b32 m0, s61
	s_mov_b64 s[98:99], s[38:39]
	s_add_u32 s70, s38, 0x20000
	ds_read_b128 v[186:189], v184 offset:16384
	ds_read_b128 v[190:193], v184 offset:17408
	ds_read_b128 v[194:197], v184 offset:18432
	ds_read_b128 v[198:201], v184 offset:19456
	ds_read_b128 v[202:205], v184 offset:20480
	ds_read_b128 v[206:209], v184 offset:21504
	ds_read_b128 v[210:213], v184 offset:22528
	global_load_lds_dwordx4 v156, s[38:39]
	s_mov_b32 m0, s62
	s_addc_u32 s71, s39, 0
	global_load_lds_dwordx4 v160, s[38:39]
	s_mov_b32 m0, s67
	s_mov_b64 s[100:101], s[42:43]
	global_load_lds_dwordx4 v156, s[70:71]
	s_mov_b32 m0, s46
	ds_read_b128 v[214:217], v184 offset:23552
	global_load_lds_dwordx4 v160, s[70:71]
	s_waitcnt vmcnt(6) lgkmcnt(0)
	s_setprio 1
	s_barrier
	v_mfma_f32_16x16x32_bf16 v[58:61], v[132:135], v[186:189], v[58:61]
	v_mfma_f32_16x16x32_bf16 v[54:57], v[140:143], v[186:189], v[54:57]
	v_mfma_f32_16x16x32_bf16 v[46:49], v[132:135], v[194:197], v[46:49]
	v_mfma_f32_16x16x32_bf16 v[42:45], v[140:143], v[194:197], v[42:45]
	v_mfma_f32_16x16x32_bf16 v[30:33], v[132:135], v[202:205], v[30:33]
	v_mfma_f32_16x16x32_bf16 v[26:29], v[140:143], v[202:205], v[26:29]
	v_mfma_f32_16x16x32_bf16 v[14:17], v[132:135], v[210:213], v[14:17]
	v_mfma_f32_16x16x32_bf16 v[10:13], v[140:143], v[210:213], v[10:13]
	v_mfma_f32_16x16x32_bf16 v[58:61], v[136:139], v[190:193], v[58:61]
	v_mfma_f32_16x16x32_bf16 v[54:57], v[144:147], v[190:193], v[54:57]
	v_mfma_f32_16x16x32_bf16 v[46:49], v[136:139], v[198:201], v[46:49]
	v_mfma_f32_16x16x32_bf16 v[42:45], v[144:147], v[198:201], v[42:45]
	v_mfma_f32_16x16x32_bf16 v[30:33], v[136:139], v[206:209], v[30:33]
	v_mfma_f32_16x16x32_bf16 v[26:29], v[144:147], v[206:209], v[26:29]
	v_mfma_f32_16x16x32_bf16 v[14:17], v[136:139], v[214:217], v[14:17]
	v_mfma_f32_16x16x32_bf16 v[10:13], v[144:147], v[214:217], v[10:13]
	s_setprio 0
	s_setprio 1
	v_mfma_f32_16x16x32_bf16 v[62:65], v[148:151], v[186:189], v[62:65]
	v_mfma_f32_16x16x32_bf16 v[50:53], v[174:177], v[186:189], v[50:53]
	v_mfma_f32_16x16x32_bf16 v[38:41], v[148:151], v[194:197], v[38:41]
	v_mfma_f32_16x16x32_bf16 v[34:37], v[174:177], v[194:197], v[34:37]
	v_mfma_f32_16x16x32_bf16 v[22:25], v[148:151], v[202:205], v[22:25]
	v_mfma_f32_16x16x32_bf16 v[18:21], v[174:177], v[202:205], v[18:21]
	v_mfma_f32_16x16x32_bf16 v[6:9], v[148:151], v[210:213], v[6:9]
	v_mfma_f32_16x16x32_bf16 v[2:5], v[174:177], v[210:213], v[2:5]
	v_mfma_f32_16x16x32_bf16 v[62:65], v[170:173], v[190:193], v[62:65]
	v_mfma_f32_16x16x32_bf16 v[50:53], v[178:181], v[190:193], v[50:53]
	v_mfma_f32_16x16x32_bf16 v[38:41], v[170:173], v[198:201], v[38:41]
	v_mfma_f32_16x16x32_bf16 v[34:37], v[178:181], v[198:201], v[34:37]
	v_mfma_f32_16x16x32_bf16 v[22:25], v[170:173], v[206:209], v[22:25]
	v_mfma_f32_16x16x32_bf16 v[18:21], v[178:181], v[206:209], v[18:21]
	v_mfma_f32_16x16x32_bf16 v[6:9], v[170:173], v[214:217], v[6:9]
	v_mfma_f32_16x16x32_bf16 v[2:5], v[178:181], v[214:217], v[2:5]
	s_barrier
; #define PG8_BAR __builtin_amdgcn_s_barrier()
;     ...
;         for (int t = 2; t < nt; t += 2) PG8_KITER(t);
;         if constexpr (ALIGN_EPI) { if (wr == 0) PG8_BAR; }
	s_setprio 0
	ds_read_b128 v[132:135], v130
	ds_read_b128 v[136:139], v130 offset:1024
	ds_read_b128 v[140:143], v130 offset:2048
	ds_read_b128 v[144:147], v130 offset:3072
	ds_read_b128 v[148:151], v131
	ds_read_b128 v[170:173], v131 offset:1024
	s_add_u32 s42, s42, 0x20000
	s_addc_u32 s43, s43, 0
	s_mov_b32 m0, s48
	ds_read_b128 v[178:181], v131 offset:3072
	global_load_lds_dwordx4 v154, s[100:101]
	s_mov_b32 m0, s49
	ds_read_b128 v[174:177], v131 offset:2048
	global_load_lds_dwordx4 v158, s[100:101]
	s_mov_b32 m0, s50
	ds_read_b128 v[186:189], v184 offset:32768
	ds_read_b128 v[190:193], v184 offset:33792
	ds_read_b128 v[194:197], v184 offset:34816
	ds_read_b128 v[198:201], v184 offset:35840
	ds_read_b128 v[202:205], v184 offset:36864
	ds_read_b128 v[206:209], v184 offset:37888
	ds_read_b128 v[210:213], v184 offset:38912
	global_load_lds_dwordx4 v154, s[42:43]
	s_mov_b32 m0, s51
	ds_read_b128 v[214:217], v184 offset:39936
	global_load_lds_dwordx4 v158, s[42:43]
	s_waitcnt vmcnt(8) lgkmcnt(0)
	s_setprio 1
	s_barrier
	v_mfma_f32_16x16x32_bf16 v[122:125], v[132:135], v[186:189], v[122:125]
	v_mfma_f32_16x16x32_bf16 v[118:121], v[140:143], v[186:189], v[118:121]
	v_mfma_f32_16x16x32_bf16 v[110:113], v[132:135], v[194:197], v[110:113]
	v_mfma_f32_16x16x32_bf16 v[106:109], v[140:143], v[194:197], v[106:109]
	v_mfma_f32_16x16x32_bf16 v[94:97], v[132:135], v[202:205], v[94:97]
	v_mfma_f32_16x16x32_bf16 v[90:93], v[140:143], v[202:205], v[90:93]
	v_mfma_f32_16x16x32_bf16 v[78:81], v[132:135], v[210:213], v[78:81]
	v_mfma_f32_16x16x32_bf16 v[74:77], v[140:143], v[210:213], v[74:77]
	v_mfma_f32_16x16x32_bf16 v[122:125], v[136:139], v[190:193], v[122:125]
	v_mfma_f32_16x16x32_bf16 v[118:121], v[144:147], v[190:193], v[118:121]
	v_mfma_f32_16x16x32_bf16 v[110:113], v[136:139], v[198:201], v[110:113]
	v_mfma_f32_16x16x32_bf16 v[106:109], v[144:147], v[198:201], v[106:109]
	v_mfma_f32_16x16x32_bf16 v[94:97], v[136:139], v[206:209], v[94:97]
	v_mfma_f32_16x16x32_bf16 v[90:93], v[144:147], v[206:209], v[90:93]
	v_mfma_f32_16x16x32_bf16 v[78:81], v[136:139], v[214:217], v[78:81]
	v_mfma_f32_16x16x32_bf16 v[74:77], v[144:147], v[214:217], v[74:77]
	s_setprio 0
	s_setprio 1
	v_mfma_f32_16x16x32_bf16 v[126:129], v[148:151], v[186:189], v[126:129]
	v_mfma_f32_16x16x32_bf16 v[114:117], v[174:177], v[186:189], v[114:117]
	v_mfma_f32_16x16x32_bf16 v[102:105], v[148:151], v[194:197], v[102:105]
	v_mfma_f32_16x16x32_bf16 v[98:101], v[174:177], v[194:197], v[98:101]
	v_mfma_f32_16x16x32_bf16 v[86:89], v[148:151], v[202:205], v[86:89]
	v_mfma_f32_16x16x32_bf16 v[82:85], v[174:177], v[202:205], v[82:85]
	v_mfma_f32_16x16x32_bf16 v[70:73], v[148:151], v[210:213], v[70:73]
	v_mfma_f32_16x16x32_bf16 v[66:69], v[174:177], v[210:213], v[66:69]
	v_mfma_f32_16x16x32_bf16 v[126:129], v[170:173], v[190:193], v[126:129]
	v_mfma_f32_16x16x32_bf16 v[114:117], v[178:181], v[190:193], v[114:117]
	v_mfma_f32_16x16x32_bf16 v[102:105], v[170:173], v[198:201], v[102:105]
	v_mfma_f32_16x16x32_bf16 v[98:101], v[178:181], v[198:201], v[98:101]
	v_mfma_f32_16x16x32_bf16 v[86:89], v[170:173], v[206:209], v[86:89]
	v_mfma_f32_16x16x32_bf16 v[82:85], v[178:181], v[206:209], v[82:85]
	v_mfma_f32_16x16x32_bf16 v[70:73], v[170:173], v[214:217], v[70:73]
	v_mfma_f32_16x16x32_bf16 v[66:69], v[178:181], v[214:217], v[66:69]
	s_barrier
	s_setprio 0
	s_mov_b32 m0, s47
	s_add_u32 s98, s98, 0x80
	s_addc_u32 s99, s99, 0
	s_add_u32 s100, s100, 0x80
	s_addc_u32 s101, s101, 0
	s_add_u32 s38, s38, 0x20080
	ds_read_b128 v[186:189], v184 offset:49152
	ds_read_b128 v[190:193], v184 offset:50176
	ds_read_b128 v[194:197], v184 offset:51200
	ds_read_b128 v[198:201], v184 offset:52224
	ds_read_b128 v[202:205], v184 offset:53248
	ds_read_b128 v[206:209], v184 offset:54272
	global_load_lds_dwordx4 v156, s[98:99]
	s_mov_b32 m0, s68
	s_addc_u32 s39, s39, 0
	global_load_lds_dwordx4 v160, s[98:99]
	s_mov_b32 m0, s56
	ds_read_b128 v[214:217], v184 offset:56320
	global_load_lds_dwordx4 v156, s[38:39]
	s_mov_b32 m0, s57
	ds_read_b128 v[210:213], v184 offset:55296
	global_load_lds_dwordx4 v160, s[38:39]
	s_waitcnt vmcnt(6) lgkmcnt(0)
	s_setprio 1
	s_barrier
	v_mfma_f32_16x16x32_bf16 v[58:61], v[132:135], v[186:189], v[58:61]
	v_mfma_f32_16x16x32_bf16 v[54:57], v[140:143], v[186:189], v[54:57]
	v_mfma_f32_16x16x32_bf16 v[46:49], v[132:135], v[194:197], v[46:49]
	v_mfma_f32_16x16x32_bf16 v[42:45], v[140:143], v[194:197], v[42:45]
	v_mfma_f32_16x16x32_bf16 v[30:33], v[132:135], v[202:205], v[30:33]
	v_mfma_f32_16x16x32_bf16 v[26:29], v[140:143], v[202:205], v[26:29]
	v_mfma_f32_16x16x32_bf16 v[14:17], v[132:135], v[210:213], v[14:17]
	v_mfma_f32_16x16x32_bf16 v[10:13], v[140:143], v[210:213], v[10:13]
	v_mfma_f32_16x16x32_bf16 v[58:61], v[136:139], v[190:193], v[58:61]
	v_mfma_f32_16x16x32_bf16 v[54:57], v[144:147], v[190:193], v[54:57]
	v_mfma_f32_16x16x32_bf16 v[46:49], v[136:139], v[198:201], v[46:49]
	v_mfma_f32_16x16x32_bf16 v[42:45], v[144:147], v[198:201], v[42:45]
	v_mfma_f32_16x16x32_bf16 v[30:33], v[136:139], v[206:209], v[30:33]
	v_mfma_f32_16x16x32_bf16 v[26:29], v[144:147], v[206:209], v[26:29]
	v_mfma_f32_16x16x32_bf16 v[14:17], v[136:139], v[214:217], v[14:17]
	v_mfma_f32_16x16x32_bf16 v[10:13], v[144:147], v[214:217], v[10:13]
	s_setprio 0
	s_setprio 1
	v_mfma_f32_16x16x32_bf16 v[62:65], v[148:151], v[186:189], v[62:65]
	v_mfma_f32_16x16x32_bf16 v[50:53], v[174:177], v[186:189], v[50:53]
	v_mfma_f32_16x16x32_bf16 v[38:41], v[148:151], v[194:197], v[38:41]
	v_mfma_f32_16x16x32_bf16 v[34:37], v[174:177], v[194:197], v[34:37]
	v_mfma_f32_16x16x32_bf16 v[22:25], v[148:151], v[202:205], v[22:25]
	v_mfma_f32_16x16x32_bf16 v[18:21], v[174:177], v[202:205], v[18:21]
	v_mfma_f32_16x16x32_bf16 v[6:9], v[148:151], v[210:213], v[6:9]
	v_mfma_f32_16x16x32_bf16 v[2:5], v[174:177], v[210:213], v[2:5]
	v_mfma_f32_16x16x32_bf16 v[62:65], v[170:173], v[190:193], v[62:65]
	v_mfma_f32_16x16x32_bf16 v[50:53], v[178:181], v[190:193], v[50:53]
	v_mfma_f32_16x16x32_bf16 v[38:41], v[170:173], v[198:201], v[38:41]
	v_mfma_f32_16x16x32_bf16 v[34:37], v[178:181], v[198:201], v[34:37]
	v_mfma_f32_16x16x32_bf16 v[22:25], v[170:173], v[206:209], v[22:25]
	v_mfma_f32_16x16x32_bf16 v[18:21], v[178:181], v[206:209], v[18:21]
	v_mfma_f32_16x16x32_bf16 v[6:9], v[170:173], v[214:217], v[6:9]
	v_mfma_f32_16x16x32_bf16 v[2:5], v[178:181], v[214:217], v[2:5]
	s_barrier
	s_setprio 0
	s_add_i32 s69, s69, 2
	s_add_u32 s40, s40, 0x100
	s_addc_u32 s41, s41, 0
	s_add_u32 s26, s26, 0x100
	s_addc_u32 s27, s27, 0
	s_cmp_gt_u32 s69, 5
	s_cbranch_scc0 .LBB0_1261
	s_mov_b32 m0, s52
	s_nop 0
	global_load_lds_dwordx4 v154, s[100:101]
	s_mov_b32 m0, s53
	s_nop 0
	global_load_lds_dwordx4 v158, s[100:101]
	s_and_b64 vcc, exec, s[16:17]
	s_cbranch_vccz .LBB0_1264
	s_barrier

.Lrb2_skip_40588:
	s_mov_b32 m0, s53
	ds_read_b128 v[188:191], v152
	ds_read_b128 v[192:195], v152 offset:1024
	ds_read_b128 v[196:199], v152 offset:2048
	ds_read_b128 v[200:203], v152 offset:3072
	ds_read_b128 v[204:207], v152 offset:4096
	ds_read_b128 v[208:211], v152 offset:5120
	ds_read_b128 v[212:215], v152 offset:6144
	global_load_lds_dwordx4 v0, s[40:41]
	s_mov_b32 m0, s54
	ds_read_b128 v[216:219], v152 offset:7168
	global_load_lds_dwordx4 v140, s[40:41]
	s_waitcnt vmcnt(8) lgkmcnt(0)
	s_setprio 1
	s_barrier
	v_mfma_f32_16x16x32_bf16 v[118:121], v[156:159], v[188:191], v[118:121]
	v_mfma_f32_16x16x32_bf16 v[114:117], v[164:167], v[188:191], v[114:117]
	v_mfma_f32_16x16x32_bf16 v[102:105], v[156:159], v[196:199], v[102:105]
	v_mfma_f32_16x16x32_bf16 v[98:101], v[164:167], v[196:199], v[98:101]
	v_mfma_f32_16x16x32_bf16 v[86:89], v[156:159], v[204:207], v[86:89]
	v_mfma_f32_16x16x32_bf16 v[82:85], v[164:167], v[204:207], v[82:85]
	v_mfma_f32_16x16x32_bf16 v[66:69], v[156:159], v[212:215], v[66:69]
	v_mfma_f32_16x16x32_bf16 v[62:65], v[164:167], v[212:215], v[62:65]
	v_mfma_f32_16x16x32_bf16 v[118:121], v[160:163], v[192:195], v[118:121]
	v_mfma_f32_16x16x32_bf16 v[114:117], v[168:171], v[192:195], v[114:117]
	v_mfma_f32_16x16x32_bf16 v[102:105], v[160:163], v[200:203], v[102:105]
	v_mfma_f32_16x16x32_bf16 v[98:101], v[168:171], v[200:203], v[98:101]
	v_mfma_f32_16x16x32_bf16 v[86:89], v[160:163], v[208:211], v[86:89]
	v_mfma_f32_16x16x32_bf16 v[82:85], v[168:171], v[208:211], v[82:85]
	v_mfma_f32_16x16x32_bf16 v[66:69], v[160:163], v[216:219], v[66:69]
	v_mfma_f32_16x16x32_bf16 v[62:65], v[168:171], v[216:219], v[62:65]
	s_setprio 0
	s_setprio 1
	v_mfma_f32_16x16x32_bf16 v[126:129], v[172:175], v[188:191], v[126:129]
	v_mfma_f32_16x16x32_bf16 v[122:125], v[180:183], v[188:191], v[122:125]
	v_mfma_f32_16x16x32_bf16 v[110:113], v[172:175], v[196:199], v[110:113]
	v_mfma_f32_16x16x32_bf16 v[106:109], v[180:183], v[196:199], v[106:109]
	v_mfma_f32_16x16x32_bf16 v[94:97], v[172:175], v[204:207], v[94:97]
	v_mfma_f32_16x16x32_bf16 v[90:93], v[180:183], v[204:207], v[90:93]
	v_mfma_f32_16x16x32_bf16 v[78:81], v[172:175], v[212:215], v[78:81]
	v_mfma_f32_16x16x32_bf16 v[74:77], v[180:183], v[212:215], v[74:77]
	v_mfma_f32_16x16x32_bf16 v[126:129], v[176:179], v[192:195], v[126:129]
	v_mfma_f32_16x16x32_bf16 v[122:125], v[184:187], v[192:195], v[122:125]
	v_mfma_f32_16x16x32_bf16 v[110:113], v[176:179], v[200:203], v[110:113]
	v_mfma_f32_16x16x32_bf16 v[106:109], v[184:187], v[200:203], v[106:109]
	v_mfma_f32_16x16x32_bf16 v[94:97], v[176:179], v[208:211], v[94:97]
	v_mfma_f32_16x16x32_bf16 v[90:93], v[184:187], v[208:211], v[90:93]
	v_mfma_f32_16x16x32_bf16 v[78:81], v[176:179], v[216:219], v[78:81]
	v_mfma_f32_16x16x32_bf16 v[74:77], v[184:187], v[216:219], v[74:77]
	s_barrier
	s_setprio 0
	s_mov_b32 m0, s59
	s_mov_b64 s[98:99], s[38:39]
	s_add_u32 s70, s38, 0x100000
	ds_read_b128 v[188:191], v152 offset:16384
	ds_read_b128 v[192:195], v152 offset:17408
	ds_read_b128 v[196:199], v152 offset:18432
	ds_read_b128 v[200:203], v152 offset:19456
	ds_read_b128 v[204:207], v152 offset:20480
	ds_read_b128 v[208:211], v152 offset:21504
	ds_read_b128 v[212:215], v152 offset:22528
	global_load_lds_dwordx4 v134, s[38:39]
	s_mov_b32 m0, s60
	s_addc_u32 s71, s39, 0
	global_load_lds_dwordx4 v130, s[38:39]
	s_mov_b32 m0, s61
	s_mov_b64 s[100:101], s[42:43]
	global_load_lds_dwordx4 v134, s[70:71]
	s_mov_b32 m0, s62
	ds_read_b128 v[216:219], v152 offset:23552
	global_load_lds_dwordx4 v130, s[70:71]
	s_waitcnt vmcnt(6) lgkmcnt(0)
	s_setprio 1
	s_barrier
	v_mfma_f32_16x16x32_bf16 v[54:57], v[156:159], v[188:191], v[54:57]
	v_mfma_f32_16x16x32_bf16 v[50:53], v[164:167], v[188:191], v[50:53]
	v_mfma_f32_16x16x32_bf16 v[38:41], v[156:159], v[196:199], v[38:41]
	v_mfma_f32_16x16x32_bf16 v[34:37], v[164:167], v[196:199], v[34:37]
	v_mfma_f32_16x16x32_bf16 v[22:25], v[156:159], v[204:207], v[22:25]
	v_mfma_f32_16x16x32_bf16 v[18:21], v[164:167], v[204:207], v[18:21]
	v_mfma_f32_16x16x32_bf16 v[6:9], v[156:159], v[212:215], v[6:9]
	v_mfma_f32_16x16x32_bf16 v[2:5], v[164:167], v[212:215], v[2:5]
	v_mfma_f32_16x16x32_bf16 v[54:57], v[160:163], v[192:195], v[54:57]
	v_mfma_f32_16x16x32_bf16 v[50:53], v[168:171], v[192:195], v[50:53]
	v_mfma_f32_16x16x32_bf16 v[38:41], v[160:163], v[200:203], v[38:41]
	v_mfma_f32_16x16x32_bf16 v[34:37], v[168:171], v[200:203], v[34:37]
	v_mfma_f32_16x16x32_bf16 v[22:25], v[160:163], v[208:211], v[22:25]
	v_mfma_f32_16x16x32_bf16 v[18:21], v[168:171], v[208:211], v[18:21]
	v_mfma_f32_16x16x32_bf16 v[6:9], v[160:163], v[216:219], v[6:9]
	v_mfma_f32_16x16x32_bf16 v[2:5], v[168:171], v[216:219], v[2:5]
	s_setprio 0
	s_setprio 1
	v_mfma_f32_16x16x32_bf16 v[70:73], v[172:175], v[188:191], v[70:73]
	v_mfma_f32_16x16x32_bf16 v[58:61], v[180:183], v[188:191], v[58:61]
	v_mfma_f32_16x16x32_bf16 v[46:49], v[172:175], v[196:199], v[46:49]
	v_mfma_f32_16x16x32_bf16 v[42:45], v[180:183], v[196:199], v[42:45]
	v_mfma_f32_16x16x32_bf16 v[30:33], v[172:175], v[204:207], v[30:33]
	v_mfma_f32_16x16x32_bf16 v[26:29], v[180:183], v[204:207], v[26:29]
	v_mfma_f32_16x16x32_bf16 v[14:17], v[172:175], v[212:215], v[14:17]
	v_mfma_f32_16x16x32_bf16 v[10:13], v[180:183], v[212:215], v[10:13]
	v_mfma_f32_16x16x32_bf16 v[70:73], v[176:179], v[192:195], v[70:73]
	v_mfma_f32_16x16x32_bf16 v[58:61], v[184:187], v[192:195], v[58:61]
	v_mfma_f32_16x16x32_bf16 v[46:49], v[176:179], v[200:203], v[46:49]
	v_mfma_f32_16x16x32_bf16 v[42:45], v[184:187], v[200:203], v[42:45]
	v_mfma_f32_16x16x32_bf16 v[30:33], v[176:179], v[208:211], v[30:33]
	v_mfma_f32_16x16x32_bf16 v[26:29], v[184:187], v[208:211], v[26:29]
	v_mfma_f32_16x16x32_bf16 v[14:17], v[176:179], v[216:219], v[14:17]
	v_mfma_f32_16x16x32_bf16 v[10:13], v[184:187], v[216:219], v[10:13]
	s_barrier
; #define PG8_BAR __builtin_amdgcn_s_barrier()
;     ...
;         for (int t = 2; t < nt; t += 2) PG8_KITER(t);
;         if constexpr (ALIGN_EPI) { if (wr == 0) PG8_BAR; }
	s_setprio 0
	ds_read_b128 v[156:159], v154
	ds_read_b128 v[160:163], v154 offset:1024
	ds_read_b128 v[164:167], v154 offset:2048
	ds_read_b128 v[168:171], v154 offset:3072
	ds_read_b128 v[172:175], v146
	ds_read_b128 v[176:179], v146 offset:1024
	s_add_u32 s42, s42, 0x100000
	s_addc_u32 s43, s43, 0
	s_mov_b32 m0, s13
	ds_read_b128 v[184:187], v146 offset:3072
	global_load_lds_dwordx4 v136, s[100:101]
	s_mov_b32 m0, s33
	ds_read_b128 v[180:183], v146 offset:2048
	global_load_lds_dwordx4 v132, s[100:101]
	s_mov_b32 m0, s48
	ds_read_b128 v[188:191], v152 offset:32768
	ds_read_b128 v[192:195], v152 offset:33792
	ds_read_b128 v[196:199], v152 offset:34816
	ds_read_b128 v[200:203], v152 offset:35840
	ds_read_b128 v[204:207], v152 offset:36864
	ds_read_b128 v[208:211], v152 offset:37888
	ds_read_b128 v[212:215], v152 offset:38912
	global_load_lds_dwordx4 v136, s[42:43]
	s_mov_b32 m0, s49
	ds_read_b128 v[216:219], v152 offset:39936
	global_load_lds_dwordx4 v132, s[42:43]
	s_waitcnt vmcnt(8) lgkmcnt(0)
	s_setprio 1
	s_barrier
	v_mfma_f32_16x16x32_bf16 v[118:121], v[156:159], v[188:191], v[118:121]
	v_mfma_f32_16x16x32_bf16 v[114:117], v[164:167], v[188:191], v[114:117]
	v_mfma_f32_16x16x32_bf16 v[102:105], v[156:159], v[196:199], v[102:105]
	v_mfma_f32_16x16x32_bf16 v[98:101], v[164:167], v[196:199], v[98:101]
	v_mfma_f32_16x16x32_bf16 v[86:89], v[156:159], v[204:207], v[86:89]
	v_mfma_f32_16x16x32_bf16 v[82:85], v[164:167], v[204:207], v[82:85]
	v_mfma_f32_16x16x32_bf16 v[66:69], v[156:159], v[212:215], v[66:69]
	v_mfma_f32_16x16x32_bf16 v[62:65], v[164:167], v[212:215], v[62:65]
	v_mfma_f32_16x16x32_bf16 v[118:121], v[160:163], v[192:195], v[118:121]
	v_mfma_f32_16x16x32_bf16 v[114:117], v[168:171], v[192:195], v[114:117]
	v_mfma_f32_16x16x32_bf16 v[102:105], v[160:163], v[200:203], v[102:105]
	v_mfma_f32_16x16x32_bf16 v[98:101], v[168:171], v[200:203], v[98:101]
	v_mfma_f32_16x16x32_bf16 v[86:89], v[160:163], v[208:211], v[86:89]
	v_mfma_f32_16x16x32_bf16 v[82:85], v[168:171], v[208:211], v[82:85]
	v_mfma_f32_16x16x32_bf16 v[66:69], v[160:163], v[216:219], v[66:69]
	v_mfma_f32_16x16x32_bf16 v[62:65], v[168:171], v[216:219], v[62:65]
	s_setprio 0
	s_setprio 1
	v_mfma_f32_16x16x32_bf16 v[126:129], v[172:175], v[188:191], v[126:129]
	v_mfma_f32_16x16x32_bf16 v[122:125], v[180:183], v[188:191], v[122:125]
	v_mfma_f32_16x16x32_bf16 v[110:113], v[172:175], v[196:199], v[110:113]
	v_mfma_f32_16x16x32_bf16 v[106:109], v[180:183], v[196:199], v[106:109]
	v_mfma_f32_16x16x32_bf16 v[94:97], v[172:175], v[204:207], v[94:97]
	v_mfma_f32_16x16x32_bf16 v[90:93], v[180:183], v[204:207], v[90:93]
	v_mfma_f32_16x16x32_bf16 v[78:81], v[172:175], v[212:215], v[78:81]
	v_mfma_f32_16x16x32_bf16 v[74:77], v[180:183], v[212:215], v[74:77]
	v_mfma_f32_16x16x32_bf16 v[126:129], v[176:179], v[192:195], v[126:129]
	v_mfma_f32_16x16x32_bf16 v[122:125], v[184:187], v[192:195], v[122:125]
	v_mfma_f32_16x16x32_bf16 v[110:113], v[176:179], v[200:203], v[110:113]
	v_mfma_f32_16x16x32_bf16 v[106:109], v[184:187], v[200:203], v[106:109]
	v_mfma_f32_16x16x32_bf16 v[94:97], v[176:179], v[208:211], v[94:97]
	v_mfma_f32_16x16x32_bf16 v[90:93], v[184:187], v[208:211], v[90:93]
	v_mfma_f32_16x16x32_bf16 v[78:81], v[176:179], v[216:219], v[78:81]
	v_mfma_f32_16x16x32_bf16 v[74:77], v[184:187], v[216:219], v[74:77]
	s_barrier
	s_setprio 0
	s_mov_b32 m0, s46
	s_add_u32 s98, s98, 0x80
	s_addc_u32 s99, s99, 0
	s_add_u32 s100, s100, 0x80
	s_addc_u32 s101, s101, 0
	s_add_u32 s38, s38, 0x100080
	ds_read_b128 v[188:191], v152 offset:49152
	ds_read_b128 v[192:195], v152 offset:50176
	ds_read_b128 v[196:199], v152 offset:51200
	ds_read_b128 v[200:203], v152 offset:52224
	ds_read_b128 v[204:207], v152 offset:53248
	ds_read_b128 v[208:211], v152 offset:54272
	global_load_lds_dwordx4 v134, s[98:99]
	s_mov_b32 m0, s47
	s_addc_u32 s39, s39, 0
	global_load_lds_dwordx4 v130, s[98:99]
	s_mov_b32 m0, s56
	ds_read_b128 v[216:219], v152 offset:56320
	global_load_lds_dwordx4 v134, s[38:39]
	s_mov_b32 m0, s57
	ds_read_b128 v[212:215], v152 offset:55296
	global_load_lds_dwordx4 v130, s[38:39]
	s_waitcnt vmcnt(6) lgkmcnt(0)
	s_setprio 1
	s_barrier
	v_mfma_f32_16x16x32_bf16 v[54:57], v[156:159], v[188:191], v[54:57]
	v_mfma_f32_16x16x32_bf16 v[50:53], v[164:167], v[188:191], v[50:53]
	v_mfma_f32_16x16x32_bf16 v[38:41], v[156:159], v[196:199], v[38:41]
	v_mfma_f32_16x16x32_bf16 v[34:37], v[164:167], v[196:199], v[34:37]
	v_mfma_f32_16x16x32_bf16 v[22:25], v[156:159], v[204:207], v[22:25]
	v_mfma_f32_16x16x32_bf16 v[18:21], v[164:167], v[204:207], v[18:21]
	v_mfma_f32_16x16x32_bf16 v[6:9], v[156:159], v[212:215], v[6:9]
	v_mfma_f32_16x16x32_bf16 v[2:5], v[164:167], v[212:215], v[2:5]
	v_mfma_f32_16x16x32_bf16 v[54:57], v[160:163], v[192:195], v[54:57]
	v_mfma_f32_16x16x32_bf16 v[50:53], v[168:171], v[192:195], v[50:53]
	v_mfma_f32_16x16x32_bf16 v[38:41], v[160:163], v[200:203], v[38:41]
	v_mfma_f32_16x16x32_bf16 v[34:37], v[168:171], v[200:203], v[34:37]
	v_mfma_f32_16x16x32_bf16 v[22:25], v[160:163], v[208:211], v[22:25]
	v_mfma_f32_16x16x32_bf16 v[18:21], v[168:171], v[208:211], v[18:21]
	v_mfma_f32_16x16x32_bf16 v[6:9], v[160:163], v[216:219], v[6:9]
	v_mfma_f32_16x16x32_bf16 v[2:5], v[168:171], v[216:219], v[2:5]
	s_setprio 0
	s_setprio 1
	v_mfma_f32_16x16x32_bf16 v[70:73], v[172:175], v[188:191], v[70:73]
	v_mfma_f32_16x16x32_bf16 v[58:61], v[180:183], v[188:191], v[58:61]
	v_mfma_f32_16x16x32_bf16 v[46:49], v[172:175], v[196:199], v[46:49]
	v_mfma_f32_16x16x32_bf16 v[42:45], v[180:183], v[196:199], v[42:45]
	v_mfma_f32_16x16x32_bf16 v[30:33], v[172:175], v[204:207], v[30:33]
	v_mfma_f32_16x16x32_bf16 v[26:29], v[180:183], v[204:207], v[26:29]
	v_mfma_f32_16x16x32_bf16 v[14:17], v[172:175], v[212:215], v[14:17]
	v_mfma_f32_16x16x32_bf16 v[10:13], v[180:183], v[212:215], v[10:13]
	v_mfma_f32_16x16x32_bf16 v[70:73], v[176:179], v[192:195], v[70:73]
	v_mfma_f32_16x16x32_bf16 v[58:61], v[184:187], v[192:195], v[58:61]
	v_mfma_f32_16x16x32_bf16 v[46:49], v[176:179], v[200:203], v[46:49]
	v_mfma_f32_16x16x32_bf16 v[42:45], v[184:187], v[200:203], v[42:45]
	v_mfma_f32_16x16x32_bf16 v[30:33], v[176:179], v[208:211], v[30:33]
	v_mfma_f32_16x16x32_bf16 v[26:29], v[184:187], v[208:211], v[26:29]
	v_mfma_f32_16x16x32_bf16 v[14:17], v[176:179], v[216:219], v[14:17]
	v_mfma_f32_16x16x32_bf16 v[10:13], v[184:187], v[216:219], v[10:13]
	s_barrier
	s_setprio 0
	s_add_i32 s68, s68, 2
	s_add_u32 s40, s40, 0x100
	s_addc_u32 s41, s41, 0
	s_add_u32 s26, s26, 0x100
	s_addc_u32 s27, s27, 0
	s_cmp_gt_u32 s68, 61
	s_cbranch_scc0 .LBB0_1345
	s_mov_b32 m0, s50
	s_nop 0
	global_load_lds_dwordx4 v136, s[100:101]
	s_mov_b32 m0, s51
	s_nop 0
	global_load_lds_dwordx4 v132, s[100:101]
	s_and_b64 vcc, exec, s[18:19]
	s_cbranch_vccz .LBB0_1348
	s_barrier

.Lrb2_skip_42710:
	s_mov_b32 m0, s49
	ds_read_b128 v[184:187], v154
	ds_read_b128 v[188:191], v154 offset:1024
	ds_read_b128 v[192:195], v154 offset:2048
	ds_read_b128 v[196:199], v154 offset:3072
	ds_read_b128 v[200:203], v154 offset:4096
	ds_read_b128 v[204:207], v154 offset:5120
	ds_read_b128 v[208:211], v154 offset:6144
	global_load_lds_dwordx4 v138, s[18:19]
	s_mov_b32 m0, s50
	ds_read_b128 v[212:215], v154 offset:7168
	global_load_lds_dwordx4 v140, s[18:19]
	s_waitcnt vmcnt(8) lgkmcnt(0)
	s_setprio 1
	s_barrier
	v_mfma_f32_16x16x32_bf16 v[126:129], v[148:151], v[184:187], v[126:129]
	v_mfma_f32_16x16x32_bf16 v[122:125], v[160:163], v[184:187], v[122:125]
	v_mfma_f32_16x16x32_bf16 v[110:113], v[148:151], v[192:195], v[110:113]
	v_mfma_f32_16x16x32_bf16 v[106:109], v[160:163], v[192:195], v[106:109]
	v_mfma_f32_16x16x32_bf16 v[94:97], v[148:151], v[200:203], v[94:97]
	v_mfma_f32_16x16x32_bf16 v[90:93], v[160:163], v[200:203], v[90:93]
	v_mfma_f32_16x16x32_bf16 v[78:81], v[148:151], v[208:211], v[78:81]
	v_mfma_f32_16x16x32_bf16 v[74:77], v[160:163], v[208:211], v[74:77]
	v_mfma_f32_16x16x32_bf16 v[126:129], v[156:159], v[188:191], v[126:129]
	v_mfma_f32_16x16x32_bf16 v[122:125], v[164:167], v[188:191], v[122:125]
	v_mfma_f32_16x16x32_bf16 v[110:113], v[156:159], v[196:199], v[110:113]
	v_mfma_f32_16x16x32_bf16 v[106:109], v[164:167], v[196:199], v[106:109]
	v_mfma_f32_16x16x32_bf16 v[94:97], v[156:159], v[204:207], v[94:97]
	v_mfma_f32_16x16x32_bf16 v[90:93], v[164:167], v[204:207], v[90:93]
	v_mfma_f32_16x16x32_bf16 v[78:81], v[156:159], v[212:215], v[78:81]
	v_mfma_f32_16x16x32_bf16 v[74:77], v[164:167], v[212:215], v[74:77]
	s_setprio 0
	s_setprio 1
	v_mfma_f32_16x16x32_bf16 v[118:121], v[168:171], v[184:187], v[118:121]
	v_mfma_f32_16x16x32_bf16 v[114:117], v[176:179], v[184:187], v[114:117]
	v_mfma_f32_16x16x32_bf16 v[102:105], v[168:171], v[192:195], v[102:105]
	v_mfma_f32_16x16x32_bf16 v[98:101], v[176:179], v[192:195], v[98:101]
	v_mfma_f32_16x16x32_bf16 v[86:89], v[168:171], v[200:203], v[86:89]
	v_mfma_f32_16x16x32_bf16 v[82:85], v[176:179], v[200:203], v[82:85]
	v_mfma_f32_16x16x32_bf16 v[70:73], v[168:171], v[208:211], v[70:73]
	v_mfma_f32_16x16x32_bf16 v[66:69], v[176:179], v[208:211], v[66:69]
	v_mfma_f32_16x16x32_bf16 v[118:121], v[172:175], v[188:191], v[118:121]
	v_mfma_f32_16x16x32_bf16 v[114:117], v[180:183], v[188:191], v[114:117]
	v_mfma_f32_16x16x32_bf16 v[102:105], v[172:175], v[196:199], v[102:105]
	v_mfma_f32_16x16x32_bf16 v[98:101], v[180:183], v[196:199], v[98:101]
	v_mfma_f32_16x16x32_bf16 v[86:89], v[172:175], v[204:207], v[86:89]
	v_mfma_f32_16x16x32_bf16 v[82:85], v[180:183], v[204:207], v[82:85]
	v_mfma_f32_16x16x32_bf16 v[70:73], v[172:175], v[212:215], v[70:73]
	v_mfma_f32_16x16x32_bf16 v[66:69], v[180:183], v[212:215], v[66:69]
	s_barrier
	s_setprio 0
	s_mov_b32 m0, s51
	s_mov_b64 s[98:99], s[20:21]
	s_add_u32 s58, s20, 0x2b0000
	ds_read_b128 v[184:187], v154 offset:16384
	ds_read_b128 v[188:191], v154 offset:17408
	ds_read_b128 v[192:195], v154 offset:18432
	ds_read_b128 v[196:199], v154 offset:19456
	ds_read_b128 v[200:203], v154 offset:20480
	ds_read_b128 v[204:207], v154 offset:21504
	ds_read_b128 v[208:211], v154 offset:22528
	global_load_lds_dwordx4 v132, s[20:21]
	s_mov_b32 m0, s52
	s_addc_u32 s59, s21, 0
	global_load_lds_dwordx4 v136, s[20:21]
	s_mov_b32 m0, s46
	s_mov_b64 s[100:101], s[22:23]
	global_load_lds_dwordx4 v132, s[58:59]
	s_mov_b32 m0, s47
	ds_read_b128 v[212:215], v154 offset:23552
	global_load_lds_dwordx4 v136, s[58:59]
	s_waitcnt vmcnt(6) lgkmcnt(0)
	s_setprio 1
	s_barrier
	v_mfma_f32_16x16x32_bf16 v[62:65], v[148:151], v[184:187], v[62:65]
	v_mfma_f32_16x16x32_bf16 v[58:61], v[160:163], v[184:187], v[58:61]
	v_mfma_f32_16x16x32_bf16 v[46:49], v[148:151], v[192:195], v[46:49]
	v_mfma_f32_16x16x32_bf16 v[42:45], v[160:163], v[192:195], v[42:45]
	v_mfma_f32_16x16x32_bf16 v[30:33], v[148:151], v[200:203], v[30:33]
	v_mfma_f32_16x16x32_bf16 v[26:29], v[160:163], v[200:203], v[26:29]
	v_mfma_f32_16x16x32_bf16 v[14:17], v[148:151], v[208:211], v[14:17]
	v_mfma_f32_16x16x32_bf16 v[10:13], v[160:163], v[208:211], v[10:13]
	v_mfma_f32_16x16x32_bf16 v[62:65], v[156:159], v[188:191], v[62:65]
	v_mfma_f32_16x16x32_bf16 v[58:61], v[164:167], v[188:191], v[58:61]
	v_mfma_f32_16x16x32_bf16 v[46:49], v[156:159], v[196:199], v[46:49]
	v_mfma_f32_16x16x32_bf16 v[42:45], v[164:167], v[196:199], v[42:45]
	v_mfma_f32_16x16x32_bf16 v[30:33], v[156:159], v[204:207], v[30:33]
	v_mfma_f32_16x16x32_bf16 v[26:29], v[164:167], v[204:207], v[26:29]
	v_mfma_f32_16x16x32_bf16 v[14:17], v[156:159], v[212:215], v[14:17]
	v_mfma_f32_16x16x32_bf16 v[10:13], v[164:167], v[212:215], v[10:13]
	s_setprio 0
	s_setprio 1
	v_mfma_f32_16x16x32_bf16 v[54:57], v[168:171], v[184:187], v[54:57]
	v_mfma_f32_16x16x32_bf16 v[50:53], v[176:179], v[184:187], v[50:53]
	v_mfma_f32_16x16x32_bf16 v[38:41], v[168:171], v[192:195], v[38:41]
	v_mfma_f32_16x16x32_bf16 v[34:37], v[176:179], v[192:195], v[34:37]
	v_mfma_f32_16x16x32_bf16 v[22:25], v[168:171], v[200:203], v[22:25]
	v_mfma_f32_16x16x32_bf16 v[18:21], v[176:179], v[200:203], v[18:21]
	v_mfma_f32_16x16x32_bf16 v[6:9], v[168:171], v[208:211], v[6:9]
	v_mfma_f32_16x16x32_bf16 v[2:5], v[176:179], v[208:211], v[2:5]
	v_mfma_f32_16x16x32_bf16 v[54:57], v[172:175], v[188:191], v[54:57]
	v_mfma_f32_16x16x32_bf16 v[50:53], v[180:183], v[188:191], v[50:53]
	v_mfma_f32_16x16x32_bf16 v[38:41], v[172:175], v[196:199], v[38:41]
	v_mfma_f32_16x16x32_bf16 v[34:37], v[180:183], v[196:199], v[34:37]
	v_mfma_f32_16x16x32_bf16 v[22:25], v[172:175], v[204:207], v[22:25]
	v_mfma_f32_16x16x32_bf16 v[18:21], v[180:183], v[204:207], v[18:21]
	v_mfma_f32_16x16x32_bf16 v[6:9], v[172:175], v[212:215], v[6:9]
	v_mfma_f32_16x16x32_bf16 v[2:5], v[180:183], v[212:215], v[2:5]
	s_barrier
; #define PG8_BAR __builtin_amdgcn_s_barrier()
;     ...
;         for (int t = 2; t < nt; t += 2) PG8_KITER(t);
;         if constexpr (ALIGN_EPI) { if (wr == 0) PG8_BAR; }
	s_setprio 0
	ds_read_b128 v[148:151], v146
	ds_read_b128 v[156:159], v146 offset:1024
	ds_read_b128 v[160:163], v146 offset:2048
	ds_read_b128 v[164:167], v146 offset:3072
	ds_read_b128 v[168:171], v147
	ds_read_b128 v[172:175], v147 offset:1024
	s_add_u32 s22, s22, 0x2b0000
	s_addc_u32 s23, s23, 0
	s_mov_b32 m0, s28
	ds_read_b128 v[180:183], v147 offset:3072
	global_load_lds_dwordx4 v130, s[100:101]
	s_mov_b32 m0, s29
	ds_read_b128 v[176:179], v147 offset:2048
	global_load_lds_dwordx4 v134, s[100:101]
	s_mov_b32 m0, s30
	ds_read_b128 v[184:187], v154 offset:32768
	ds_read_b128 v[188:191], v154 offset:33792
	ds_read_b128 v[192:195], v154 offset:34816
	ds_read_b128 v[196:199], v154 offset:35840
	ds_read_b128 v[200:203], v154 offset:36864
	ds_read_b128 v[204:207], v154 offset:37888
	ds_read_b128 v[208:211], v154 offset:38912
	global_load_lds_dwordx4 v130, s[22:23]
	s_mov_b32 m0, s31
	ds_read_b128 v[212:215], v154 offset:39936
	global_load_lds_dwordx4 v134, s[22:23]
	s_waitcnt vmcnt(8) lgkmcnt(0)
	s_setprio 1
	s_barrier
	v_mfma_f32_16x16x32_bf16 v[126:129], v[148:151], v[184:187], v[126:129]
	v_mfma_f32_16x16x32_bf16 v[122:125], v[160:163], v[184:187], v[122:125]
	v_mfma_f32_16x16x32_bf16 v[110:113], v[148:151], v[192:195], v[110:113]
	v_mfma_f32_16x16x32_bf16 v[106:109], v[160:163], v[192:195], v[106:109]
	v_mfma_f32_16x16x32_bf16 v[94:97], v[148:151], v[200:203], v[94:97]
	v_mfma_f32_16x16x32_bf16 v[90:93], v[160:163], v[200:203], v[90:93]
	v_mfma_f32_16x16x32_bf16 v[78:81], v[148:151], v[208:211], v[78:81]
	v_mfma_f32_16x16x32_bf16 v[74:77], v[160:163], v[208:211], v[74:77]
	v_mfma_f32_16x16x32_bf16 v[126:129], v[156:159], v[188:191], v[126:129]
	v_mfma_f32_16x16x32_bf16 v[122:125], v[164:167], v[188:191], v[122:125]
	v_mfma_f32_16x16x32_bf16 v[110:113], v[156:159], v[196:199], v[110:113]
	v_mfma_f32_16x16x32_bf16 v[106:109], v[164:167], v[196:199], v[106:109]
	v_mfma_f32_16x16x32_bf16 v[94:97], v[156:159], v[204:207], v[94:97]
	v_mfma_f32_16x16x32_bf16 v[90:93], v[164:167], v[204:207], v[90:93]
	v_mfma_f32_16x16x32_bf16 v[78:81], v[156:159], v[212:215], v[78:81]
	v_mfma_f32_16x16x32_bf16 v[74:77], v[164:167], v[212:215], v[74:77]
	s_setprio 0
	s_setprio 1
	v_mfma_f32_16x16x32_bf16 v[118:121], v[168:171], v[184:187], v[118:121]
	v_mfma_f32_16x16x32_bf16 v[114:117], v[176:179], v[184:187], v[114:117]
	v_mfma_f32_16x16x32_bf16 v[102:105], v[168:171], v[192:195], v[102:105]
	v_mfma_f32_16x16x32_bf16 v[98:101], v[176:179], v[192:195], v[98:101]
	v_mfma_f32_16x16x32_bf16 v[86:89], v[168:171], v[200:203], v[86:89]
	v_mfma_f32_16x16x32_bf16 v[82:85], v[176:179], v[200:203], v[82:85]
	v_mfma_f32_16x16x32_bf16 v[70:73], v[168:171], v[208:211], v[70:73]
	v_mfma_f32_16x16x32_bf16 v[66:69], v[176:179], v[208:211], v[66:69]
	v_mfma_f32_16x16x32_bf16 v[118:121], v[172:175], v[188:191], v[118:121]
	v_mfma_f32_16x16x32_bf16 v[114:117], v[180:183], v[188:191], v[114:117]
	v_mfma_f32_16x16x32_bf16 v[102:105], v[172:175], v[196:199], v[102:105]
	v_mfma_f32_16x16x32_bf16 v[98:101], v[180:183], v[196:199], v[98:101]
	v_mfma_f32_16x16x32_bf16 v[86:89], v[172:175], v[204:207], v[86:89]
	v_mfma_f32_16x16x32_bf16 v[82:85], v[180:183], v[204:207], v[82:85]
	v_mfma_f32_16x16x32_bf16 v[70:73], v[172:175], v[212:215], v[70:73]
	v_mfma_f32_16x16x32_bf16 v[66:69], v[180:183], v[212:215], v[66:69]
	s_barrier
	s_setprio 0
	s_mov_b32 m0, s53
	s_add_u32 s98, s98, 0x80
	s_addc_u32 s99, s99, 0
	s_add_u32 s100, s100, 0x80
	s_addc_u32 s101, s101, 0
	s_add_u32 s20, s20, 0x2b0080
	ds_read_b128 v[184:187], v154 offset:49152
	ds_read_b128 v[188:191], v154 offset:50176
	ds_read_b128 v[192:195], v154 offset:51200
	ds_read_b128 v[196:199], v154 offset:52224
	ds_read_b128 v[200:203], v154 offset:53248
	ds_read_b128 v[204:207], v154 offset:54272
	global_load_lds_dwordx4 v132, s[98:99]
	s_mov_b32 m0, s54
	s_addc_u32 s21, s21, 0
	global_load_lds_dwordx4 v136, s[98:99]
	s_mov_b32 m0, s55
	ds_read_b128 v[212:215], v154 offset:56320
	global_load_lds_dwordx4 v132, s[20:21]
	s_mov_b32 m0, s56
	ds_read_b128 v[208:211], v154 offset:55296
	global_load_lds_dwordx4 v136, s[20:21]
	s_waitcnt vmcnt(6) lgkmcnt(0)
	s_setprio 1
	s_barrier
	v_mfma_f32_16x16x32_bf16 v[62:65], v[148:151], v[184:187], v[62:65]
	v_mfma_f32_16x16x32_bf16 v[58:61], v[160:163], v[184:187], v[58:61]
	v_mfma_f32_16x16x32_bf16 v[46:49], v[148:151], v[192:195], v[46:49]
	v_mfma_f32_16x16x32_bf16 v[42:45], v[160:163], v[192:195], v[42:45]
	v_mfma_f32_16x16x32_bf16 v[30:33], v[148:151], v[200:203], v[30:33]
	v_mfma_f32_16x16x32_bf16 v[26:29], v[160:163], v[200:203], v[26:29]
	v_mfma_f32_16x16x32_bf16 v[14:17], v[148:151], v[208:211], v[14:17]
	v_mfma_f32_16x16x32_bf16 v[10:13], v[160:163], v[208:211], v[10:13]
	v_mfma_f32_16x16x32_bf16 v[62:65], v[156:159], v[188:191], v[62:65]
	v_mfma_f32_16x16x32_bf16 v[58:61], v[164:167], v[188:191], v[58:61]
	v_mfma_f32_16x16x32_bf16 v[46:49], v[156:159], v[196:199], v[46:49]
	v_mfma_f32_16x16x32_bf16 v[42:45], v[164:167], v[196:199], v[42:45]
	v_mfma_f32_16x16x32_bf16 v[30:33], v[156:159], v[204:207], v[30:33]
	v_mfma_f32_16x16x32_bf16 v[26:29], v[164:167], v[204:207], v[26:29]
	v_mfma_f32_16x16x32_bf16 v[14:17], v[156:159], v[212:215], v[14:17]
	v_mfma_f32_16x16x32_bf16 v[10:13], v[164:167], v[212:215], v[10:13]
	s_setprio 0
	s_setprio 1
	v_mfma_f32_16x16x32_bf16 v[54:57], v[168:171], v[184:187], v[54:57]
	v_mfma_f32_16x16x32_bf16 v[50:53], v[176:179], v[184:187], v[50:53]
	v_mfma_f32_16x16x32_bf16 v[38:41], v[168:171], v[192:195], v[38:41]
	v_mfma_f32_16x16x32_bf16 v[34:37], v[176:179], v[192:195], v[34:37]
	v_mfma_f32_16x16x32_bf16 v[22:25], v[168:171], v[200:203], v[22:25]
	v_mfma_f32_16x16x32_bf16 v[18:21], v[176:179], v[200:203], v[18:21]
	v_mfma_f32_16x16x32_bf16 v[6:9], v[168:171], v[208:211], v[6:9]
	v_mfma_f32_16x16x32_bf16 v[2:5], v[176:179], v[208:211], v[2:5]
	v_mfma_f32_16x16x32_bf16 v[54:57], v[172:175], v[188:191], v[54:57]
	v_mfma_f32_16x16x32_bf16 v[50:53], v[180:183], v[188:191], v[50:53]
	v_mfma_f32_16x16x32_bf16 v[38:41], v[172:175], v[196:199], v[38:41]
	v_mfma_f32_16x16x32_bf16 v[34:37], v[180:183], v[196:199], v[34:37]
	v_mfma_f32_16x16x32_bf16 v[22:25], v[172:175], v[204:207], v[22:25]
	v_mfma_f32_16x16x32_bf16 v[18:21], v[180:183], v[204:207], v[18:21]
	v_mfma_f32_16x16x32_bf16 v[6:9], v[172:175], v[212:215], v[6:9]
	v_mfma_f32_16x16x32_bf16 v[2:5], v[180:183], v[212:215], v[2:5]
	s_barrier
	s_setprio 0
	s_add_i32 s57, s57, 2
	s_add_u32 s18, s18, 0x100
	s_addc_u32 s19, s19, 0
	s_add_u32 s26, s26, 0x100
	s_addc_u32 s27, s27, 0
	s_cmpk_gt_u32 s57, 0xa9
	s_cbranch_scc0 .LBB0_1425
	s_mov_b32 m0, s34
	s_nop 0
	global_load_lds_dwordx4 v130, s[100:101]
	s_mov_b32 m0, s35
	s_nop 0
	global_load_lds_dwordx4 v134, s[100:101]
	s_and_b64 vcc, exec, s[10:11]
	s_cbranch_vccz .LBB0_1428
	s_barrier
